# rwkv prep: P/mu/param loads of each block hoisted to the block start + operand records staged in LDS and written as whole 896-byte records per head
# baseline (speedup 1.0000x reference)
; template <bool COOP>
; __global__ void __launch_bounds__(NTHREADS, 2) mega(Params p0) {
;     ...
;     for (int ph0 = p0.ph_lo * 2; ph0 < p0.ph_hi * 2; ++ph0) {
;         const int ph = ph0 >> 1;
;         const int kind = (ph == 0) ? 9 : (ph == NPHASE - 1 ? 10 : (ph - 1) % 9);
;         const bool rep = ((MK_REP_MASK >> kind) & 1) != 0;
;         if ((ph0 & 1) && !rep) continue;
;         Params p = p0; Lt lt; lt.tid = threadIdx.x; lt.bid = blockIdx.x;
;         asm volatile("" : "+v"(lt.tid)); asm volatile("" : "+s"(lt.bid));
;         { size_t z = 0; asm volatile("" : "+s"(z)); p.ws = p0.ws + z; }
;         unsigned char* ws = p.ws;
;         if (ph == 0) { if (SEL(0)) phase_prep(p, lt, lds); }
.LBB0_11:
	s_bitcmp1_b32 s82, 0
	s_cbranch_scc0 .Lprobe_run
	s_mov_b32 s98, 0x20100804
	s_mov_b32 s99, 0x0
	s_lshr_b32 vcc_lo, s82, 1
	s_bitcmp1_b64 s[98:99], vcc_lo
	s_cbranch_scc0 .LBB0_10
.Lprobe_run:
	v_mov_b32_e32 v245, v238
	s_mov_b64 s[0:1], 0
	s_ashr_i32 s60, s82, 1
	s_mov_b32 s97, s86
	s_add_u32 s62, s80, s0
	v_writelane_b32 v253, s0, 60
	s_addc_u32 s63, s81, s1
	s_movk_i32 s85, 0x300
	v_writelane_b32 v253, s1, 61
	v_writelane_b32 v253, s60, 62
	s_cmp_gt_u32 s82, 1
	s_mov_b64 s[0:1], -1
	v_writelane_b32 v253, s62, 63
	s_nop 1
	v_writelane_b32 v254, s63, 0
	s_cbranch_scc0 .LBB0_470
	s_cmp_lg_u32 s60, 37
	s_cbranch_scc0 .LBB0_465
	s_add_i32 s0, s60, -1
	s_mul_hi_i32 s1, s0, 0x38e38e39
	s_lshr_b32 s4, s1, 31
	s_ashr_i32 s1, s1, 1
	s_add_i32 s6, s1, s4
	s_mov_b32 s4, s6
	v_writelane_b32 v254, s4, 1
	s_mul_i32 s1, s6, 9
	s_mov_b64 s[6:7], 0
	v_writelane_b32 v254, s5, 2
	s_sub_i32 s4, s0, s1
	v_writelane_b32 v254, s4, 3
	s_cmp_lt_i32 s4, 4
	s_mov_b64 s[4:5], 0
	v_writelane_b32 v254, s4, 4
	s_mov_b64 s[0:1], -1
	s_nop 0
	v_writelane_b32 v254, s5, 5
	s_cbranch_scc1 .LBB0_141
	v_readlane_b32 s0, v254, 3
	s_cmp_gt_i32 s0, 5
	s_cbranch_scc0 .LBB0_88
	s_cmp_gt_i32 s0, 6
	s_cbranch_scc0 .LBB0_89
	s_cmp_eq_u32 s0, 7
	s_mov_b64 s[0:1], -1
	s_cbranch_scc0 .LBB0_87
	s_cmpk_lt_i32 s86, 0x400
	s_cselect_b64 s[0:1], -1, 0
	s_cmpk_gt_i32 s86, 0x3ff
	v_readfirstlane_b32 s10, v245
	s_cbranch_scc1 .LBB0_24
	s_ashr_i32 s4, s86, 31
	s_lshr_b32 s4, s4, 29
	s_add_i32 s8, s86, s4
	s_and_b32 s4, s8, -8
	s_sub_i32 s9, s86, s4
	s_cmp_gt_i32 s9, -1
	s_mov_b64 s[4:5], -1
	s_cbranch_scc0 .LBB0_21
	s_lshl_b32 s28, s9, 7
	s_mov_b64 s[4:5], 0

; __device__ __forceinline__ unsigned cvt_pk_bf16(float lo, float hi) { const f32x2 v = {lo, hi}; return __builtin_bit_cast(unsigned, __builtin_convertvector(v, bf16x2_t)); }
; __device__ __forceinline__ float bflo(unsigned u) { return __uint_as_float(u << 16); }
; __device__ __forceinline__ float bfhi(unsigned u) { return __uint_as_float(u & 0xffff0000u); }
; __device__ __forceinline__ void rwkv_prep_item(const Params& p, const Lt& lt, int l, int item) {
;     const int tid = lt.tid, lane = tid & 63, w = __builtin_amdgcn_readfirstlane(tid >> 6), qi = lane & 15, quad = lane >> 4;
;     const int t = item * 32 + (w >> 2) * 16 + qi, hg = w & 3;
;     const bf16_t* P = (const bf16_t*)(p.ws + WS_P);
;     const bf16_t* pt = P + (size_t)t * INC;
;     const bf16_t* pp = P + (size_t)(t > 0 ? t - 1 : 0) * INC;
;     const float pm = t > 0 ? 1.f : 0.f;
;     const float* mu = p.in[3] + l * 2560;
;     const bf16_t* lora = (const bf16_t*)(p.ws + WS_LORA + l * SZ_LORA);
;     const bf16_t* decT = lora; const bf16_t* aT = lora + 49152; const bf16_t* gT = lora + 98304;
;     bf16x8 fw[2], fa[2], fg[4];
; #pragma unroll
;     for (int ks = 0; ks < 8; ++ks) {
;         const int col = COL_XW + ks * 32 + quad * 8;
;         const u32x4 c4 = *(const u32x4*)(pt + col), q4 = *(const u32x4*)(pp + col);
;         const f32x4 m0 = *(const f32x4*)(mu + col), m1 = *(const f32x4*)(mu + col + 4);
;         float v[8];
; #pragma unroll
;         for (int i = 0; i < 4; ++i) {
;             const float c0 = bflo(c4[i]), c1 = bfhi(c4[i]), p0 = bflo(q4[i]) * pm, p1 = bfhi(q4[i]) * pm;
;             const float mu0 = (i < 2) ? m0[2 * i] : m1[2 * i - 4], mu1 = (i < 2) ? m0[2 * i + 1] : m1[2 * i - 3];
;             v[2 * i] = c0 + (p0 - c0) * mu0; v[2 * i + 1] = c1 + (p1 - c1) * mu1;
;         }
;         if (ks < 2) {
; #pragma unroll
;             for (int i = 0; i < 8; ++i) v[i] = tanhf_(v[i]);
;         } else if (ks >= 4) {
; #pragma unroll
;             for (int i = 0; i < 8; ++i) v[i] = sigmoidf_(v[i]);
;         }
;         u32x4 pk; pk.x = cvt_pk_bf16(v[0], v[1]); pk.y = cvt_pk_bf16(v[2], v[3]); pk.z = cvt_pk_bf16(v[4], v[5]); pk.w = cvt_pk_bf16(v[6], v[7]);
;         const bf16x8 f = __builtin_bit_cast(bf16x8, pk);
;         if (ks < 2) fw[ks] = f; else if (ks < 4) fa[ks - 2] = f; else fg[ks - 4] = f;
;     }
.LBB0_343:
	s_and_b32 s0, s54, 0xfe
	s_ashr_i32 s1, s55, 7
	s_add_i32 s4, s0, s1
	v_and_b32_e32 v210, 63, v245
	v_lshrrev_b32_e32 v211, 6, v245
	v_and_b32_e32 v212, 15, v245
	v_mul_u32_u24_e32 v213, 0x3900, v211
	v_lshl_add_u32 v226, v210, 4, v213
	v_lshrrev_b32_e32 v214, 2, v211
	v_lshlrev_b32_e32 v214, 4, v214
	s_lshl_b32 s98, s4, 5
	v_add_u32_e32 v214, s98, v214
	v_and_b32_e32 v215, 3, v211
	v_mul_u32_u24_e32 v215, 0xa80, v215
	s_movk_i32 s98, 0x2a00
	v_mul_lo_u32 v216, v214, s98
	v_add_u32_e32 v216, v216, v215
	v_lshl_add_u32 v218, v210, 4, v216
	v_mov_b32_e32 v219, 0
	v_readlane_b32 s98, v253, 63
	v_readlane_b32 s99, v254, 0
	s_add_u32 s98, s98, 0x23b00000
	s_addc_u32 s99, s99, 0
	v_lshl_add_u64 v[234:235], s[98:99], 0, v[218:219]
	v_mul_u32_u24_e32 v217, 0x2670, v212
	v_add_u32_e32 v217, v217, v216
	v_sub_u32_e32 v217, v217, v213
	v_add_u32_e32 v230, s98, v217
	v_add_u32_e32 v231, 0x380, v230
	v_add_u32_e32 v232, 0x700, v230
	v_readlane_b32 s0, v253, 52
	v_readlane_b32 s1, v253, 53
	v_mov_b32_e32 v0, v245
	s_and_b64 s[0:1], s[0:1], exec
	s_cselect_b32 s1, s4, s55
	v_readfirstlane_b32 s0, v0
	s_ashr_i32 s4, s0, 4
	v_bfe_u32 v1, v0, 4, 2
	s_lshl_b32 s1, s1, 5
	s_and_b32 s4, s4, -16
	v_and_b32_e32 v180, 15, v0
	s_add_i32 s4, s4, s1
	v_lshlrev_b32_e32 v44, 3, v1
	v_or_b32_e32 v84, s4, v180
	s_waitcnt vmcnt(63) lgkmcnt(0)
	v_mov_b64_e32 v[4:5], s[6:7]
	v_or_b32_e32 v0, 0x900, v44
	v_mad_i64_i32 v[114:115], s[4:5], v84, s76, v[4:5]
	v_lshlrev_b32_e32 v2, 1, v0
	v_lshl_add_u64 v[6:7], v[114:115], 0, v[2:3]
	global_load_dwordx4 v[8:11], v[6:7], off
	v_max_i32_e32 v6, 1, v84
	v_add_u32_e32 v6, -1, v6
	v_mad_u64_u32 v[110:111], s[4:5], v6, s76, v[4:5]
	v_lshl_add_u64 v[4:5], v[110:111], 0, v[2:3]
	global_load_dwordx4 v[12:15], v[4:5], off
	v_lshlrev_b32_e32 v0, 2, v0
	global_load_dwordx4 v[16:19], v0, s[8:9]
	global_load_dwordx4 v[20:23], v0, s[8:9] offset:16
	v_or_b32_e32 v2, 0x920, v44
	v_lshlrev_b32_e32 v0, 2, v2
	v_lshlrev_b32_e32 v2, 1, v2
	v_lshl_add_u64 v[28:29], v[114:115], 0, v[2:3]
	v_lshl_add_u64 v[32:33], v[110:111], 0, v[2:3]
	global_load_dwordx4 v[4:7], v0, s[8:9] offset:16
	global_load_dwordx4 v[24:27], v0, s[8:9]
	s_nop 0
	global_load_dwordx4 v[28:31], v[28:29], off
	s_nop 0
	global_load_dwordx4 v[32:35], v[32:33], off
	v_cmp_lt_i32_e32 vcc, 0, v84
	v_or_b32_e32 v59, 0x980, v44
	s_bfe_u32 s4, s0, 0x20006
	v_cndmask_b32_e64 v0, 0, 1.0, vcc
	s_mul_i32 s5, s4, 0xc0
	v_lshlrev_b32_e32 v112, 4, v1
	v_mov_b32_e32 v113, v3
	v_lshl_add_u64 v[88:89], s[28:29], 0, v[112:113]
	v_lshl_add_u64 v[92:93], s[30:31], 0, v[112:113]
	v_lshlrev_b32_e32 v181, 2, v1
	s_mul_i32 s10, s4, 0xa80
	v_lshl_add_u64 v[94:95], s[34:35], 0, v[112:113]
	s_mov_b32 s57, 0x3f317217
	s_mov_b32 s58, 0x7f800000
	s_mul_i32 s56, s4, 3
	s_waitcnt vmcnt(7)
	v_lshlrev_b32_e32 v2, 16, v8
	v_and_b32_e32 v8, 0xffff0000, v8
	v_lshlrev_b32_e32 v38, 16, v11
	v_and_b32_e32 v39, 0xffff0000, v11
	v_lshlrev_b32_e32 v36, 16, v9
	v_and_b32_e32 v9, 0xffff0000, v9
	s_waitcnt vmcnt(6)
	v_lshlrev_b32_e32 v11, 16, v12
	v_and_b32_e32 v12, 0xffff0000, v12
	v_lshlrev_b32_e32 v40, 16, v13
	v_and_b32_e32 v13, 0xffff0000, v13
	v_fma_f32 v12, v0, v12, -v8
	v_fma_f32 v11, v0, v11, -v2
	v_fma_f32 v13, v0, v13, -v9
	s_waitcnt vmcnt(5)
	v_fmac_f32_e32 v8, v17, v12
	v_fmac_f32_e32 v2, v16, v11
	v_fmac_f32_e32 v9, v19, v13
	v_add_f32_e32 v8, v8, v8
	v_add_f32_e32 v2, v2, v2
	v_add_f32_e32 v9, v9, v9
	v_mul_f32_e32 v8, 0x3fb8aa3b, v8
	v_mul_f32_e32 v2, 0x3fb8aa3b, v2
	v_mul_f32_e32 v9, 0x3fb8aa3b, v9
	v_exp_f32_e32 v8, v8
	v_exp_f32_e32 v2, v2
	v_exp_f32_e32 v9, v9
	v_lshlrev_b32_e32 v37, 16, v10
	v_and_b32_e32 v10, 0xffff0000, v10
	v_lshlrev_b32_e32 v41, 16, v14
	v_and_b32_e32 v14, 0xffff0000, v14
	v_lshlrev_b32_e32 v42, 16, v15
	v_and_b32_e32 v15, 0xffff0000, v15
	v_fma_f32 v40, v0, v40, -v36
	v_fma_f32 v14, v0, v14, -v10
	v_fma_f32 v42, v0, v42, -v38
	v_add_f32_e32 v13, 1.0, v8
	v_fmac_f32_e32 v36, v18, v40
	s_waitcnt vmcnt(4)
	v_fmac_f32_e32 v10, v21, v14
	v_fmac_f32_e32 v38, v22, v42
	v_add_f32_e32 v2, 1.0, v2
	v_add_f32_e32 v14, 1.0, v9
	v_rcp_f32_e32 v9, v13
	v_fma_f32 v13, v0, v15, -v39
	v_add_f32_e32 v11, v36, v36
	v_rcp_f32_e32 v8, v2
	v_add_f32_e32 v2, v38, v38
	v_fmac_f32_e32 v39, v23, v13
	v_add_f32_e32 v10, v10, v10
	v_mul_f32_e32 v11, 0x3fb8aa3b, v11
	v_mul_f32_e32 v2, 0x3fb8aa3b, v2
	v_add_f32_e32 v13, v39, v39
	v_mul_f32_e32 v10, 0x3fb8aa3b, v10
	v_exp_f32_e32 v11, v11
	v_exp_f32_e32 v2, v2
	v_mul_f32_e32 v13, 0x3fb8aa3b, v13
	v_exp_f32_e32 v10, v10
	v_exp_f32_e32 v15, v13
	v_fma_f32 v41, v0, v41, -v37
	v_add_f32_e32 v11, 1.0, v11
	v_add_f32_e32 v2, 1.0, v2
	v_fmac_f32_e32 v37, v20, v41
	v_add_f32_e32 v16, 1.0, v10
	v_rcp_f32_e32 v10, v11
	v_rcp_f32_e32 v11, v14
	v_rcp_f32_e32 v14, v2
	v_add_f32_e32 v2, 1.0, v15
	v_add_f32_e32 v12, v37, v37
	v_rcp_f32_e32 v15, v2
	v_pk_fma_f32 v[8:9], v[8:9], 2.0, 1.0 op_sel_hi:[1,0,0] neg_lo:[1,0,0] neg_hi:[1,0,0]
	s_waitcnt vmcnt(1)
	v_lshlrev_b32_e32 v40, 16, v28
	s_waitcnt vmcnt(0)
; __device__ __forceinline__ unsigned cvt_pk_bf16(float lo, float hi) { const f32x2 v = {lo, hi}; return __builtin_bit_cast(unsigned, __builtin_convertvector(v, bf16x2_t)); }
; __device__ __forceinline__ float bflo(unsigned u) { return __uint_as_float(u << 16); }
; __device__ __forceinline__ float bfhi(unsigned u) { return __uint_as_float(u & 0xffff0000u); }
; __device__ __forceinline__ float sigmoidf_(float x) { return __builtin_amdgcn_rcpf(1.0f + __expf(-x)); }
; __device__ __forceinline__ float tanhf_(float x) { return 1.0f - 2.0f * __builtin_amdgcn_rcpf(1.0f + __expf(2.0f * x)); }
; __device__ __forceinline__ void rwkv_prep_item(const Params& p, const Lt& lt, int l, int item) {
;     ...
;     for (int ks = 0; ks < 8; ++ks) {
;         const int col = COL_XW + ks * 32 + quad * 8;
;         const u32x4 c4 = *(const u32x4*)(pt + col), q4 = *(const u32x4*)(pp + col);
;         const f32x4 m0 = *(const f32x4*)(mu + col), m1 = *(const f32x4*)(mu + col + 4);
;         float v[8];
; #pragma unroll
;         for (int i = 0; i < 4; ++i) {
;             const float c0 = bflo(c4[i]), c1 = bfhi(c4[i]), p0 = bflo(q4[i]) * pm, p1 = bfhi(q4[i]) * pm;
;             const float mu0 = (i < 2) ? m0[2 * i] : m1[2 * i - 4], mu1 = (i < 2) ? m0[2 * i + 1] : m1[2 * i - 3];
;             v[2 * i] = c0 + (p0 - c0) * mu0; v[2 * i + 1] = c1 + (p1 - c1) * mu1;
;         }
;         if (ks < 2) {
; #pragma unroll
;             for (int i = 0; i < 8; ++i) v[i] = tanhf_(v[i]);
;         } else if (ks >= 4) {
; #pragma unroll
;             for (int i = 0; i < 8; ++i) v[i] = sigmoidf_(v[i]);
;         }
;         u32x4 pk; pk.x = cvt_pk_bf16(v[0], v[1]); pk.y = cvt_pk_bf16(v[2], v[3]); pk.z = cvt_pk_bf16(v[4], v[5]); pk.w = cvt_pk_bf16(v[6], v[7]);
;         const bf16x8 f = __builtin_bit_cast(bf16x8, pk);
;         if (ks < 2) fw[ks] = f; else if (ks < 4) fa[ks - 2] = f; else fg[ks - 4] = f;
;     }
	v_lshlrev_b32_e32 v2, 16, v32
	v_mul_f32_e32 v12, 0x3fb8aa3b, v12
	v_cvt_pk_bf16_f32 v20, v8, v9
	v_and_b32_e32 v28, 0xffff0000, v28
	v_and_b32_e32 v8, 0xffff0000, v32
	v_fma_f32 v2, v0, v2, -v40
	v_exp_f32_e32 v12, v12
	v_fmac_f32_e32 v40, v24, v2
	v_fma_f32 v2, v0, v8, -v28
	v_fmac_f32_e32 v28, v25, v2
	v_lshlrev_b32_e32 v25, 16, v29
	v_lshlrev_b32_e32 v2, 16, v33
	v_and_b32_e32 v29, 0xffff0000, v29
	v_and_b32_e32 v8, 0xffff0000, v33
	v_fma_f32 v2, v0, v2, -v25
	v_fmac_f32_e32 v25, v26, v2
	v_fma_f32 v2, v0, v8, -v29
	v_add_f32_e32 v12, 1.0, v12
	v_fmac_f32_e32 v29, v27, v2
	v_lshlrev_b32_e32 v27, 16, v30
	v_lshlrev_b32_e32 v2, 16, v34
	v_rcp_f32_e32 v12, v12
	v_rcp_f32_e32 v13, v16
	v_and_b32_e32 v30, 0xffff0000, v30
	v_and_b32_e32 v8, 0xffff0000, v34
	v_fma_f32 v2, v0, v2, -v27
	v_fmac_f32_e32 v27, v4, v2
	v_fma_f32 v2, v0, v8, -v30
	v_or_b32_e32 v16, 0x940, v44
	v_fmac_f32_e32 v30, v5, v2
	v_lshlrev_b32_e32 v2, 1, v16
	v_pk_fma_f32 v[10:11], v[10:11], 2.0, 1.0 op_sel_hi:[1,0,0] neg_lo:[1,0,0] neg_hi:[1,0,0]
	v_lshl_add_u64 v[4:5], v[114:115], 0, v[2:3]
	v_pk_fma_f32 v[12:13], v[12:13], 2.0, 1.0 op_sel_hi:[1,0,0] neg_lo:[1,0,0] neg_hi:[1,0,0]
	v_pk_fma_f32 v[14:15], v[14:15], 2.0, 1.0 op_sel_hi:[1,0,0] neg_lo:[1,0,0] neg_hi:[1,0,0]
	v_cvt_pk_bf16_f32 v21, v10, v11
	global_load_dwordx4 v[8:11], v[4:5], off
	v_lshl_add_u64 v[4:5], v[110:111], 0, v[2:3]
	v_lshlrev_b32_e32 v2, 2, v16
	v_cvt_pk_bf16_f32 v22, v12, v13
	v_cvt_pk_bf16_f32 v23, v14, v15
	global_load_dwordx4 v[12:15], v[4:5], off
	global_load_dwordx4 v[16:19], v2, s[8:9] offset:16
	global_load_dwordx4 v[36:39], v2, s[8:9]
	v_add_f32_e32 v2, v40, v40
	v_mul_f32_e32 v2, 0x3fb8aa3b, v2
	v_exp_f32_e32 v2, v2
	v_add_f32_e32 v4, v28, v28
	v_mul_f32_e32 v4, 0x3fb8aa3b, v4
	v_exp_f32_e32 v4, v4
	v_add_f32_e32 v2, 1.0, v2
	v_rcp_f32_e32 v24, v2
	v_add_f32_e32 v2, v25, v25
	v_mul_f32_e32 v2, 0x3fb8aa3b, v2
	v_exp_f32_e32 v28, v2
	v_add_f32_e32 v2, v29, v29
	v_mul_f32_e32 v2, 0x3fb8aa3b, v2
	v_or_b32_e32 v25, 0x960, v44
	v_exp_f32_e32 v29, v2
	v_lshlrev_b32_e32 v2, 1, v25
	v_add_f32_e32 v26, 1.0, v4
	v_lshl_add_u64 v[4:5], v[114:115], 0, v[2:3]
	v_lshlrev_b32_e32 v54, 16, v35
	v_and_b32_e32 v55, 0xffff0000, v35
	global_load_dwordx4 v[32:35], v[4:5], off
	v_lshl_add_u64 v[4:5], v[110:111], 0, v[2:3]
	global_load_dwordx4 v[40:43], v[4:5], off
	v_lshlrev_b32_e32 v2, 2, v25
	global_load_dwordx4 v[46:49], v2, s[8:9] offset:16
	global_load_dwordx4 v[50:53], v2, s[8:9]
	v_add_f32_e32 v4, v27, v27
	v_mul_f32_e32 v4, 0x3fb8aa3b, v4
	v_add_f32_e32 v5, v30, v30
	v_exp_f32_e32 v4, v4
	v_mul_f32_e32 v5, 0x3fb8aa3b, v5
	v_exp_f32_e32 v5, v5
	v_add_f32_e32 v2, 1.0, v28
	v_rcp_f32_e32 v25, v26
	v_rcp_f32_e32 v26, v2
	v_add_f32_e32 v2, 1.0, v29
	v_rcp_f32_e32 v27, v2
	v_add_f32_e32 v2, 1.0, v4
	v_lshlrev_b32_e32 v45, 16, v31
	v_rcp_f32_e32 v28, v2
	v_add_f32_e32 v2, 1.0, v5
	v_rcp_f32_e32 v29, v2
	v_fma_f32 v2, v0, v54, -v45
	v_fmac_f32_e32 v45, v6, v2
	v_add_f32_e32 v2, v45, v45
	v_and_b32_e32 v31, 0xffff0000, v31
	v_mul_f32_e32 v2, 0x3fb8aa3b, v2
	v_exp_f32_e32 v45, v2
	v_fma_f32 v2, v0, v55, -v31
	v_fmac_f32_e32 v31, v7, v2
	v_add_f32_e32 v2, v31, v31
	v_mul_f32_e32 v2, 0x3fb8aa3b, v2
	v_exp_f32_e32 v58, v2
	v_lshlrev_b32_e32 v2, 1, v59
	v_lshl_add_u64 v[4:5], v[114:115], 0, v[2:3]
	v_lshl_add_u64 v[30:31], v[110:111], 0, v[2:3]
	global_load_dwordx4 v[4:7], v[4:5], off
	v_add_f32_e32 v2, 1.0, v45
	global_load_dwordx4 v[54:57], v[30:31], off
	v_lshlrev_b32_e32 v31, 2, v59
	v_rcp_f32_e32 v30, v2
	v_add_f32_e32 v2, 1.0, v58
	global_load_dwordx4 v[58:61], v31, s[8:9] offset:16
	global_load_dwordx4 v[62:65], v31, s[8:9]
	v_rcp_f32_e32 v31, v2
	v_pk_fma_f32 v[24:25], v[24:25], 2.0, 1.0 op_sel_hi:[1,0,0] neg_lo:[1,0,0] neg_hi:[1,0,0]
	v_pk_fma_f32 v[26:27], v[26:27], 2.0, 1.0 op_sel_hi:[1,0,0] neg_lo:[1,0,0] neg_hi:[1,0,0]
	v_pk_fma_f32 v[28:29], v[28:29], 2.0, 1.0 op_sel_hi:[1,0,0] neg_lo:[1,0,0] neg_hi:[1,0,0]
	v_pk_fma_f32 v[30:31], v[30:31], 2.0, 1.0 op_sel_hi:[1,0,0] neg_lo:[1,0,0] neg_hi:[1,0,0]
	v_cvt_pk_bf16_f32 v24, v24, v25
	v_cvt_pk_bf16_f32 v25, v26, v27
	v_cvt_pk_bf16_f32 v26, v28, v29
	v_cvt_pk_bf16_f32 v27, v30, v31
	s_waitcnt vmcnt(11)
	v_lshlrev_b32_e32 v28, 16, v8
	v_and_b32_e32 v29, 0xffff0000, v8
	v_lshlrev_b32_e32 v8, 16, v9
	v_and_b32_e32 v9, 0xffff0000, v9
	s_waitcnt vmcnt(10)
	v_lshlrev_b32_e32 v30, 16, v12
	v_and_b32_e32 v31, 0xffff0000, v12
	v_lshlrev_b32_e32 v12, 16, v13
	v_and_b32_e32 v13, 0xffff0000, v13
	v_pk_fma_f32 v[30:31], v[0:1], v[30:31], v[28:29] op_sel_hi:[0,1,1] neg_lo:[0,0,1] neg_hi:[0,0,1]
	v_pk_fma_f32 v[12:13], v[0:1], v[12:13], v[8:9] op_sel_hi:[0,1,1] neg_lo:[0,0,1] neg_hi:[0,0,1]
	s_waitcnt vmcnt(8)
	v_pk_fma_f32 v[28:29], v[36:37], v[30:31], v[28:29]
	v_pk_fma_f32 v[8:9], v[38:39], v[12:13], v[8:9]
	v_lshlrev_b32_e32 v12, 16, v10
	v_and_b32_e32 v13, 0xffff0000, v10
	v_lshlrev_b32_e32 v30, 16, v14
	v_and_b32_e32 v31, 0xffff0000, v14
	v_lshlrev_b32_e32 v10, 16, v11
	v_and_b32_e32 v11, 0xffff0000, v11
	v_lshlrev_b32_e32 v14, 16, v15
	v_and_b32_e32 v15, 0xffff0000, v15
	v_pk_fma_f32 v[14:15], v[0:1], v[14:15], v[10:11] op_sel_hi:[0,1,1] neg_lo:[0,0,1] neg_hi:[0,0,1]
	v_pk_fma_f32 v[30:31], v[0:1], v[30:31], v[12:13] op_sel_hi:[0,1,1] neg_lo:[0,0,1] neg_hi:[0,0,1]
	v_pk_fma_f32 v[10:11], v[18:19], v[14:15], v[10:11]
	v_pk_fma_f32 v[12:13], v[16:17], v[30:31], v[12:13]
	v_cvt_pk_bf16_f32 v28, v28, v29
	v_cvt_pk_bf16_f32 v29, v8, v9
	v_cvt_pk_bf16_f32 v31, v10, v11
	s_waitcnt vmcnt(7)
	v_lshlrev_b32_e32 v8, 16, v32
	v_and_b32_e32 v9, 0xffff0000, v32
	s_waitcnt vmcnt(6)
	v_lshlrev_b32_e32 v10, 16, v40
	v_and_b32_e32 v11, 0xffff0000, v40
	v_pk_fma_f32 v[10:11], v[0:1], v[10:11], v[8:9] op_sel_hi:[0,1,1] neg_lo:[0,0,1] neg_hi:[0,0,1]
	s_waitcnt vmcnt(4)
; __device__ __forceinline__ unsigned cvt_pk_bf16(float lo, float hi) { const f32x2 v = {lo, hi}; return __builtin_bit_cast(unsigned, __builtin_convertvector(v, bf16x2_t)); }
; __device__ __forceinline__ float bflo(unsigned u) { return __uint_as_float(u << 16); }
; __device__ __forceinline__ float bfhi(unsigned u) { return __uint_as_float(u & 0xffff0000u); }
; __device__ __forceinline__ float sigmoidf_(float x) { return __builtin_amdgcn_rcpf(1.0f + __expf(-x)); }
; __device__ __forceinline__ float tanhf_(float x) { return 1.0f - 2.0f * __builtin_amdgcn_rcpf(1.0f + __expf(2.0f * x)); }
; __device__ __forceinline__ void rwkv_prep_item(const Params& p, const Lt& lt, int l, int item) {
;     ...
;     for (int ks = 0; ks < 8; ++ks) {
;         const int col = COL_XW + ks * 32 + quad * 8;
;         const u32x4 c4 = *(const u32x4*)(pt + col), q4 = *(const u32x4*)(pp + col);
;         const f32x4 m0 = *(const f32x4*)(mu + col), m1 = *(const f32x4*)(mu + col + 4);
;         float v[8];
; #pragma unroll
;         for (int i = 0; i < 4; ++i) {
;             const float c0 = bflo(c4[i]), c1 = bfhi(c4[i]), p0 = bflo(q4[i]) * pm, p1 = bfhi(q4[i]) * pm;
;             const float mu0 = (i < 2) ? m0[2 * i] : m1[2 * i - 4], mu1 = (i < 2) ? m0[2 * i + 1] : m1[2 * i - 3];
;             v[2 * i] = c0 + (p0 - c0) * mu0; v[2 * i + 1] = c1 + (p1 - c1) * mu1;
;         }
;         if (ks < 2) {
; #pragma unroll
;             for (int i = 0; i < 8; ++i) v[i] = tanhf_(v[i]);
;         } else if (ks >= 4) {
; #pragma unroll
;             for (int i = 0; i < 8; ++i) v[i] = sigmoidf_(v[i]);
;         }
;         u32x4 pk; pk.x = cvt_pk_bf16(v[0], v[1]); pk.y = cvt_pk_bf16(v[2], v[3]); pk.z = cvt_pk_bf16(v[4], v[5]); pk.w = cvt_pk_bf16(v[6], v[7]);
;         const bf16x8 f = __builtin_bit_cast(bf16x8, pk);
;         if (ks < 2) fw[ks] = f; else if (ks < 4) fa[ks - 2] = f; else fg[ks - 4] = f;
;     }
	v_pk_fma_f32 v[16:17], v[50:51], v[10:11], v[8:9]
	v_lshlrev_b32_e32 v8, 16, v33
	v_and_b32_e32 v9, 0xffff0000, v33
	v_lshlrev_b32_e32 v10, 16, v41
	v_and_b32_e32 v11, 0xffff0000, v41
	v_pk_fma_f32 v[10:11], v[0:1], v[10:11], v[8:9] op_sel_hi:[0,1,1] neg_lo:[0,0,1] neg_hi:[0,0,1]
	v_pk_fma_f32 v[18:19], v[52:53], v[10:11], v[8:9]
	v_lshlrev_b32_e32 v8, 16, v34
	v_and_b32_e32 v9, 0xffff0000, v34
	v_lshlrev_b32_e32 v10, 16, v42
	v_and_b32_e32 v11, 0xffff0000, v42
	v_or_b32_e32 v40, 0x9a0, v44
	v_pk_fma_f32 v[10:11], v[0:1], v[10:11], v[8:9] op_sel_hi:[0,1,1] neg_lo:[0,0,1] neg_hi:[0,0,1]
	v_lshlrev_b32_e32 v2, 1, v40
	v_cvt_pk_bf16_f32 v30, v12, v13
	v_pk_fma_f32 v[36:37], v[46:47], v[10:11], v[8:9]
	v_lshlrev_b32_e32 v32, 16, v35
	v_and_b32_e32 v33, 0xffff0000, v35
	v_lshlrev_b32_e32 v34, 16, v43
	v_and_b32_e32 v35, 0xffff0000, v43
	v_lshl_add_u64 v[8:9], v[114:115], 0, v[2:3]
	v_lshl_add_u64 v[12:13], v[110:111], 0, v[2:3]
	global_load_dwordx4 v[8:11], v[8:9], off
	v_pk_fma_f32 v[34:35], v[0:1], v[34:35], v[32:33] op_sel_hi:[0,1,1] neg_lo:[0,0,1] neg_hi:[0,0,1]
	global_load_dwordx4 v[12:15], v[12:13], off
	v_pk_fma_f32 v[38:39], v[48:49], v[34:35], v[32:33]
	v_cvt_pk_bf16_f32 v34, v36, v37
	v_lshlrev_b32_e32 v36, 2, v40
	v_cvt_pk_bf16_f32 v32, v16, v17
	v_cvt_pk_bf16_f32 v33, v18, v19
	v_cvt_pk_bf16_f32 v35, v38, v39
	global_load_dwordx4 v[16:19], v36, s[8:9] offset:16
	s_nop 0
	global_load_dwordx4 v[36:39], v36, s[8:9]
	s_waitcnt vmcnt(7)
	v_lshlrev_b32_e32 v2, 16, v4
	v_and_b32_e32 v4, 0xffff0000, v4
	s_waitcnt vmcnt(6)
	v_lshlrev_b32_e32 v41, 16, v54
	v_and_b32_e32 v40, 0xffff0000, v54
	v_fma_f32 v41, v0, v41, -v2
	v_fma_f32 v40, v0, v40, -v4
	s_waitcnt vmcnt(4)
	v_fmac_f32_e32 v2, v62, v41
	v_fmac_f32_e32 v4, v63, v40
	v_lshlrev_b32_e32 v40, 16, v5
	v_lshlrev_b32_e32 v41, 16, v55
	v_and_b32_e32 v5, 0xffff0000, v5
	v_and_b32_e32 v42, 0xffff0000, v55
	v_fma_f32 v41, v0, v41, -v40
	v_fmac_f32_e32 v40, v64, v41
	v_fma_f32 v41, v0, v42, -v5
	v_fmac_f32_e32 v5, v65, v41
	v_lshlrev_b32_e32 v41, 16, v6
	v_lshlrev_b32_e32 v42, 16, v56
	v_and_b32_e32 v6, 0xffff0000, v6
	v_and_b32_e32 v43, 0xffff0000, v56
	v_fma_f32 v42, v0, v42, -v41
	v_fmac_f32_e32 v41, v58, v42
	v_fma_f32 v42, v0, v43, -v6
	v_fmac_f32_e32 v6, v59, v42
	v_lshlrev_b32_e32 v42, 16, v7
	v_lshlrev_b32_e32 v43, 16, v57
	v_and_b32_e32 v7, 0xffff0000, v7
	v_and_b32_e32 v45, 0xffff0000, v57
	v_fma_f32 v43, v0, v43, -v42
	v_mul_f32_e32 v2, 0xbfb8aa3b, v2
	v_mul_f32_e32 v4, 0xbfb8aa3b, v4
	v_fmac_f32_e32 v42, v60, v43
	v_fma_f32 v43, v0, v45, -v7
	v_exp_f32_e32 v2, v2
	v_exp_f32_e32 v4, v4
	v_mul_f32_e32 v40, 0xbfb8aa3b, v40
	v_mul_f32_e32 v5, 0xbfb8aa3b, v5
	v_mul_f32_e32 v41, 0xbfb8aa3b, v41
	v_mul_f32_e32 v6, 0xbfb8aa3b, v6
	v_fmac_f32_e32 v7, v61, v43
	v_exp_f32_e32 v40, v40
	v_exp_f32_e32 v5, v5
	v_exp_f32_e32 v41, v41
	v_exp_f32_e32 v6, v6
	v_mul_f32_e32 v42, 0xbfb8aa3b, v42
	v_mul_f32_e32 v7, 0xbfb8aa3b, v7
	v_exp_f32_e32 v42, v42
	v_exp_f32_e32 v7, v7
	v_add_f32_e32 v2, 1.0, v2
	v_add_f32_e32 v4, 1.0, v4
	v_rcp_f32_e32 v2, v2
	v_rcp_f32_e32 v4, v4
	v_add_f32_e32 v40, 1.0, v40
	v_add_f32_e32 v5, 1.0, v5
	v_add_f32_e32 v41, 1.0, v41
	v_add_f32_e32 v6, 1.0, v6
	v_rcp_f32_e32 v40, v40
	v_rcp_f32_e32 v5, v5
	v_rcp_f32_e32 v41, v41
	v_rcp_f32_e32 v6, v6
	v_add_f32_e32 v42, 1.0, v42
	v_add_f32_e32 v7, 1.0, v7
	v_rcp_f32_e32 v42, v42
	v_rcp_f32_e32 v7, v7
	v_or_b32_e32 v45, 0x9c0, v44
	v_cvt_pk_bf16_f32 v4, v2, v4
	v_lshlrev_b32_e32 v2, 1, v45
	v_cvt_pk_bf16_f32 v5, v40, v5
	v_cvt_pk_bf16_f32 v6, v41, v6
	v_lshl_add_u64 v[40:41], v[114:115], 0, v[2:3]
	global_load_dwordx4 v[46:49], v[40:41], off
	v_lshl_add_u64 v[40:41], v[110:111], 0, v[2:3]
	v_lshlrev_b32_e32 v2, 2, v45
	v_cvt_pk_bf16_f32 v7, v42, v7
	s_waitcnt vmcnt(4)
	v_lshlrev_b32_e32 v42, 16, v8
	v_and_b32_e32 v8, 0xffff0000, v8
	s_waitcnt vmcnt(3)
	v_lshlrev_b32_e32 v43, 16, v12
	global_load_dwordx4 v[50:53], v[40:41], off
	global_load_dwordx4 v[54:57], v2, s[8:9] offset:16
	global_load_dwordx4 v[58:61], v2, s[8:9]
	v_and_b32_e32 v2, 0xffff0000, v12
	v_fma_f32 v12, v0, v43, -v42
	v_fma_f32 v2, v0, v2, -v8
	s_waitcnt vmcnt(4)
	v_fmac_f32_e32 v42, v36, v12
	v_fmac_f32_e32 v8, v37, v2
	v_lshlrev_b32_e32 v2, 16, v9
	v_lshlrev_b32_e32 v12, 16, v13
	v_and_b32_e32 v9, 0xffff0000, v9
	v_and_b32_e32 v13, 0xffff0000, v13
	v_fma_f32 v12, v0, v12, -v2
	v_fmac_f32_e32 v2, v38, v12
	v_fma_f32 v12, v0, v13, -v9
	v_mul_f32_e32 v8, 0xbfb8aa3b, v8
	v_fmac_f32_e32 v9, v39, v12
	v_lshlrev_b32_e32 v12, 16, v10
	v_lshlrev_b32_e32 v13, 16, v14
	v_exp_f32_e32 v8, v8
	v_and_b32_e32 v10, 0xffff0000, v10
	v_and_b32_e32 v14, 0xffff0000, v14
	v_fma_f32 v13, v0, v13, -v12
	v_fmac_f32_e32 v12, v16, v13
	v_fma_f32 v13, v0, v14, -v10
	v_fmac_f32_e32 v10, v17, v13
	v_lshlrev_b32_e32 v13, 16, v11
	v_lshlrev_b32_e32 v14, 16, v15
	v_and_b32_e32 v11, 0xffff0000, v11
	v_and_b32_e32 v15, 0xffff0000, v15
	v_fma_f32 v14, v0, v14, -v13
	v_mul_f32_e32 v2, 0xbfb8aa3b, v2
	v_add_f32_e32 v8, 1.0, v8
	v_fmac_f32_e32 v13, v18, v14
	v_fma_f32 v14, v0, v15, -v11
	v_exp_f32_e32 v2, v2
	v_rcp_f32_e32 v15, v8
	v_mul_f32_e32 v8, 0xbfb8aa3b, v9
	v_exp_f32_e32 v8, v8
	v_mul_f32_e32 v9, 0xbfb8aa3b, v12
	v_exp_f32_e32 v9, v9
	v_add_f32_e32 v2, 1.0, v2
	v_rcp_f32_e32 v12, v2
	v_add_f32_e32 v2, 1.0, v8
	v_mul_f32_e32 v8, 0xbfb8aa3b, v10
	v_rcp_f32_e32 v45, v2
	v_add_f32_e32 v2, 1.0, v9
	v_exp_f32_e32 v8, v8
	v_mul_f32_e32 v9, 0xbfb8aa3b, v13
	v_mul_f32_e32 v16, 0xbfb8aa3b, v42
	v_exp_f32_e32 v9, v9
	v_exp_f32_e32 v16, v16
	v_rcp_f32_e32 v10, v2
	v_add_f32_e32 v2, 1.0, v8
	v_fmac_f32_e32 v11, v19, v14
	v_rcp_f32_e32 v13, v2
	v_add_f32_e32 v2, 1.0, v9
	v_add_f32_e32 v14, 1.0, v16
	v_rcp_f32_e32 v66, v2
	v_mul_f32_e32 v2, 0xbfb8aa3b, v11
	v_or_b32_e32 v16, 0x9e0, v44
	v_exp_f32_e32 v11, v2
	v_lshlrev_b32_e32 v2, 1, v16
	v_lshl_add_u64 v[8:9], v[114:115], 0, v[2:3]
	global_load_dwordx4 v[36:39], v[8:9], off
	v_lshl_add_u64 v[8:9], v[110:111], 0, v[2:3]
	global_load_dwordx4 v[40:43], v[8:9], off
	v_lshlrev_b32_e32 v2, 2, v16
	global_load_dwordx4 v[16:19], v2, s[8:9] offset:16
	global_load_dwordx4 v[62:65], v2, s[8:9]
	v_add_f32_e32 v2, 1.0, v11
	v_rcp_f32_e32 v2, v2
	v_rcp_f32_e32 v14, v14
	v_cvt_pk_bf16_f32 v10, v10, v13
	v_cvt_pk_bf16_f32 v9, v12, v45
	v_cvt_pk_bf16_f32 v11, v66, v2
	s_waitcnt vmcnt(7)
; __device__ __forceinline__ float bflo(unsigned u) { return __uint_as_float(u << 16); }
; __device__ __forceinline__ void rwkv_prep_item(const Params& p, const Lt& lt, int l, int item) {
;     ...
;     for (int ks = 0; ks < 8; ++ks) {
;         const int col = COL_XW + ks * 32 + quad * 8;
;         const u32x4 c4 = *(const u32x4*)(pt + col), q4 = *(const u32x4*)(pp + col);
;         const f32x4 m0 = *(const f32x4*)(mu + col), m1 = *(const f32x4*)(mu + col + 4);
;         float v[8];
; #pragma unroll
;         for (int i = 0; i < 4; ++i) {
;             const float c0 = bflo(c4[i]), c1 = bfhi(c4[i]), p0 = bflo(q4[i]) * pm, p1 = bfhi(q4[i]) * pm;
;             const float mu0 = (i < 2) ? m0[2 * i] : m1[2 * i - 4], mu1 = (i < 2) ? m0[2 * i + 1] : m1[2 * i - 3];
;             v[2 * i] = c0 + (p0 - c0) * mu0; v[2 * i + 1] = c1 + (p1 - c1) * mu1;
;         }
;         if (ks < 2) {
; #pragma unroll
;             for (int i = 0; i < 8; ++i) v[i] = tanhf_(v[i]);
;         } else if (ks >= 4) {
; #pragma unroll
;             for (int i = 0; i < 8; ++i) v[i] = sigmoidf_(v[i]);
;         }
;         u32x4 pk; pk.x = cvt_pk_bf16(v[0], v[1]); pk.y = cvt_pk_bf16(v[2], v[3]); pk.z = cvt_pk_bf16(v[4], v[5]); pk.w = cvt_pk_bf16(v[6], v[7]);
;         const bf16x8 f = __builtin_bit_cast(bf16x8, pk);
;         if (ks < 2) fw[ks] = f; else if (ks < 4) fa[ks - 2] = f; else fg[ks - 4] = f;
;     }
;     ...
;     for (int hh = 0; hh < 3; ++hh) {
;         const int h = hg * 3 + hh;
;         f32x4 va[4], vkk[4];
;         float nrm = 0.f, bon = 0.f;
;         unsigned char* ob = opnd + (size_t)t * OPTB + h * OPB;
; #pragma unroll
;         for (int ct = 0; ct < 4; ++ct) {
;             const int crow = h * 64 + ct * 16 + qi;
;             f32x4 aw = {0.f, 0.f, 0.f, 0.f}, aa = aw, ag = aw;
; #pragma unroll
;             for (int ks = 0; ks < 2; ++ks) {
;                 aw = __builtin_amdgcn_mfma_f32_16x16x32_bf16(*(const bf16x8*)(decT + crow * 64 + ks * 32 + quad * 8), fw[ks], aw, 0, 0, 0);
;                 aa = __builtin_amdgcn_mfma_f32_16x16x32_bf16(*(const bf16x8*)(aT + crow * 64 + ks * 32 + quad * 8), fa[ks], aa, 0, 0, 0);
;             }
; #pragma unroll
;             for (int ks = 0; ks < 4; ++ks) ag = __builtin_amdgcn_mfma_f32_16x16x32_bf16(*(const bf16x8*)(gT + crow * 128 + ks * 32 + quad * 8), fg[ks], ag, 0, 0, 0);
;             const int c = h * 64 + ct * 16 + quad * 4;
	v_lshlrev_b32_e32 v2, 16, v46
	v_cvt_pk_bf16_f32 v8, v14, v15
	v_and_b32_e32 v12, 0xffff0000, v46
	s_waitcnt vmcnt(6)
	v_lshlrev_b32_e32 v13, 16, v50
	v_and_b32_e32 v14, 0xffff0000, v50
	v_fma_f32 v13, v0, v13, -v2
	s_waitcnt vmcnt(4)
	v_fmac_f32_e32 v2, v58, v13
	v_fma_f32 v13, v0, v14, -v12
	v_fmac_f32_e32 v12, v59, v13
	v_lshlrev_b32_e32 v13, 16, v47
	v_lshlrev_b32_e32 v15, 16, v51
	v_and_b32_e32 v14, 0xffff0000, v47
	v_and_b32_e32 v45, 0xffff0000, v51
	v_fma_f32 v15, v0, v15, -v13
	v_fmac_f32_e32 v13, v60, v15
	v_fma_f32 v15, v0, v45, -v14
	v_fmac_f32_e32 v14, v61, v15
	v_lshlrev_b32_e32 v15, 16, v48
	v_lshlrev_b32_e32 v46, 16, v52
	v_and_b32_e32 v45, 0xffff0000, v48
	v_and_b32_e32 v47, 0xffff0000, v52
	v_fma_f32 v46, v0, v46, -v15
	v_fmac_f32_e32 v15, v54, v46
	v_fma_f32 v46, v0, v47, -v45
	v_fmac_f32_e32 v45, v55, v46
	v_mul_f32_e32 v2, 0xbfb8aa3b, v2
	v_mul_f32_e32 v12, 0xbfb8aa3b, v12
	v_mul_f32_e32 v13, 0xbfb8aa3b, v13
	v_mul_f32_e32 v14, 0xbfb8aa3b, v14
	v_mul_f32_e32 v15, 0xbfb8aa3b, v15
	v_mul_f32_e32 v45, 0xbfb8aa3b, v45
	v_lshlrev_b32_e32 v46, 16, v49
	v_lshlrev_b32_e32 v48, 16, v53
	v_exp_f32_e32 v2, v2
	v_exp_f32_e32 v12, v12
	v_exp_f32_e32 v13, v13
	v_exp_f32_e32 v14, v14
	v_exp_f32_e32 v15, v15
	v_exp_f32_e32 v45, v45
	v_and_b32_e32 v47, 0xffff0000, v49
	v_and_b32_e32 v49, 0xffff0000, v53
	v_fma_f32 v48, v0, v48, -v46
	v_fmac_f32_e32 v46, v56, v48
	v_fma_f32 v48, v0, v49, -v47
	v_fmac_f32_e32 v47, v57, v48
	v_add_f32_e32 v2, 1.0, v2
	v_add_f32_e32 v12, 1.0, v12
	v_add_f32_e32 v13, 1.0, v13
	v_add_f32_e32 v14, 1.0, v14
	v_add_f32_e32 v15, 1.0, v15
	v_add_f32_e32 v45, 1.0, v45
	v_mul_f32_e32 v46, 0xbfb8aa3b, v46
	v_mul_f32_e32 v47, 0xbfb8aa3b, v47
	v_rcp_f32_e32 v2, v2
	v_rcp_f32_e32 v12, v12
	v_rcp_f32_e32 v13, v13
	v_rcp_f32_e32 v14, v14
	v_rcp_f32_e32 v15, v15
	v_exp_f32_e32 v46, v46
	v_exp_f32_e32 v47, v47
	v_rcp_f32_e32 v45, v45
	v_cvt_pk_bf16_f32 v12, v2, v12
	v_add_f32_e32 v46, 1.0, v46
	v_add_f32_e32 v47, 1.0, v47
	v_cvt_pk_bf16_f32 v13, v13, v14
	v_cvt_pk_bf16_f32 v14, v15, v45
	s_waitcnt vmcnt(3)
	v_lshlrev_b32_e32 v2, 16, v36
	v_and_b32_e32 v45, 0xffff0000, v36
	s_waitcnt vmcnt(2)
	v_lshlrev_b32_e32 v36, 16, v40
	v_rcp_f32_e32 v46, v46
	v_rcp_f32_e32 v47, v47
	v_and_b32_e32 v40, 0xffff0000, v40
	v_fma_f32 v36, v0, v36, -v2
	s_waitcnt vmcnt(0)
	v_fmac_f32_e32 v2, v62, v36
	v_fma_f32 v36, v0, v40, -v45
	v_or_b32_e32 v60, s5, v180
	v_fmac_f32_e32 v45, v63, v36
	v_lshlrev_b32_e32 v58, 16, v37
	v_and_b32_e32 v59, 0xffff0000, v37
	v_lshlrev_b32_e32 v36, 7, v60
	v_mov_b32_e32 v37, v3
	v_lshlrev_b32_e32 v50, 16, v41
	v_and_b32_e32 v54, 0xffff0000, v41
	v_lshl_add_u64 v[40:41], v[88:89], 0, v[36:37]
	v_cvt_pk_bf16_f32 v15, v46, v47
	global_load_dwordx4 v[46:49], v[40:41], off
	v_fma_f32 v50, v0, v50, -v58
	v_lshl_add_u64 v[36:37], v[92:93], 0, v[36:37]
	v_fmac_f32_e32 v58, v64, v50
	global_load_dwordx4 v[50:53], v[36:37], off
	global_load_dwordx4 v[68:71], v[36:37], off offset:64
	v_fma_f32 v54, v0, v54, -v59
	v_fmac_f32_e32 v59, v65, v54
	global_load_dwordx4 v[54:57], v[40:41], off offset:64
	v_or_b32_e32 v36, s5, v181
	v_lshlrev_b32_e32 v64, 1, v36
	v_mov_b32_e32 v65, v3
	v_lshlrev_b32_e32 v61, 16, v38
	v_and_b32_e32 v40, 0xffff0000, v38
	v_lshlrev_b32_e32 v38, 16, v42
	v_lshl_add_u64 v[90:91], v[114:115], 0, v[64:65]
	v_and_b32_e32 v41, 0xffff0000, v42
	v_fma_f32 v38, v0, v38, -v61
	global_load_dwordx2 v[98:99], v[90:91], off
	global_load_dwordx2 v[104:105], v[90:91], off offset:3072
	v_fmac_f32_e32 v61, v16, v38
	v_fma_f32 v16, v0, v41, -v40
	v_lshl_add_u64 v[96:97], v[110:111], 0, v[64:65]
	v_fmac_f32_e32 v40, v17, v16
	v_lshlrev_b32_e32 v16, 16, v39
	global_load_dwordx2 v[106:107], v[96:97], off
	global_load_dwordx2 v[66:67], v[90:91], off offset:1536
	v_and_b32_e32 v17, 0xffff0000, v39
	v_lshlrev_b32_e32 v37, 16, v43
	v_and_b32_e32 v38, 0xffff0000, v43
	v_fma_f32 v37, v0, v37, -v16
	v_fma_f32 v38, v0, v38, -v17
	v_lshlrev_b32_e32 v160, 2, v36
	v_fmac_f32_e32 v17, v19, v38
	v_fmac_f32_e32 v16, v18, v37
	global_load_dwordx4 v[36:39], v160, s[8:9]
	global_load_dwordx4 v[72:75], v160, s[42:43]
	global_load_dwordx2 v[108:109], v[96:97], off offset:1536
	global_load_dwordx2 v[120:121], v[96:97], off offset:3072
	global_load_dwordx4 v[76:79], v160, s[44:45]
	v_mul_f32_e32 v17, 0xbfb8aa3b, v17
	v_exp_f32_e32 v17, v17
	v_mul_f32_e32 v2, 0xbfb8aa3b, v2
	v_mul_f32_e32 v18, 0xbfb8aa3b, v58
	v_mul_f32_e32 v41, 0xbfb8aa3b, v59
	v_add_f32_e32 v17, 1.0, v17
	v_rcp_f32_e32 v19, v17
	v_mul_f32_e32 v17, 0xbfb8aa3b, v45
	v_mul_f32_e32 v42, 0xbfb8aa3b, v61
	v_mul_f32_e32 v40, 0xbfb8aa3b, v40
	v_exp_f32_e32 v2, v2
	v_exp_f32_e32 v17, v17
	v_exp_f32_e32 v18, v18
	v_exp_f32_e32 v41, v41
	v_exp_f32_e32 v42, v42
	v_exp_f32_e32 v40, v40
	v_mul_f32_e32 v16, 0xbfb8aa3b, v16
	v_exp_f32_e32 v16, v16
	v_add_f32_e32 v2, 1.0, v2
	v_add_f32_e32 v17, 1.0, v17
	v_add_f32_e32 v18, 1.0, v18
	v_add_f32_e32 v41, 1.0, v41
	v_add_f32_e32 v42, 1.0, v42
	v_add_f32_e32 v40, 1.0, v40
	v_rcp_f32_e32 v2, v2
	v_rcp_f32_e32 v17, v17
	v_rcp_f32_e32 v18, v18
	v_rcp_f32_e32 v41, v41
	v_rcp_f32_e32 v42, v42
	v_rcp_f32_e32 v40, v40
	v_add_f32_e32 v16, 1.0, v16
	v_rcp_f32_e32 v43, v16
	v_cvt_pk_bf16_f32 v16, v2, v17
	v_cvt_pk_bf16_f32 v17, v18, v41
	v_cvt_pk_bf16_f32 v18, v42, v40
	v_mov_b64_e32 v[40:41], s[36:37]
	v_cvt_pk_bf16_f32 v19, v43, v19
	v_mad_i64_i32 v[118:119], s[0:1], v84, s65, v[40:41]
	s_waitcnt vmcnt(12)
	v_mfma_f32_16x16x32_bf16 v[40:43], v[46:49], v[20:23], 0
	v_lshl_add_u64 v[86:87], v[118:119], 0, s[10:11]
	s_mov_b32 s10, 0xbfb8aa3b
	v_mov_b32_e32 v2, v44
	s_waitcnt vmcnt(11)
; __device__ __forceinline__ void rwkv_prep_item(const Params& p, const Lt& lt, int l, int item) {
;     ...
;         for (int ct = 0; ct < 4; ++ct) {
;             const int crow = h * 64 + ct * 16 + qi;
;             f32x4 aw = {0.f, 0.f, 0.f, 0.f}, aa = aw, ag = aw;
; #pragma unroll
;             for (int ks = 0; ks < 2; ++ks) {
;                 aw = __builtin_amdgcn_mfma_f32_16x16x32_bf16(*(const bf16x8*)(decT + crow * 64 + ks * 32 + quad * 8), fw[ks], aw, 0, 0, 0);
;                 aa = __builtin_amdgcn_mfma_f32_16x16x32_bf16(*(const bf16x8*)(aT + crow * 64 + ks * 32 + quad * 8), fa[ks], aa, 0, 0, 0);
;             }
; #pragma unroll
;             for (int ks = 0; ks < 4; ++ks) ag = __builtin_amdgcn_mfma_f32_16x16x32_bf16(*(const bf16x8*)(gT + crow * 128 + ks * 32 + quad * 8), fg[ks], ag, 0, 0, 0);
;             const int c = h * 64 + ct * 16 + quad * 4;
;             const f32x4 mr = *(const f32x4*)(mu + c), mk = *(const f32x4*)(mu + COL_K + c), mv = *(const f32x4*)(mu + COL_V + c);
;             const f32x4 cr = ld_bf4(pt + c), ck = ld_bf4(pt + COL_K + c), cv = ld_bf4(pt + COL_V + c);
;             const f32x4 qr = ld_bf4(pp + c) * pm, qk = ld_bf4(pp + COL_K + c) * pm, qv = ld_bf4(pp + COL_V + c) * pm;
;             const f32x4 r = cr + (qr - cr) * mr, k = ck + (qk - ck) * mk, v = cv + (qv - cv) * mv;
;             const f32x4 w0v = *(const f32x4*)(w0 + c), a0v = *(const f32x4*)(a0 + c), kkv = *(const f32x4*)(kkp + c), kav = *(const f32x4*)(kap + c), rkv = *(const f32x4*)(rkp + c);
;             f32x4 dec, a, kk, k2;
; #pragma unroll
;             for (int j = 0; j < 4; ++j) {
;                 const float z = -(w0v[j] + aw[j]);
;                 const float sp = fmaxf(z, 0.f) + __logf(1.0f + __expf(-fabsf(z)));
;                 dec[j] = __expf(-__expf(-sp - 0.5f));
;                 a[j] = sigmoidf_(a0v[j] + aa[j]);
;                 kk[j] = k[j] * kkv[j];
;                 nrm += kk[j] * kk[j];
;                 k2[j] = k[j] * (1.0f + (a[j] - 1.0f) * kav[j]);
;                 bon += r[j] * k2[j] * rkv[j];
;             }
;             va[ct] = a; vkk[ct] = kk;
;             { const int cc = ct * 16 + quad * 4; *(f32x4*)(ob + cc * 4) = dec; st_bf4(ob + 512 + cc * 2, k2); st_bf4(ob + 640 + cc * 2, v); st_bf4(ob + 768 + cc * 2, r); }
;             st_bf4((unsigned char*)((bf16_t*)gate + (size_t)t * RW + c), ag);
;         }
	v_mfma_f32_16x16x32_bf16 v[80:83], v[50:53], v[28:31], 0
	v_mov_b64_e32 v[44:45], s[38:39]
	s_movk_i32 s0, 0x600
	v_mad_i64_i32 v[116:117], s[0:1], v84, s0, v[44:45]
	s_waitcnt vmcnt(9)
	v_mfma_f32_16x16x32_bf16 v[100:103], v[54:57], v[24:27], v[40:43]
	v_lshlrev_b32_e32 v44, 8, v60
	v_mov_b32_e32 v45, v3
	v_lshl_add_u64 v[44:45], v[94:95], 0, v[44:45]
	v_mfma_f32_16x16x32_bf16 v[80:83], v[68:71], v[32:35], v[80:83]
	s_waitcnt vmcnt(8)
	v_lshlrev_b32_e32 v40, 16, v98
	v_and_b32_e32 v41, 0xffff0000, v98
	v_lshlrev_b32_e32 v42, 16, v99
	v_and_b32_e32 v43, 0xffff0000, v99
	v_xor_b32_e32 v123, 0x80000000, v41
	v_xor_b32_e32 v122, 0x80000000, v40
	s_waitcnt vmcnt(6)
	v_lshlrev_b32_e32 v98, 16, v106
	v_and_b32_e32 v99, 0xffff0000, v106
	v_lshlrev_b32_e32 v68, 16, v104
	v_and_b32_e32 v69, 0xffff0000, v104
	v_lshlrev_b32_e32 v70, 16, v105
	v_and_b32_e32 v71, 0xffff0000, v105
	v_lshlrev_b32_e32 v104, 16, v107
	v_and_b32_e32 v105, 0xffff0000, v107
	v_pk_fma_f32 v[122:123], v[0:1], v[98:99], v[122:123] op_sel_hi:[0,1,1]
	v_xor_b32_e32 v99, 0x80000000, v43
	v_xor_b32_e32 v98, 0x80000000, v42
	v_pk_fma_f32 v[98:99], v[0:1], v[104:105], v[98:99] op_sel_hi:[0,1,1]
	s_waitcnt vmcnt(4)
	v_pk_fma_f32 v[98:99], v[38:39], v[98:99], v[42:43]
	s_waitcnt vmcnt(3)
	v_add_f32_e32 v38, v100, v72
	v_pk_fma_f32 v[128:129], v[36:37], v[122:123], v[40:41]
	v_mul_f32_e64 v36, |v38|, s10
	v_exp_f32_e32 v39, v36
	s_waitcnt vmcnt(1)
	v_lshlrev_b32_e32 v106, 16, v120
	v_and_b32_e32 v107, 0xffff0000, v120
	v_xor_b32_e32 v37, 0x80000000, v69
	v_xor_b32_e32 v36, 0x80000000, v68
	v_pk_fma_f32 v[130:131], v[0:1], v[106:107], v[36:37] op_sel_hi:[0,1,1]
	v_add_f32_e32 v36, 1.0, v39
	v_cmp_gt_f32_e32 vcc, s75, v36
	global_load_dwordx4 v[60:63], v[44:45], off
	global_load_dwordx4 v[52:55], v[44:45], off offset:64
	global_load_dwordx4 v[48:51], v[44:45], off offset:128
	s_nop 0
	global_load_dwordx4 v[44:47], v[44:45], off offset:192
	v_cndmask_b32_e64 v39, 0, 32, vcc
	v_ldexp_f32 v36, v36, v39
	v_log_f32_e32 v39, v36
	v_lshlrev_b32_e32 v120, 16, v121
	v_and_b32_e32 v121, 0xffff0000, v121
	v_xor_b32_e32 v37, 0x80000000, v71
	v_xor_b32_e32 v36, 0x80000000, v70
	v_pk_fma_f32 v[140:141], v[0:1], v[120:121], v[36:37] op_sel_hi:[0,1,1]
	v_mul_f32_e32 v37, 0x3f317217, v39
	v_fma_f32 v37, v39, s57, -v37
	v_fmac_f32_e32 v37, 0x3377d1cf, v39
	v_fmac_f32_e32 v37, 0x3f317217, v39
	v_cmp_lt_f32_e64 s[0:1], |v39|, s58
	v_max_f32_e64 v36, -v38, 0
	v_cndmask_b32_e32 v38, 0, v243, vcc
	v_cndmask_b32_e64 v37, v39, v37, s[0:1]
	v_sub_f32_e32 v37, v37, v38
	v_add_f32_e32 v36, v36, v37
	global_load_dwordx4 v[56:59], v160, s[8:9] offset:3072
	v_sub_f32_e32 v36, -0.5, v36
	v_mul_f32_e32 v36, 0x3fb8aa3b, v36
	v_exp_f32_e32 v72, v36
	global_load_dwordx4 v[36:39], v160, s[46:47]
	global_load_dwordx4 v[104:107], v160, s[48:49]
	global_load_dwordx4 v[122:125], v160, s[52:53]
	global_load_dwordx4 v[40:43], v160, s[50:51]
	v_add_f32_e32 v73, v101, v73
	v_mul_f32_e64 v85, |v73|, s10
	v_exp_f32_e32 v85, v85
	s_waitcnt vmcnt(9)
	v_add_f32_e32 v76, v80, v76
	v_mul_f32_e32 v76, 0xbfb8aa3b, v76
	v_max_f32_e64 v73, -v73, 0
	v_add_f32_e32 v80, 1.0, v85
	v_cmp_gt_f32_e32 vcc, s75, v80
	v_add_f32_e32 v74, v102, v74
	v_exp_f32_e32 v76, v76
	v_cndmask_b32_e64 v85, 0, 32, vcc
	v_ldexp_f32 v80, v80, v85
	v_log_f32_e32 v80, v80
	v_add_f32_e32 v76, 1.0, v76
	v_rcp_f32_e32 v100, v76
	v_add_f32_e32 v76, v81, v77
	v_mul_f32_e32 v85, 0x3f317217, v80
	v_fma_f32 v85, v80, s57, -v85
	v_fmac_f32_e32 v85, 0x3377d1cf, v80
	v_fmac_f32_e32 v85, 0x3f317217, v80
	v_cmp_lt_f32_e64 s[0:1], |v80|, s58
	v_mul_f32_e32 v76, 0xbfb8aa3b, v76
	v_exp_f32_e32 v76, v76
	v_cndmask_b32_e64 v80, v80, v85, s[0:1]
	v_cndmask_b32_e32 v85, 0, v243, vcc
	v_sub_f32_e32 v80, v80, v85
	v_add_f32_e32 v73, v73, v80
	v_mul_f32_e64 v80, |v74|, s10
	v_exp_f32_e32 v80, v80
	v_add_f32_e32 v76, 1.0, v76
	v_add_f32_e32 v75, v103, v75
	v_rcp_f32_e32 v101, v76
	v_add_f32_e32 v77, 1.0, v80
	v_cmp_gt_f32_e32 vcc, s75, v77
	v_mul_f32_e64 v76, |v75|, s10
	v_exp_f32_e32 v76, v76
	v_cndmask_b32_e64 v80, 0, 32, vcc
	v_ldexp_f32 v77, v77, v80
	v_log_f32_e32 v77, v77
	v_add_f32_e32 v76, 1.0, v76
	v_max_f32_e64 v74, -v74, 0
	s_waitcnt vmcnt(8)
	v_mfma_f32_16x16x32_bf16 v[60:63], v[60:63], v[4:7], 0
	v_mul_f32_e32 v80, 0x3f317217, v77
	v_fma_f32 v80, v77, s57, -v80
	v_fmac_f32_e32 v80, 0x3377d1cf, v77
	v_fmac_f32_e32 v80, 0x3f317217, v77
	v_cmp_lt_f32_e64 s[0:1], |v77|, s58
	v_max_f32_e64 v75, -v75, 0
	s_waitcnt vmcnt(7)
	v_mfma_f32_16x16x32_bf16 v[52:55], v[52:55], v[8:11], v[60:63]
	v_cndmask_b32_e64 v77, v77, v80, s[0:1]
	v_cndmask_b32_e32 v80, 0, v243, vcc
	v_sub_f32_e32 v77, v77, v80
	v_cmp_gt_f32_e32 vcc, s75, v76
	v_add_f32_e32 v74, v74, v77
	v_add_f32_e32 v77, v82, v78
	v_cndmask_b32_e64 v78, 0, 32, vcc
	v_ldexp_f32 v76, v76, v78
	v_log_f32_e32 v76, v76
	v_mul_f32_e32 v77, 0xbfb8aa3b, v77
	v_exp_f32_e32 v77, v77
	v_sub_f32_e32 v73, -0.5, v73
	v_mul_f32_e32 v78, 0x3f317217, v76
	v_fma_f32 v78, v76, s57, -v78
	v_fmac_f32_e32 v78, 0x3377d1cf, v76
	v_fmac_f32_e32 v78, 0x3f317217, v76
	v_cmp_lt_f32_e64 s[0:1], |v76|, s58
	v_sub_f32_e32 v74, -0.5, v74
	v_mul_f32_e32 v73, 0x3fb8aa3b, v73
	v_cndmask_b32_e64 v76, v76, v78, s[0:1]
	v_cndmask_b32_e32 v78, 0, v243, vcc
	v_sub_f32_e32 v76, v76, v78
	v_add_f32_e32 v75, v75, v76
	v_add_f32_e32 v76, v83, v79
	v_mul_f32_e32 v76, 0xbfb8aa3b, v76
	v_exp_f32_e32 v76, v76
	v_sub_f32_e32 v75, -0.5, v75
	v_mul_f32_e32 v74, 0x3fb8aa3b, v74
	v_mul_f32_e32 v75, 0x3fb8aa3b, v75
	v_exp_f32_e32 v73, v73
	v_exp_f32_e32 v74, v74
	v_exp_f32_e32 v75, v75
	v_add_f32_e32 v77, 1.0, v77
	v_add_f32_e32 v76, 1.0, v76
	s_waitcnt vmcnt(6)
; __device__ __forceinline__ void rwkv_prep_item(const Params& p, const Lt& lt, int l, int item) {
;     ...
;         for (int ct = 0; ct < 4; ++ct) {
;             const int crow = h * 64 + ct * 16 + qi;
;             f32x4 aw = {0.f, 0.f, 0.f, 0.f}, aa = aw, ag = aw;
; #pragma unroll
;             for (int ks = 0; ks < 2; ++ks) {
;                 aw = __builtin_amdgcn_mfma_f32_16x16x32_bf16(*(const bf16x8*)(decT + crow * 64 + ks * 32 + quad * 8), fw[ks], aw, 0, 0, 0);
;                 aa = __builtin_amdgcn_mfma_f32_16x16x32_bf16(*(const bf16x8*)(aT + crow * 64 + ks * 32 + quad * 8), fa[ks], aa, 0, 0, 0);
;             }
; #pragma unroll
;             for (int ks = 0; ks < 4; ++ks) ag = __builtin_amdgcn_mfma_f32_16x16x32_bf16(*(const bf16x8*)(gT + crow * 128 + ks * 32 + quad * 8), fg[ks], ag, 0, 0, 0);
;             const int c = h * 64 + ct * 16 + quad * 4;
;             const f32x4 mr = *(const f32x4*)(mu + c), mk = *(const f32x4*)(mu + COL_K + c), mv = *(const f32x4*)(mu + COL_V + c);
;             const f32x4 cr = ld_bf4(pt + c), ck = ld_bf4(pt + COL_K + c), cv = ld_bf4(pt + COL_V + c);
;             const f32x4 qr = ld_bf4(pp + c) * pm, qk = ld_bf4(pp + COL_K + c) * pm, qv = ld_bf4(pp + COL_V + c) * pm;
;             const f32x4 r = cr + (qr - cr) * mr, k = ck + (qk - ck) * mk, v = cv + (qv - cv) * mv;
;             const f32x4 w0v = *(const f32x4*)(w0 + c), a0v = *(const f32x4*)(a0 + c), kkv = *(const f32x4*)(kkp + c), kav = *(const f32x4*)(kap + c), rkv = *(const f32x4*)(rkp + c);
;             f32x4 dec, a, kk, k2;
; #pragma unroll
;             for (int j = 0; j < 4; ++j) {
;                 const float z = -(w0v[j] + aw[j]);
;                 const float sp = fmaxf(z, 0.f) + __logf(1.0f + __expf(-fabsf(z)));
;                 dec[j] = __expf(-__expf(-sp - 0.5f));
;                 a[j] = sigmoidf_(a0v[j] + aa[j]);
;                 kk[j] = k[j] * kkv[j];
;                 nrm += kk[j] * kk[j];
;                 k2[j] = k[j] * (1.0f + (a[j] - 1.0f) * kav[j]);
;                 bon += r[j] * k2[j] * rkv[j];
;             }
;             va[ct] = a; vkk[ct] = kk;
;             { const int cc = ct * 16 + quad * 4; *(f32x4*)(ob + cc * 4) = dec; st_bf4(ob + 512 + cc * 2, k2); st_bf4(ob + 640 + cc * 2, v); st_bf4(ob + 768 + cc * 2, r); }
;             st_bf4((unsigned char*)((bf16_t*)gate + (size_t)t * RW + c), ag);
;         }
	v_mfma_f32_16x16x32_bf16 v[48:51], v[48:51], v[12:15], v[52:55]
	v_rcp_f32_e32 v120, v77
	v_rcp_f32_e32 v121, v76
	v_lshlrev_b32_e32 v78, 16, v66
	v_and_b32_e32 v79, 0xffff0000, v66
	v_lshlrev_b32_e32 v126, 16, v108
	v_and_b32_e32 v127, 0xffff0000, v108
	v_mul_f32_e32 v72, 0xbfb8aa3b, v72
	v_mul_f32_e32 v73, 0xbfb8aa3b, v73
	v_mul_f32_e32 v74, 0xbfb8aa3b, v74
	v_mul_f32_e32 v75, 0xbfb8aa3b, v75
	v_lshlrev_b32_e32 v76, 16, v67
	v_and_b32_e32 v77, 0xffff0000, v67
	v_xor_b32_e32 v81, 0x80000000, v79
	v_xor_b32_e32 v80, 0x80000000, v78
	v_lshlrev_b32_e32 v108, 16, v109
	v_and_b32_e32 v109, 0xffff0000, v109
	v_exp_f32_e32 v72, v72
	v_exp_f32_e32 v73, v73
	v_exp_f32_e32 v74, v74
	v_exp_f32_e32 v75, v75
	v_xor_b32_e32 v67, 0x80000000, v77
	v_xor_b32_e32 v66, 0x80000000, v76
	v_pk_fma_f32 v[80:81], v[0:1], v[126:127], v[80:81] op_sel_hi:[0,1,1]
	s_waitcnt vmcnt(5)
	v_mfma_f32_16x16x32_bf16 v[44:47], v[44:47], v[16:19], v[48:51]
	v_fma_f32 v66, v0, v108, v66
	v_fma_f32 v67, v0, v109, v67
	s_waitcnt vmcnt(4)
	v_pk_fma_f32 v[138:139], v[56:57], v[80:81], v[78:79]
	v_pk_add_f32 v[56:57], v[100:101], -1.0 op_sel_hi:[1,0]
	v_pk_add_f32 v[52:53], v[120:121], -1.0 op_sel_hi:[1,0]
	s_waitcnt vmcnt(2)
	v_pk_fma_f32 v[56:57], v[104:105], v[56:57], 1.0 op_sel_hi:[1,1,0]
	v_pk_fma_f32 v[132:133], v[58:59], v[66:67], v[76:77]
	v_pk_fma_f32 v[52:53], v[106:107], v[52:53], 1.0 op_sel_hi:[1,1,0]
	s_waitcnt vmcnt(1)
	v_pk_fma_f32 v[48:49], v[124:125], v[140:141], v[70:71]
	v_pk_fma_f32 v[50:51], v[122:123], v[130:131], v[68:69]
	s_or_b32 s0, s5, 16
	v_pk_mul_f32 v[136:137], v[138:139], v[56:57]
	v_pk_mul_f32 v[134:135], v[132:133], v[52:53]
	v_lshl_add_u64 v[52:53], v[86:87], 0, v[112:113]
	v_lshl_add_u64 v[122:123], v[86:87], 0, v[2:3]
	v_cvt_pk_bf16_f32 v50, v50, v51
	v_cvt_pk_bf16_f32 v51, v48, v49
	v_cvt_pk_bf16_f32 v48, v128, v129
	v_cvt_pk_bf16_f32 v49, v98, v99
	v_or_b32_e32 v58, s0, v180
	v_sub_u32_e32 v233, v52, v230
	ds_write_b128 v233, v[72:75]
	v_cvt_pk_bf16_f32 v52, v136, v137
	v_cvt_pk_bf16_f32 v53, v134, v135
	v_sub_u32_e32 v233, v122, v230
	ds_write_b64 v233, v[48:49] offset:768
	v_cvt_pk_bf16_f32 v44, v44, v45
	v_cvt_pk_bf16_f32 v45, v46, v47
	v_lshl_add_u64 v[124:125], v[116:117], 0, v[64:65]
	v_lshlrev_b32_e32 v48, 7, v58
	v_mov_b32_e32 v49, v3
	v_sub_u32_e32 v233, v122, v230
	ds_write_b64 v233, v[52:53] offset:512
	v_sub_u32_e32 v233, v122, v230
	ds_write_b64 v233, v[50:51] offset:640
	global_store_dwordx2 v[124:125], v[44:45], off
	v_lshl_add_u64 v[52:53], v[88:89], 0, v[48:49]
	global_load_dwordx2 v[236:237], v[90:91], off offset:32
	global_load_dwordx2 v[194:195], v[90:91], off offset:3104
	global_load_dwordx2 v[198:199], v[96:97], off offset:32
	global_load_dwordx2 v[206:207], v[96:97], off offset:1568
	global_load_dwordx2 v[248:249], v[96:97], off offset:3104
	global_load_dwordx4 v[210:213], v160, s[8:9] offset:64
	global_load_dwordx4 v[214:217], v160, s[42:43] offset:64
	global_load_dwordx4 v[218:221], v160, s[44:45] offset:64
	global_load_dwordx4 v[222:225], v160, s[8:9] offset:3136
	global_load_dwordx4 v[44:47], v[52:53], off
	v_lshl_add_u64 v[56:57], v[92:93], 0, v[48:49]
	global_load_dwordx4 v[48:51], v[56:57], off
	s_nop 0
	global_load_dwordx4 v[52:55], v[52:53], off offset:64
	s_nop 0
	global_load_dwordx4 v[68:71], v[56:57], off offset:64
	s_waitcnt vmcnt(12)
	v_mov_b64_e32 v[76:77], v[236:237]
	s_waitcnt vmcnt(11)
	v_mov_b64_e32 v[78:79], v[194:195]
	s_waitcnt vmcnt(10)
	v_mov_b64_e32 v[126:127], v[198:199]
	s_waitcnt vmcnt(9)
	v_mov_b64_e32 v[130:131], v[206:207]
	s_waitcnt vmcnt(8)
	v_mov_b64_e32 v[140:141], v[248:249]
	s_waitcnt vmcnt(7)
	v_mov_b64_e32 v[80:81], v[210:211]
	v_mov_b64_e32 v[82:83], v[212:213]
	s_waitcnt vmcnt(6)
	v_mov_b64_e32 v[102:103], v[214:215]
	v_mov_b64_e32 v[104:105], v[216:217]
	s_waitcnt vmcnt(5)
	v_mov_b64_e32 v[106:107], v[218:219]
	v_mov_b64_e32 v[108:109], v[220:221]
	global_load_dwordx2 v[154:155], v[90:91], off offset:1568
	s_waitcnt vmcnt(4)
	v_mfma_f32_16x16x32_bf16 v[44:47], v[44:47], v[20:23], 0
	v_lshlrev_b32_e32 v56, 8, v58
	v_mov_b32_e32 v57, v3
	v_lshl_add_u64 v[56:57], v[94:95], 0, v[56:57]
	s_waitcnt vmcnt(3)
	v_mfma_f32_16x16x32_bf16 v[48:51], v[48:51], v[28:31], 0
	global_load_dwordx4 v[72:75], v[56:57], off
	global_load_dwordx4 v[64:67], v[56:57], off offset:64
	global_load_dwordx4 v[60:63], v[56:57], off offset:128
	s_nop 0
	global_load_dwordx4 v[56:59], v[56:57], off offset:192
	s_waitcnt vmcnt(5)
	v_lshlrev_b32_e32 v156, 16, v130
	v_and_b32_e32 v157, 0xffff0000, v130
	v_mfma_f32_16x16x32_bf16 v[146:149], v[52:55], v[24:27], v[44:47]
	v_lshlrev_b32_e32 v158, 16, v131
	v_and_b32_e32 v159, 0xffff0000, v131
	s_waitcnt vmcnt(5)
	v_lshlrev_b32_e32 v130, 16, v141
	v_or_b32_e32 v44, s0, v181
	v_lshlrev_b32_e32 v44, 2, v44
	v_mfma_f32_16x16x32_bf16 v[150:153], v[68:71], v[32:35], v[48:51]
	s_waitcnt vmcnt(9)
	v_mov_b64_e32 v[68:69], v[222:223]
	v_mov_b64_e32 v[70:71], v[224:225]
	global_load_dwordx4 v[52:55], v44, s[52:53]
	v_lshlrev_b32_e32 v44, 16, v76
	v_and_b32_e32 v45, 0xffff0000, v76
	v_lshlrev_b32_e32 v46, 16, v77
	v_and_b32_e32 v47, 0xffff0000, v77
	v_lshlrev_b32_e32 v48, 16, v126
	v_and_b32_e32 v49, 0xffff0000, v126
	v_lshlrev_b32_e32 v50, 16, v127
	v_and_b32_e32 v51, 0xffff0000, v127
	v_lshlrev_b32_e32 v126, 16, v140
	v_and_b32_e32 v127, 0xffff0000, v140
	v_and_b32_e32 v131, 0xffff0000, v141
	v_xor_b32_e32 v141, 0x80000000, v45
	v_xor_b32_e32 v140, 0x80000000, v44
	v_pk_fma_f32 v[48:49], v[0:1], v[48:49], v[140:141] op_sel_hi:[0,1,1]
	v_xor_b32_e32 v141, 0x80000000, v47
	v_xor_b32_e32 v140, 0x80000000, v46
	v_pk_fma_f32 v[50:51], v[0:1], v[50:51], v[140:141] op_sel_hi:[0,1,1]
	s_waitcnt vmcnt(6)
; __device__ __forceinline__ void rwkv_prep_item(const Params& p, const Lt& lt, int l, int item) {
;     ...
;         for (int ct = 0; ct < 4; ++ct) {
;             const int crow = h * 64 + ct * 16 + qi;
;             f32x4 aw = {0.f, 0.f, 0.f, 0.f}, aa = aw, ag = aw;
; #pragma unroll
;             for (int ks = 0; ks < 2; ++ks) {
;                 aw = __builtin_amdgcn_mfma_f32_16x16x32_bf16(*(const bf16x8*)(decT + crow * 64 + ks * 32 + quad * 8), fw[ks], aw, 0, 0, 0);
;                 aa = __builtin_amdgcn_mfma_f32_16x16x32_bf16(*(const bf16x8*)(aT + crow * 64 + ks * 32 + quad * 8), fa[ks], aa, 0, 0, 0);
;             }
; #pragma unroll
;             for (int ks = 0; ks < 4; ++ks) ag = __builtin_amdgcn_mfma_f32_16x16x32_bf16(*(const bf16x8*)(gT + crow * 128 + ks * 32 + quad * 8), fg[ks], ag, 0, 0, 0);
;             const int c = h * 64 + ct * 16 + quad * 4;
;             const f32x4 mr = *(const f32x4*)(mu + c), mk = *(const f32x4*)(mu + COL_K + c), mv = *(const f32x4*)(mu + COL_V + c);
;             const f32x4 cr = ld_bf4(pt + c), ck = ld_bf4(pt + COL_K + c), cv = ld_bf4(pt + COL_V + c);
;             const f32x4 qr = ld_bf4(pp + c) * pm, qk = ld_bf4(pp + COL_K + c) * pm, qv = ld_bf4(pp + COL_V + c) * pm;
;             const f32x4 r = cr + (qr - cr) * mr, k = ck + (qk - ck) * mk, v = cv + (qv - cv) * mv;
;             const f32x4 w0v = *(const f32x4*)(w0 + c), a0v = *(const f32x4*)(a0 + c), kkv = *(const f32x4*)(kkp + c), kav = *(const f32x4*)(kap + c), rkv = *(const f32x4*)(rkp + c);
;             f32x4 dec, a, kk, k2;
; #pragma unroll
;             for (int j = 0; j < 4; ++j) {
;                 const float z = -(w0v[j] + aw[j]);
;                 const float sp = fmaxf(z, 0.f) + __logf(1.0f + __expf(-fabsf(z)));
;                 dec[j] = __expf(-__expf(-sp - 0.5f));
;                 a[j] = sigmoidf_(a0v[j] + aa[j]);
;                 kk[j] = k[j] * kkv[j];
;                 nrm += kk[j] * kk[j];
;                 k2[j] = k[j] * (1.0f + (a[j] - 1.0f) * kav[j]);
;                 bon += r[j] * k2[j] * rkv[j];
;             }
;             va[ct] = a; vkk[ct] = kk;
;             { const int cc = ct * 16 + quad * 4; *(f32x4*)(ob + cc * 4) = dec; st_bf4(ob + 512 + cc * 2, k2); st_bf4(ob + 640 + cc * 2, v); st_bf4(ob + 768 + cc * 2, r); }
;             st_bf4((unsigned char*)((bf16_t*)gate + (size_t)t * RW + c), ag);
;         }
	v_pk_fma_f32 v[142:143], v[82:83], v[50:51], v[46:47]
	s_waitcnt vmcnt(6)
	v_add_f32_e32 v46, v146, v102
	v_pk_fma_f32 v[144:145], v[80:81], v[48:49], v[44:45]
	v_mul_f32_e64 v44, |v46|, s10
	v_exp_f32_e32 v47, v44
	v_lshlrev_b32_e32 v76, 16, v78
	v_and_b32_e32 v77, 0xffff0000, v78
	v_xor_b32_e32 v45, 0x80000000, v77
	v_xor_b32_e32 v44, 0x80000000, v76
	v_pk_fma_f32 v[140:141], v[0:1], v[126:127], v[44:45] op_sel_hi:[0,1,1]
	v_add_f32_e32 v44, 1.0, v47
	v_cmp_gt_f32_e32 vcc, s75, v44
	v_lshlrev_b32_e32 v78, 16, v79
	v_and_b32_e32 v79, 0xffff0000, v79
	v_cndmask_b32_e64 v47, 0, 32, vcc
	v_ldexp_f32 v44, v44, v47
	v_log_f32_e32 v47, v44
	v_xor_b32_e32 v45, 0x80000000, v79
	v_xor_b32_e32 v44, 0x80000000, v78
	v_pk_fma_f32 v[162:163], v[0:1], v[130:131], v[44:45] op_sel_hi:[0,1,1]
	v_mul_f32_e32 v45, 0x3f317217, v47
	v_fma_f32 v45, v47, s57, -v45
	v_fmac_f32_e32 v45, 0x3377d1cf, v47
	v_fmac_f32_e32 v45, 0x3f317217, v47
	v_cmp_lt_f32_e64 s[0:1], |v47|, s58
	v_max_f32_e64 v44, -v46, 0
	v_cndmask_b32_e32 v46, 0, v243, vcc
	v_cndmask_b32_e64 v45, v47, v45, s[0:1]
	v_sub_f32_e32 v45, v45, v46
	v_add_f32_e32 v44, v44, v45
	v_sub_f32_e32 v44, -0.5, v44
	v_mul_f32_e32 v44, 0x3fb8aa3b, v44
	v_exp_f32_e32 v85, v44
	global_load_dwordx4 v[48:51], v160, s[46:47] offset:64
	global_load_dwordx4 v[80:83], v160, s[48:49] offset:64
	global_load_dwordx4 v[44:47], v160, s[50:51] offset:64
	v_add_f32_e32 v103, v147, v103
	v_mul_f32_e64 v102, |v103|, s10
	v_exp_f32_e32 v102, v102
	s_waitcnt vmcnt(9)
	v_add_f32_e32 v106, v150, v106
	v_mul_f32_e32 v106, 0xbfb8aa3b, v106
	v_exp_f32_e32 v106, v106
	v_add_f32_e32 v102, 1.0, v102
	v_cmp_gt_f32_e32 vcc, s75, v102
	v_mul_f32_e32 v85, 0xbfb8aa3b, v85
	v_max_f32_e64 v103, -v103, 0
	v_cndmask_b32_e64 v126, 0, 32, vcc
	v_ldexp_f32 v102, v102, v126
	v_log_f32_e32 v126, v102
	v_exp_f32_e32 v102, v85
	v_add_f32_e32 v85, 1.0, v106
	v_add_f32_e32 v104, v148, v104
	v_mul_f32_e32 v106, 0x3f317217, v126
	v_fma_f32 v106, v126, s57, -v106
	v_fmac_f32_e32 v106, 0x3377d1cf, v126
	v_fmac_f32_e32 v106, 0x3f317217, v126
	v_cmp_lt_f32_e64 s[0:1], |v126|, s58
	v_add_f32_e32 v105, v149, v105
	s_waitcnt vmcnt(7)
	v_mfma_f32_16x16x32_bf16 v[72:75], v[72:75], v[4:7], 0
	v_cndmask_b32_e64 v106, v126, v106, s[0:1]
	v_cndmask_b32_e32 v126, 0, v243, vcc
	v_sub_f32_e32 v106, v106, v126
	v_add_f32_e32 v103, v103, v106
	v_mul_f32_e64 v106, |v104|, s10
	v_sub_f32_e32 v103, -0.5, v103
	v_exp_f32_e32 v106, v106
	v_mul_f32_e32 v103, 0x3fb8aa3b, v103
	v_exp_f32_e32 v103, v103
	v_rcp_f32_e32 v126, v85
	v_add_f32_e32 v106, 1.0, v106
	v_cmp_gt_f32_e32 vcc, s75, v106
	v_mul_f32_e32 v85, 0xbfb8aa3b, v103
	v_add_f32_e32 v103, v151, v107
	v_cndmask_b32_e64 v107, 0, 32, vcc
	v_ldexp_f32 v106, v106, v107
	v_log_f32_e32 v106, v106
	v_mul_f32_e32 v103, 0xbfb8aa3b, v103
	v_exp_f32_e32 v107, v103
	v_max_f32_e64 v103, -v104, 0
	v_mul_f32_e32 v104, 0x3f317217, v106
	v_fma_f32 v104, v106, s57, -v104
	v_fmac_f32_e32 v104, 0x3377d1cf, v106
	v_fmac_f32_e32 v104, 0x3f317217, v106
	v_cmp_lt_f32_e64 s[0:1], |v106|, s58
	s_waitcnt vmcnt(6)
	v_mfma_f32_16x16x32_bf16 v[64:67], v[64:67], v[8:11], v[72:75]
	s_waitcnt vmcnt(3)
	v_pk_fma_f32 v[54:55], v[54:55], v[162:163], v[78:79]
	v_cndmask_b32_e64 v104, v106, v104, s[0:1]
	v_cndmask_b32_e32 v106, 0, v243, vcc
	v_sub_f32_e32 v104, v104, v106
	v_add_f32_e32 v103, v103, v104
	v_sub_f32_e32 v103, -0.5, v103
	v_mul_f32_e32 v103, 0x3fb8aa3b, v103
	v_exp_f32_e32 v104, v103
	v_exp_f32_e32 v103, v85
	v_add_f32_e32 v85, 1.0, v107
	v_rcp_f32_e32 v127, v85
	v_mul_f32_e32 v85, 0xbfb8aa3b, v104
	v_mul_f32_e64 v104, |v105|, s10
	v_exp_f32_e32 v104, v104
	v_add_f32_e32 v106, v152, v108
	v_mul_f32_e32 v106, 0xbfb8aa3b, v106
	v_exp_f32_e32 v106, v106
	v_add_f32_e32 v104, 1.0, v104
	v_cmp_gt_f32_e32 vcc, s75, v104
	v_max_f32_e64 v105, -v105, 0
	v_mfma_f32_16x16x32_bf16 v[60:63], v[60:63], v[12:15], v[64:67]
	v_cndmask_b32_e64 v107, 0, 32, vcc
	v_ldexp_f32 v104, v104, v107
	v_log_f32_e32 v107, v104
	v_exp_f32_e32 v104, v85
	v_add_f32_e32 v85, 1.0, v106
	v_rcp_f32_e32 v130, v85
	v_mul_f32_e32 v106, 0x3f317217, v107
	v_fma_f32 v106, v107, s57, -v106
	v_fmac_f32_e32 v106, 0x3377d1cf, v107
	v_fmac_f32_e32 v106, 0x3f317217, v107
	v_cmp_lt_f32_e64 s[0:1], |v107|, s58
	v_lshlrev_b32_e32 v108, 16, v154
	v_xor_b32_e32 v148, 0x80000000, v108
	v_cndmask_b32_e64 v106, v107, v106, s[0:1]
	v_cndmask_b32_e32 v107, 0, v243, vcc
	v_sub_f32_e32 v106, v106, v107
	v_add_f32_e32 v105, v105, v106
	v_sub_f32_e32 v105, -0.5, v105
	v_mul_f32_e32 v105, 0x3fb8aa3b, v105
	v_add_f32_e32 v106, v153, v109
	v_exp_f32_e32 v105, v105
	v_mul_f32_e32 v106, 0xbfb8aa3b, v106
	v_exp_f32_e32 v106, v106
	v_and_b32_e32 v107, 0xffff0000, v155
	v_mul_f32_e32 v85, 0xbfb8aa3b, v105
	v_exp_f32_e32 v105, v85
	v_add_f32_e32 v85, 1.0, v106
	v_rcp_f32_e32 v131, v85
	v_lshlrev_b32_e32 v106, 16, v155
	v_and_b32_e32 v109, 0xffff0000, v154
	v_xor_b32_e32 v147, 0x80000000, v107
	v_xor_b32_e32 v146, 0x80000000, v106
	v_xor_b32_e32 v149, 0x80000000, v109
	v_pk_fma_f32 v[146:147], v[0:1], v[158:159], v[146:147] op_sel_hi:[0,1,1]
	v_pk_fma_f32 v[148:149], v[0:1], v[156:157], v[148:149] op_sel_hi:[0,1,1]
	v_mfma_f32_16x16x32_bf16 v[56:59], v[56:59], v[16:19], v[60:63]
	v_fma_f32 v152, v68, v148, v108
	v_fma_f32 v153, v69, v149, v109
	v_pk_fma_f32 v[148:149], v[70:71], v[146:147], v[106:107]
	v_mov_b32_e32 v107, v3
	v_or_b32_e32 v62, 16, v181
	v_lshlrev_b32_e32 v106, 2, v62
	v_pk_add_f32 v[68:69], v[126:127], -1.0 op_sel_hi:[1,0]
	v_pk_add_f32 v[64:65], v[130:131], -1.0 op_sel_hi:[1,0]
	v_pk_fma_f32 v[52:53], v[52:53], v[140:141], v[76:77]
	v_lshl_add_u64 v[60:61], v[86:87], 0, v[106:107]
	v_lshlrev_b32_e32 v108, 1, v62
	v_mov_b32_e32 v109, v3
	s_waitcnt vmcnt(1)
; __device__ __forceinline__ void rwkv_prep_item(const Params& p, const Lt& lt, int l, int item) {
;     ...
;         for (int ct = 0; ct < 4; ++ct) {
;             const int crow = h * 64 + ct * 16 + qi;
;             f32x4 aw = {0.f, 0.f, 0.f, 0.f}, aa = aw, ag = aw;
; #pragma unroll
;             for (int ks = 0; ks < 2; ++ks) {
;                 aw = __builtin_amdgcn_mfma_f32_16x16x32_bf16(*(const bf16x8*)(decT + crow * 64 + ks * 32 + quad * 8), fw[ks], aw, 0, 0, 0);
;                 aa = __builtin_amdgcn_mfma_f32_16x16x32_bf16(*(const bf16x8*)(aT + crow * 64 + ks * 32 + quad * 8), fa[ks], aa, 0, 0, 0);
;             }
; #pragma unroll
;             for (int ks = 0; ks < 4; ++ks) ag = __builtin_amdgcn_mfma_f32_16x16x32_bf16(*(const bf16x8*)(gT + crow * 128 + ks * 32 + quad * 8), fg[ks], ag, 0, 0, 0);
;             const int c = h * 64 + ct * 16 + quad * 4;
;             const f32x4 mr = *(const f32x4*)(mu + c), mk = *(const f32x4*)(mu + COL_K + c), mv = *(const f32x4*)(mu + COL_V + c);
;             const f32x4 cr = ld_bf4(pt + c), ck = ld_bf4(pt + COL_K + c), cv = ld_bf4(pt + COL_V + c);
;             const f32x4 qr = ld_bf4(pp + c) * pm, qk = ld_bf4(pp + COL_K + c) * pm, qv = ld_bf4(pp + COL_V + c) * pm;
;             const f32x4 r = cr + (qr - cr) * mr, k = ck + (qk - ck) * mk, v = cv + (qv - cv) * mv;
;             const f32x4 w0v = *(const f32x4*)(w0 + c), a0v = *(const f32x4*)(a0 + c), kkv = *(const f32x4*)(kkp + c), kav = *(const f32x4*)(kap + c), rkv = *(const f32x4*)(rkp + c);
;             f32x4 dec, a, kk, k2;
; #pragma unroll
;             for (int j = 0; j < 4; ++j) {
;                 const float z = -(w0v[j] + aw[j]);
;                 const float sp = fmaxf(z, 0.f) + __logf(1.0f + __expf(-fabsf(z)));
;                 dec[j] = __expf(-__expf(-sp - 0.5f));
;                 a[j] = sigmoidf_(a0v[j] + aa[j]);
;                 kk[j] = k[j] * kkv[j];
;                 nrm += kk[j] * kk[j];
;                 k2[j] = k[j] * (1.0f + (a[j] - 1.0f) * kav[j]);
;                 bon += r[j] * k2[j] * rkv[j];
;             }
;             va[ct] = a; vkk[ct] = kk;
;             { const int cc = ct * 16 + quad * 4; *(f32x4*)(ob + cc * 4) = dec; st_bf4(ob + 512 + cc * 2, k2); st_bf4(ob + 640 + cc * 2, v); st_bf4(ob + 768 + cc * 2, r); }
;             st_bf4((unsigned char*)((bf16_t*)gate + (size_t)t * RW + c), ag);
;         }
	v_pk_fma_f32 v[68:69], v[80:81], v[68:69], 1.0 op_sel_hi:[1,1,0]
	v_pk_fma_f32 v[64:65], v[82:83], v[64:65], 1.0 op_sel_hi:[1,1,0]
	v_sub_u32_e32 v233, v60, v230
	ds_write_b128 v233, v[102:105]
	v_lshl_add_u64 v[60:61], v[86:87], 0, v[108:109]
	v_cvt_pk_bf16_f32 v52, v52, v53
	v_cvt_pk_bf16_f32 v53, v54, v55
	s_or_b32 s0, s5, 32
	v_pk_mul_f32 v[154:155], v[152:153], v[68:69]
	v_pk_mul_f32 v[150:151], v[148:149], v[64:65]
	v_sub_u32_e32 v233, v60, v230
	ds_write_b64 v233, v[52:53] offset:640
	v_cvt_pk_bf16_f32 v52, v144, v145
	v_cvt_pk_bf16_f32 v53, v142, v143
	v_or_b32_e32 v66, s0, v180
	v_cvt_pk_bf16_f32 v62, v154, v155
	v_cvt_pk_bf16_f32 v63, v150, v151
	v_sub_u32_e32 v233, v60, v230
	ds_write_b64 v233, v[52:53] offset:768
	v_cvt_pk_bf16_f32 v52, v56, v57
	v_cvt_pk_bf16_f32 v53, v58, v59
	v_lshlrev_b32_e32 v56, 7, v66
	v_mov_b32_e32 v57, v3
	v_sub_u32_e32 v233, v60, v230
	ds_write_b64 v233, v[62:63] offset:512
	global_store_dwordx2 v[124:125], v[52:53], off offset:32
	v_lshl_add_u64 v[60:61], v[88:89], 0, v[56:57]
	global_load_dwordx2 v[236:237], v[90:91], off offset:64
	global_load_dwordx2 v[194:195], v[90:91], off offset:3136
	global_load_dwordx2 v[198:199], v[96:97], off offset:64
	global_load_dwordx2 v[206:207], v[96:97], off offset:1600
	global_load_dwordx2 v[248:249], v[96:97], off offset:3136
	global_load_dwordx4 v[210:213], v160, s[8:9] offset:128
	global_load_dwordx4 v[214:217], v160, s[42:43] offset:128
	global_load_dwordx4 v[218:221], v160, s[44:45] offset:128
	global_load_dwordx4 v[222:225], v160, s[8:9] offset:3200
	global_load_dwordx4 v[52:55], v[60:61], off
	v_lshl_add_u64 v[64:65], v[92:93], 0, v[56:57]
	global_load_dwordx4 v[56:59], v[64:65], off
	s_nop 0
	global_load_dwordx4 v[60:63], v[60:61], off offset:64
	s_nop 0
	global_load_dwordx4 v[76:79], v[64:65], off offset:64
	s_waitcnt vmcnt(12)
	v_mov_b64_e32 v[102:103], v[236:237]
	s_waitcnt vmcnt(11)
	v_mov_b64_e32 v[104:105], v[194:195]
	s_waitcnt vmcnt(10)
	v_mov_b64_e32 v[140:141], v[198:199]
	s_waitcnt vmcnt(9)
	v_mov_b64_e32 v[146:147], v[206:207]
	s_waitcnt vmcnt(8)
	v_mov_b64_e32 v[156:157], v[248:249]
	s_waitcnt vmcnt(7)
	v_mov_b64_e32 v[162:163], v[210:211]
	v_mov_b64_e32 v[164:165], v[212:213]
	s_waitcnt vmcnt(6)
	v_mov_b64_e32 v[166:167], v[214:215]
	v_mov_b64_e32 v[168:169], v[216:217]
	s_waitcnt vmcnt(5)
	v_mov_b64_e32 v[170:171], v[218:219]
	v_mov_b64_e32 v[172:173], v[220:221]
	global_load_dwordx2 v[178:179], v[90:91], off offset:1600
	s_waitcnt vmcnt(4)
	v_mfma_f32_16x16x32_bf16 v[52:55], v[52:55], v[20:23], 0
	v_lshlrev_b32_e32 v64, 8, v66
	v_mov_b32_e32 v65, v3
	v_lshl_add_u64 v[64:65], v[94:95], 0, v[64:65]
	s_waitcnt vmcnt(3)
	v_mfma_f32_16x16x32_bf16 v[56:59], v[56:59], v[28:31], 0
	global_load_dwordx4 v[80:83], v[64:65], off
	global_load_dwordx4 v[72:75], v[64:65], off offset:64
	global_load_dwordx4 v[68:71], v[64:65], off offset:128
	s_nop 0
	global_load_dwordx4 v[64:67], v[64:65], off offset:192
	s_waitcnt vmcnt(5)
	v_lshlrev_b32_e32 v186, 16, v146
	v_and_b32_e32 v187, 0xffff0000, v146
	v_mfma_f32_16x16x32_bf16 v[174:177], v[60:63], v[24:27], v[52:55]
	v_lshlrev_b32_e32 v188, 16, v147
	v_and_b32_e32 v189, 0xffff0000, v147
	s_waitcnt vmcnt(5)
	v_lshlrev_b32_e32 v146, 16, v157
	v_or_b32_e32 v52, s0, v181
	v_lshlrev_b32_e32 v52, 2, v52
	v_mfma_f32_16x16x32_bf16 v[182:185], v[76:79], v[32:35], v[56:59]
	s_waitcnt vmcnt(9)
	v_mov_b64_e32 v[76:77], v[222:223]
	v_mov_b64_e32 v[78:79], v[224:225]
	global_load_dwordx4 v[60:63], v52, s[52:53]
	v_lshlrev_b32_e32 v52, 16, v102
	v_and_b32_e32 v53, 0xffff0000, v102
	v_lshlrev_b32_e32 v54, 16, v103
	v_and_b32_e32 v55, 0xffff0000, v103
	v_lshlrev_b32_e32 v56, 16, v140
	v_and_b32_e32 v57, 0xffff0000, v140
	v_lshlrev_b32_e32 v58, 16, v141
	v_and_b32_e32 v59, 0xffff0000, v141
	v_lshlrev_b32_e32 v140, 16, v156
	v_and_b32_e32 v141, 0xffff0000, v156
	v_and_b32_e32 v147, 0xffff0000, v157
	v_xor_b32_e32 v157, 0x80000000, v53
	v_xor_b32_e32 v156, 0x80000000, v52
	v_pk_fma_f32 v[56:57], v[0:1], v[56:57], v[156:157] op_sel_hi:[0,1,1]
	v_xor_b32_e32 v157, 0x80000000, v55
	v_xor_b32_e32 v156, 0x80000000, v54
	v_pk_fma_f32 v[58:59], v[0:1], v[58:59], v[156:157] op_sel_hi:[0,1,1]
	s_waitcnt vmcnt(6)
	v_pk_fma_f32 v[156:157], v[164:165], v[58:59], v[54:55]
	s_waitcnt vmcnt(6)
	v_add_f32_e32 v54, v174, v166
	v_pk_fma_f32 v[158:159], v[162:163], v[56:57], v[52:53]
	v_mul_f32_e64 v52, |v54|, s10
	v_exp_f32_e32 v55, v52
	v_lshlrev_b32_e32 v102, 16, v104
	v_and_b32_e32 v103, 0xffff0000, v104
	v_xor_b32_e32 v53, 0x80000000, v103
	v_xor_b32_e32 v52, 0x80000000, v102
	v_pk_fma_f32 v[190:191], v[0:1], v[140:141], v[52:53] op_sel_hi:[0,1,1]
	v_add_f32_e32 v52, 1.0, v55
	v_cmp_gt_f32_e32 vcc, s75, v52
	v_lshlrev_b32_e32 v104, 16, v105
	v_and_b32_e32 v105, 0xffff0000, v105
	v_cndmask_b32_e64 v55, 0, 32, vcc
	v_ldexp_f32 v52, v52, v55
	v_log_f32_e32 v55, v52
	v_xor_b32_e32 v53, 0x80000000, v105
	v_xor_b32_e32 v52, 0x80000000, v104
	v_pk_fma_f32 v[192:193], v[0:1], v[146:147], v[52:53] op_sel_hi:[0,1,1]
	v_mul_f32_e32 v53, 0x3f317217, v55
	v_fma_f32 v53, v55, s57, -v53
	v_fmac_f32_e32 v53, 0x3377d1cf, v55
	v_fmac_f32_e32 v53, 0x3f317217, v55
	v_cmp_lt_f32_e64 s[0:1], |v55|, s58
	v_max_f32_e64 v52, -v54, 0
	v_cndmask_b32_e32 v54, 0, v243, vcc
	v_cndmask_b32_e64 v53, v55, v53, s[0:1]
	v_add_f32_e32 v140, v175, v167
	v_sub_f32_e32 v53, v53, v54
	v_mul_f32_e64 v141, |v140|, s10
	v_add_f32_e32 v52, v52, v53
	v_exp_f32_e32 v141, v141
	v_sub_f32_e32 v52, -0.5, v52
	v_mul_f32_e32 v52, 0x3fb8aa3b, v52
	v_exp_f32_e32 v85, v52
	global_load_dwordx4 v[56:59], v160, s[46:47] offset:128
	global_load_dwordx4 v[162:165], v160, s[48:49] offset:128
	global_load_dwordx4 v[52:55], v160, s[50:51] offset:128
	v_add_f32_e32 v141, 1.0, v141
	v_cmp_gt_f32_e32 vcc, s75, v141
	s_waitcnt vmcnt(9)
; __device__ __forceinline__ void rwkv_prep_item(const Params& p, const Lt& lt, int l, int item) {
;     ...
;         for (int ct = 0; ct < 4; ++ct) {
;             const int crow = h * 64 + ct * 16 + qi;
;             f32x4 aw = {0.f, 0.f, 0.f, 0.f}, aa = aw, ag = aw;
; #pragma unroll
;             for (int ks = 0; ks < 2; ++ks) {
;                 aw = __builtin_amdgcn_mfma_f32_16x16x32_bf16(*(const bf16x8*)(decT + crow * 64 + ks * 32 + quad * 8), fw[ks], aw, 0, 0, 0);
;                 aa = __builtin_amdgcn_mfma_f32_16x16x32_bf16(*(const bf16x8*)(aT + crow * 64 + ks * 32 + quad * 8), fa[ks], aa, 0, 0, 0);
;             }
; #pragma unroll
;             for (int ks = 0; ks < 4; ++ks) ag = __builtin_amdgcn_mfma_f32_16x16x32_bf16(*(const bf16x8*)(gT + crow * 128 + ks * 32 + quad * 8), fg[ks], ag, 0, 0, 0);
;             const int c = h * 64 + ct * 16 + quad * 4;
;             const f32x4 mr = *(const f32x4*)(mu + c), mk = *(const f32x4*)(mu + COL_K + c), mv = *(const f32x4*)(mu + COL_V + c);
;             const f32x4 cr = ld_bf4(pt + c), ck = ld_bf4(pt + COL_K + c), cv = ld_bf4(pt + COL_V + c);
;             const f32x4 qr = ld_bf4(pp + c) * pm, qk = ld_bf4(pp + COL_K + c) * pm, qv = ld_bf4(pp + COL_V + c) * pm;
;             const f32x4 r = cr + (qr - cr) * mr, k = ck + (qk - ck) * mk, v = cv + (qv - cv) * mv;
;             const f32x4 w0v = *(const f32x4*)(w0 + c), a0v = *(const f32x4*)(a0 + c), kkv = *(const f32x4*)(kkp + c), kav = *(const f32x4*)(kap + c), rkv = *(const f32x4*)(rkp + c);
;             f32x4 dec, a, kk, k2;
; #pragma unroll
;             for (int j = 0; j < 4; ++j) {
;                 const float z = -(w0v[j] + aw[j]);
;                 const float sp = fmaxf(z, 0.f) + __logf(1.0f + __expf(-fabsf(z)));
;                 dec[j] = __expf(-__expf(-sp - 0.5f));
;                 a[j] = sigmoidf_(a0v[j] + aa[j]);
;                 kk[j] = k[j] * kkv[j];
;                 nrm += kk[j] * kk[j];
;                 k2[j] = k[j] * (1.0f + (a[j] - 1.0f) * kav[j]);
;                 bon += r[j] * k2[j] * rkv[j];
;             }
;             va[ct] = a; vkk[ct] = kk;
;             { const int cc = ct * 16 + quad * 4; *(f32x4*)(ob + cc * 4) = dec; st_bf4(ob + 512 + cc * 2, k2); st_bf4(ob + 640 + cc * 2, v); st_bf4(ob + 768 + cc * 2, r); }
;             st_bf4((unsigned char*)((bf16_t*)gate + (size_t)t * RW + c), ag);
;         }
	v_add_f32_e32 v146, v182, v170
	v_mul_f32_e32 v146, 0xbfb8aa3b, v146
	v_cndmask_b32_e64 v147, 0, 32, vcc
	v_ldexp_f32 v141, v141, v147
	v_exp_f32_e32 v146, v146
	v_log_f32_e32 v141, v141
	v_mul_f32_e32 v85, 0xbfb8aa3b, v85
	v_exp_f32_e32 v166, v85
	v_add_f32_e32 v85, 1.0, v146
	v_mul_f32_e32 v146, 0x3f317217, v141
	v_fma_f32 v146, v141, s57, -v146
	v_fmac_f32_e32 v146, 0x3377d1cf, v141
	v_fmac_f32_e32 v146, 0x3f317217, v141
	v_cmp_lt_f32_e64 s[0:1], |v141|, s58
	v_max_f32_e64 v140, -v140, 0
	s_waitcnt vmcnt(7)
	v_mfma_f32_16x16x32_bf16 v[80:83], v[80:83], v[4:7], 0
	v_cndmask_b32_e64 v141, v141, v146, s[0:1]
	v_cndmask_b32_e32 v146, 0, v243, vcc
	v_sub_f32_e32 v141, v141, v146
	v_add_f32_e32 v140, v140, v141
	v_sub_f32_e32 v140, -0.5, v140
	v_mul_f32_e32 v140, 0x3fb8aa3b, v140
	v_add_f32_e32 v146, v176, v168
	v_exp_f32_e32 v141, v140
	v_mul_f32_e64 v140, |v146|, s10
	v_exp_f32_e32 v147, v140
	v_max_f32_e64 v146, -v146, 0
	v_rcp_f32_e32 v140, v85
	v_mul_f32_e32 v85, 0xbfb8aa3b, v141
	v_add_f32_e32 v147, 1.0, v147
	v_cmp_gt_f32_e32 vcc, s75, v147
	v_add_f32_e32 v141, v183, v171
	v_mul_f32_e32 v141, 0xbfb8aa3b, v141
	v_cndmask_b32_e64 v161, 0, 32, vcc
	v_ldexp_f32 v147, v147, v161
	v_log_f32_e32 v147, v147
	v_exp_f32_e32 v141, v141
	v_exp_f32_e32 v167, v85
	s_waitcnt vmcnt(6)
	v_mfma_f32_16x16x32_bf16 v[72:75], v[72:75], v[8:11], v[80:83]
	v_mul_f32_e32 v161, 0x3f317217, v147
	v_fma_f32 v161, v147, s57, -v161
	v_fmac_f32_e32 v161, 0x3377d1cf, v147
	v_fmac_f32_e32 v161, 0x3f317217, v147
	v_cmp_lt_f32_e64 s[0:1], |v147|, s58
	v_add_f32_e32 v85, 1.0, v141
	v_rcp_f32_e32 v141, v85
	v_cndmask_b32_e64 v147, v147, v161, s[0:1]
	v_cndmask_b32_e32 v161, 0, v243, vcc
	v_sub_f32_e32 v147, v147, v161
	v_add_f32_e32 v146, v146, v147
	v_sub_f32_e32 v146, -0.5, v146
	v_mul_f32_e32 v146, 0x3fb8aa3b, v146
	v_exp_f32_e32 v146, v146
	v_add_f32_e32 v161, v184, v172
	v_mul_f32_e32 v161, 0xbfb8aa3b, v161
	v_exp_f32_e32 v161, v161
	v_mul_f32_e32 v85, 0xbfb8aa3b, v146
	v_add_f32_e32 v146, v177, v169
	v_mul_f32_e64 v147, |v146|, s10
	v_exp_f32_e32 v147, v147
	v_max_f32_e64 v146, -v146, 0
	s_waitcnt vmcnt(5)
	v_mfma_f32_16x16x32_bf16 v[68:71], v[68:71], v[12:15], v[72:75]
	v_lshlrev_b32_e32 v172, 16, v178
	v_add_f32_e32 v147, 1.0, v147
	v_cmp_gt_f32_e32 vcc, s75, v147
	v_lshlrev_b32_e32 v170, 16, v179
	v_and_b32_e32 v171, 0xffff0000, v179
	v_cndmask_b32_e64 v168, 0, 32, vcc
	v_ldexp_f32 v147, v147, v168
	v_log_f32_e32 v147, v147
	v_exp_f32_e32 v168, v85
	v_add_f32_e32 v85, 1.0, v161
	v_xor_b32_e32 v176, 0x80000000, v172
	v_mul_f32_e32 v161, 0x3f317217, v147
	v_fma_f32 v161, v147, s57, -v161
	v_fmac_f32_e32 v161, 0x3377d1cf, v147
	v_fmac_f32_e32 v161, 0x3f317217, v147
	v_cmp_lt_f32_e64 s[0:1], |v147|, s58
	s_waitcnt vmcnt(4)
	v_mfma_f32_16x16x32_bf16 v[64:67], v[64:67], v[16:19], v[68:71]
	v_xor_b32_e32 v175, 0x80000000, v171
	v_cndmask_b32_e64 v147, v147, v161, s[0:1]
	v_cndmask_b32_e32 v161, 0, v243, vcc
	v_sub_f32_e32 v147, v147, v161
	v_add_f32_e32 v146, v146, v147
	v_sub_f32_e32 v146, -0.5, v146
	v_mul_f32_e32 v146, 0x3fb8aa3b, v146
	v_exp_f32_e32 v147, v146
	v_add_f32_e32 v146, v185, v173
	v_mul_f32_e32 v146, 0xbfb8aa3b, v146
	v_exp_f32_e32 v161, v146
	v_rcp_f32_e32 v146, v85
	v_mul_f32_e32 v85, 0xbfb8aa3b, v147
	v_exp_f32_e32 v169, v85
	v_add_f32_e32 v85, 1.0, v161
	v_rcp_f32_e32 v147, v85
	v_and_b32_e32 v173, 0xffff0000, v178
	v_xor_b32_e32 v177, 0x80000000, v173
	v_or_b32_e32 v70, 32, v181
	v_xor_b32_e32 v174, 0x80000000, v170
	v_pk_fma_f32 v[176:177], v[0:1], v[186:187], v[176:177] op_sel_hi:[0,1,1]
	s_waitcnt vmcnt(3)
	v_pk_fma_f32 v[60:61], v[60:61], v[190:191], v[102:103]
	v_lshlrev_b32_e32 v102, 2, v70
	v_mov_b32_e32 v103, v3
	v_pk_fma_f32 v[174:175], v[0:1], v[188:189], v[174:175] op_sel_hi:[0,1,1]
	v_pk_fma_f32 v[76:77], v[76:77], v[176:177], v[172:173]
	v_pk_add_f32 v[172:173], v[140:141], -1.0 op_sel_hi:[1,0]
	v_pk_add_f32 v[72:73], v[146:147], -1.0 op_sel_hi:[1,0]
	v_pk_fma_f32 v[62:63], v[62:63], v[192:193], v[104:105]
	v_lshl_add_u64 v[68:69], v[86:87], 0, v[102:103]
	v_lshlrev_b32_e32 v104, 1, v70
	v_mov_b32_e32 v105, v3
	s_waitcnt vmcnt(1)
	v_pk_fma_f32 v[80:81], v[162:163], v[172:173], 1.0 op_sel_hi:[1,1,0]
	v_pk_fma_f32 v[170:171], v[78:79], v[174:175], v[170:171]
	v_pk_fma_f32 v[72:73], v[164:165], v[72:73], 1.0 op_sel_hi:[1,1,0]
	v_sub_u32_e32 v233, v68, v230
	ds_write_b128 v233, v[166:169]
	v_lshl_add_u64 v[68:69], v[86:87], 0, v[104:105]
	v_cvt_pk_bf16_f32 v60, v60, v61
	v_cvt_pk_bf16_f32 v61, v62, v63
	s_or_b32 s0, s5, 48
	v_pk_mul_f32 v[162:163], v[76:77], v[80:81]
	v_pk_mul_f32 v[164:165], v[170:171], v[72:73]
	v_sub_u32_e32 v233, v68, v230
	ds_write_b64 v233, v[60:61] offset:640
	v_cvt_pk_bf16_f32 v60, v158, v159
	v_cvt_pk_bf16_f32 v61, v156, v157
	v_or_b32_e32 v161, s0, v180
	v_cvt_pk_bf16_f32 v70, v162, v163
	v_cvt_pk_bf16_f32 v71, v164, v165
	v_sub_u32_e32 v233, v68, v230
	ds_write_b64 v233, v[60:61] offset:768
	v_cvt_pk_bf16_f32 v60, v64, v65
	v_cvt_pk_bf16_f32 v61, v66, v67
	v_lshlrev_b32_e32 v64, 7, v161
	v_mov_b32_e32 v65, v3
	v_sub_u32_e32 v233, v68, v230
	ds_write_b64 v233, v[70:71] offset:512
	global_store_dwordx2 v[124:125], v[60:61], off offset:64
	v_lshl_add_u64 v[68:69], v[88:89], 0, v[64:65]
	global_load_dwordx2 v[236:237], v[90:91], off offset:96
	global_load_dwordx2 v[194:195], v[90:91], off offset:1632
	global_load_dwordx2 v[198:199], v[90:91], off offset:3168
	global_load_dwordx2 v[206:207], v[96:97], off offset:96
	global_load_dwordx2 v[248:249], v[96:97], off offset:1632
	global_load_dwordx4 v[210:213], v160, s[8:9] offset:192
	global_load_dwordx4 v[214:217], v160, s[42:43] offset:192
	global_load_dwordx4 v[218:221], v160, s[44:45] offset:192
	global_load_dwordx4 v[222:225], v160, s[8:9] offset:3264
	global_load_dwordx4 v[60:63], v[68:69], off
	v_lshl_add_u64 v[70:71], v[92:93], 0, v[64:65]
	global_load_dwordx4 v[64:67], v[70:71], off
	global_load_dwordx4 v[72:75], v[68:69], off offset:64
	global_load_dwordx4 v[80:83], v[70:71], off offset:64
	s_waitcnt vmcnt(12)
; __device__ __forceinline__ void rwkv_prep_item(const Params& p, const Lt& lt, int l, int item) {
;     ...
;         for (int ct = 0; ct < 4; ++ct) {
;             const int crow = h * 64 + ct * 16 + qi;
;             f32x4 aw = {0.f, 0.f, 0.f, 0.f}, aa = aw, ag = aw;
; #pragma unroll
;             for (int ks = 0; ks < 2; ++ks) {
;                 aw = __builtin_amdgcn_mfma_f32_16x16x32_bf16(*(const bf16x8*)(decT + crow * 64 + ks * 32 + quad * 8), fw[ks], aw, 0, 0, 0);
;                 aa = __builtin_amdgcn_mfma_f32_16x16x32_bf16(*(const bf16x8*)(aT + crow * 64 + ks * 32 + quad * 8), fa[ks], aa, 0, 0, 0);
;             }
; #pragma unroll
;             for (int ks = 0; ks < 4; ++ks) ag = __builtin_amdgcn_mfma_f32_16x16x32_bf16(*(const bf16x8*)(gT + crow * 128 + ks * 32 + quad * 8), fg[ks], ag, 0, 0, 0);
;             const int c = h * 64 + ct * 16 + quad * 4;
;             const f32x4 mr = *(const f32x4*)(mu + c), mk = *(const f32x4*)(mu + COL_K + c), mv = *(const f32x4*)(mu + COL_V + c);
;             const f32x4 cr = ld_bf4(pt + c), ck = ld_bf4(pt + COL_K + c), cv = ld_bf4(pt + COL_V + c);
;             const f32x4 qr = ld_bf4(pp + c) * pm, qk = ld_bf4(pp + COL_K + c) * pm, qv = ld_bf4(pp + COL_V + c) * pm;
;             const f32x4 r = cr + (qr - cr) * mr, k = ck + (qk - ck) * mk, v = cv + (qv - cv) * mv;
;             const f32x4 w0v = *(const f32x4*)(w0 + c), a0v = *(const f32x4*)(a0 + c), kkv = *(const f32x4*)(kkp + c), kav = *(const f32x4*)(kap + c), rkv = *(const f32x4*)(rkp + c);
;             f32x4 dec, a, kk, k2;
; #pragma unroll
;             for (int j = 0; j < 4; ++j) {
;                 const float z = -(w0v[j] + aw[j]);
;                 const float sp = fmaxf(z, 0.f) + __logf(1.0f + __expf(-fabsf(z)));
;                 dec[j] = __expf(-__expf(-sp - 0.5f));
;                 a[j] = sigmoidf_(a0v[j] + aa[j]);
;                 kk[j] = k[j] * kkv[j];
;                 nrm += kk[j] * kk[j];
;                 k2[j] = k[j] * (1.0f + (a[j] - 1.0f) * kav[j]);
;                 bon += r[j] * k2[j] * rkv[j];
;             }
;             va[ct] = a; vkk[ct] = kk;
;             { const int cc = ct * 16 + quad * 4; *(f32x4*)(ob + cc * 4) = dec; st_bf4(ob + 512 + cc * 2, k2); st_bf4(ob + 640 + cc * 2, v); st_bf4(ob + 768 + cc * 2, r); }
;             st_bf4((unsigned char*)((bf16_t*)gate + (size_t)t * RW + c), ag);
;         }
	v_mov_b64_e32 v[166:167], v[236:237]
	s_waitcnt vmcnt(11)
	v_mov_b64_e32 v[168:169], v[194:195]
	s_waitcnt vmcnt(10)
	v_mov_b64_e32 v[172:173], v[198:199]
	s_waitcnt vmcnt(9)
	v_mov_b64_e32 v[174:175], v[206:207]
	s_waitcnt vmcnt(8)
	v_mov_b64_e32 v[176:177], v[248:249]
	v_and_b32_e32 v69, 64, v240
	v_xor_b32_e32 v68, 16, v240
	v_add_u32_e32 v69, 64, v69
	v_cmp_lt_i32_e32 vcc, v68, v69
	v_ashrrev_i32_e32 v85, 31, v84
	global_load_dwordx2 v[178:179], v[96:97], off offset:3168
	v_cndmask_b32_e32 v68, v240, v68, vcc
	v_lshlrev_b32_e32 v182, 2, v68
	v_xor_b32_e32 v68, 32, v240
	v_cmp_lt_i32_e32 vcc, v68, v69
	s_waitcnt vmcnt(1)
	v_lshlrev_b32_e32 v204, 16, v168
	v_cndmask_b32_e32 v68, v240, v68, vcc
	v_cmp_eq_u32_e32 vcc, 0, v1
	v_mul_f32_e32 v1, v128, v136
	v_lshlrev_b32_e32 v183, 2, v68
	v_lshlrev_b64 v[68:69], 6, v[84:85]
	v_pk_mul_f32 v[84:85], v[36:37], v[138:139]
	v_fma_f32 v1, v40, v1, 0
	v_mul_f32_e32 v40, v129, v137
	v_pk_mul_f32 v[36:37], v[84:85], v[84:85]
	v_fmac_f32_e32 v1, v41, v40
	v_mul_f32_e32 v40, v98, v134
	v_pk_mul_f32 v[136:137], v[38:39], v[132:133]
	v_fmac_f32_e32 v1, v42, v40
	v_pk_mul_f32 v[38:39], v[136:137], v[136:137]
	v_mul_f32_e32 v40, v99, v135
	v_add_f32_e32 v36, v36, v37
	v_fmac_f32_e32 v1, v43, v40
	v_pk_mul_f32 v[132:133], v[48:49], v[152:153]
	v_mul_f32_e32 v42, v144, v154
	v_add_f32_e32 v36, v38, v36
	v_pk_mul_f32 v[40:41], v[132:133], v[132:133]
	v_fmac_f32_e32 v1, v44, v42
	v_mul_f32_e32 v42, v145, v155
	s_waitcnt vmcnt(8)
	v_mov_b64_e32 v[152:153], v[210:211]
	v_mov_b64_e32 v[154:155], v[212:213]
	v_pk_mul_f32 v[128:129], v[56:57], v[76:77]
	s_waitcnt vmcnt(7)
	v_mov_b64_e32 v[76:77], v[214:215]
	v_mov_b64_e32 v[78:79], v[216:217]
	v_add_f32_e32 v36, v39, v36
	v_fmac_f32_e32 v1, v45, v42
	v_mul_f32_e32 v42, v142, v150
	v_pk_mul_f32 v[134:135], v[50:51], v[148:149]
	v_add_f32_e32 v36, v36, v40
	v_fmac_f32_e32 v1, v46, v42
	v_pk_mul_f32 v[42:43], v[134:135], v[134:135]
	v_mul_f32_e32 v44, v143, v151
	v_add_f32_e32 v36, v41, v36
	v_fmac_f32_e32 v1, v47, v44
	v_mul_f32_e32 v46, v158, v162
	v_add_f32_e32 v36, v42, v36
	v_pk_mul_f32 v[44:45], v[128:129], v[128:129]
	v_fmac_f32_e32 v1, v52, v46
	v_mul_f32_e32 v46, v159, v163
	v_add_f32_e32 v36, v43, v36
	v_fmac_f32_e32 v1, v53, v46
	v_mul_f32_e32 v46, v156, v164
	v_pk_mul_f32 v[138:139], v[58:59], v[170:171]
	v_add_f32_e32 v36, v36, v44
	v_fmac_f32_e32 v1, v54, v46
	v_pk_mul_f32 v[46:47], v[138:139], v[138:139]
	v_add_f32_e32 v36, v45, v36
	v_add_f32_e32 v36, v46, v36
	v_add_f32_e32 v184, v47, v36
	v_mul_f32_e32 v36, v157, v165
	v_fmac_f32_e32 v1, v55, v36
	v_lshlrev_b32_e32 v36, 8, v161
	v_mov_b32_e32 v37, v3
	v_lshl_add_u64 v[36:37], v[94:95], 0, v[36:37]
	v_lshl_add_u64 v[90:91], s[40:41], 0, v[68:69]
	s_waitcnt vmcnt(6)
	v_mov_b64_e32 v[68:69], v[218:219]
	v_mov_b64_e32 v[70:71], v[220:221]
	v_mfma_f32_16x16x32_bf16 v[40:43], v[60:63], v[20:23], 0
	global_load_dwordx4 v[52:55], v[36:37], off
	global_load_dwordx4 v[48:51], v[36:37], off offset:64
	global_load_dwordx4 v[44:47], v[36:37], off offset:128
	s_nop 0
	global_load_dwordx4 v[36:39], v[36:37], off offset:192
	v_lshlrev_b32_e32 v144, 16, v166
	v_and_b32_e32 v145, 0xffff0000, v166
	v_mfma_f32_16x16x32_bf16 v[96:99], v[64:67], v[28:31], 0
	s_waitcnt vmcnt(9)
	v_mov_b64_e32 v[64:65], v[222:223]
	v_mov_b64_e32 v[66:67], v[224:225]
	global_load_dwordx4 v[56:59], v160, s[46:47] offset:192
	global_load_dwordx4 v[60:63], v160, s[48:49] offset:192
	s_waitcnt vmcnt(7)
	v_lshlrev_b32_e32 v150, 16, v175
	v_and_b32_e32 v151, 0xffff0000, v175
	v_mfma_f32_16x16x32_bf16 v[156:159], v[72:75], v[24:27], v[40:43]
	v_lshlrev_b32_e32 v72, 16, v174
	v_and_b32_e32 v73, 0xffff0000, v174
	v_xor_b32_e32 v75, 0x80000000, v145
	v_xor_b32_e32 v74, 0x80000000, v144
	v_pk_fma_f32 v[174:175], v[0:1], v[72:73], v[74:75] op_sel_hi:[0,1,1]
	global_load_dwordx4 v[72:75], v160, s[50:51] offset:192
	v_or_b32_e32 v40, s0, v181
	v_lshlrev_b32_e32 v142, 16, v167
	v_and_b32_e32 v143, 0xffff0000, v167
	v_xor_b32_e32 v161, 0x80000000, v143
	v_xor_b32_e32 v160, 0x80000000, v142
	v_lshlrev_b32_e32 v164, 16, v169
	v_and_b32_e32 v148, 0xffff0000, v169
	v_pk_fma_f32 v[150:151], v[0:1], v[150:151], v[160:161] op_sel_hi:[0,1,1]
	v_and_b32_e32 v162, 0xffff0000, v168
	s_waitcnt vmcnt(8)
	v_lshlrev_b32_e32 v168, 16, v177
	v_and_b32_e32 v169, 0xffff0000, v177
	v_lshlrev_b32_e32 v40, 2, v40
	global_load_dwordx4 v[40:43], v40, s[52:53]
	v_mfma_f32_16x16x32_bf16 v[80:83], v[80:83], v[32:35], v[96:99]
	v_lshlrev_b32_e32 v166, 16, v176
	v_and_b32_e32 v167, 0xffff0000, v176
	s_waitcnt vmcnt(8)
	v_lshlrev_b32_e32 v170, 16, v178
	v_lshlrev_b32_e32 v96, 16, v172
	v_and_b32_e32 v97, 0xffff0000, v172
	v_lshlrev_b32_e32 v98, 16, v173
	v_and_b32_e32 v99, 0xffff0000, v173
	v_and_b32_e32 v171, 0xffff0000, v178
	v_lshlrev_b32_e32 v172, 16, v179
	v_and_b32_e32 v173, 0xffff0000, v179
	v_xor_b32_e32 v161, 0x80000000, v99
	v_xor_b32_e32 v160, 0x80000000, v98
	v_pk_fma_f32 v[160:161], v[0:1], v[172:173], v[160:161] op_sel_hi:[0,1,1]
	v_mov_b32_e32 v163, v205
	s_waitcnt vmcnt(7)
	v_mfma_f32_16x16x32_bf16 v[52:55], v[52:55], v[4:7], 0
	v_add_f32_e32 v76, v156, v76
	v_mul_f32_e64 v149, |v76|, s10
	v_exp_f32_e32 v149, v149
	v_pk_fma_f32 v[142:143], v[154:155], v[150:151], v[142:143]
	v_xor_b32_e32 v151, 0x80000000, v148
	v_xor_b32_e32 v150, 0x80000000, v164
	v_add_f32_e32 v149, 1.0, v149
	v_cmp_gt_f32_e64 s[0:1], s75, v149
	v_pk_fma_f32 v[144:145], v[152:153], v[174:175], v[144:145]
	v_pk_fma_f32 v[152:153], v[0:1], v[168:169], v[150:151] op_sel_hi:[0,1,1]
	v_cndmask_b32_e64 v156, 0, 32, s[0:1]
	v_ldexp_f32 v149, v149, v156
	v_log_f32_e32 v149, v149
	s_waitcnt vmcnt(2)
; __device__ __forceinline__ float sigmoidf_(float x) { return __builtin_amdgcn_rcpf(1.0f + __expf(-x)); }
; __device__ __forceinline__ void st_bf4(unsigned char* q, f32x4 v) { u32x2 w; w.x = cvt_pk_bf16(v[0], v[1]); w.y = cvt_pk_bf16(v[2], v[3]); *(u32x2*)q = w; }
; __device__ __forceinline__ f32x4 ld_bf4(const bf16_t* q) { const u32x2 u = *(const u32x2*)q; return (f32x4){bflo(u.x), bfhi(u.x), bflo(u.y), bfhi(u.y)}; }
; __device__ __forceinline__ void rwkv_prep_item(const Params& p, const Lt& lt, int l, int item) {
;     ...
;             const f32x4 mr = *(const f32x4*)(mu + c), mk = *(const f32x4*)(mu + COL_K + c), mv = *(const f32x4*)(mu + COL_V + c);
;             const f32x4 cr = ld_bf4(pt + c), ck = ld_bf4(pt + COL_K + c), cv = ld_bf4(pt + COL_V + c);
;             const f32x4 qr = ld_bf4(pp + c) * pm, qk = ld_bf4(pp + COL_K + c) * pm, qv = ld_bf4(pp + COL_V + c) * pm;
;             const f32x4 r = cr + (qr - cr) * mr, k = ck + (qk - ck) * mk, v = cv + (qv - cv) * mv;
;             const f32x4 w0v = *(const f32x4*)(w0 + c), a0v = *(const f32x4*)(a0 + c), kkv = *(const f32x4*)(kkp + c), kav = *(const f32x4*)(kap + c), rkv = *(const f32x4*)(rkp + c);
;             f32x4 dec, a, kk, k2;
; #pragma unroll
;             for (int j = 0; j < 4; ++j) {
;                 const float z = -(w0v[j] + aw[j]);
;                 const float sp = fmaxf(z, 0.f) + __logf(1.0f + __expf(-fabsf(z)));
;                 dec[j] = __expf(-__expf(-sp - 0.5f));
;                 a[j] = sigmoidf_(a0v[j] + aa[j]);
;                 kk[j] = k[j] * kkv[j];
;                 nrm += kk[j] * kk[j];
;                 k2[j] = k[j] * (1.0f + (a[j] - 1.0f) * kav[j]);
;                 bon += r[j] * k2[j] * rkv[j];
;             }
;             va[ct] = a; vkk[ct] = kk;
;             { const int cc = ct * 16 + quad * 4; *(f32x4*)(ob + cc * 4) = dec; st_bf4(ob + 512 + cc * 2, k2); st_bf4(ob + 640 + cc * 2, v); st_bf4(ob + 768 + cc * 2, r); }
;             st_bf4((unsigned char*)((bf16_t*)gate + (size_t)t * RW + c), ag);
;         }
	v_mov_b32_e32 v169, v60
	v_add_f32_e32 v60, v157, v77
	v_mov_b32_e32 v168, v64
	v_mul_f32_e64 v64, |v60|, s10
	v_exp_f32_e32 v64, v64
	v_mul_f32_e32 v156, 0x3f317217, v149
	v_fma_f32 v156, v149, s57, -v156
	v_fmac_f32_e32 v156, 0x3377d1cf, v149
	v_fmac_f32_e32 v156, 0x3f317217, v149
	v_cmp_lt_f32_e64 s[4:5], |v149|, s58
	v_add_f32_e32 v64, 1.0, v64
	v_add_f32_e32 v68, v80, v68
	v_cndmask_b32_e64 v149, v149, v156, s[4:5]
	v_cndmask_b32_e64 v156, 0, v243, s[0:1]
	v_cmp_gt_f32_e64 s[0:1], s75, v64
	v_mul_f32_e32 v68, 0xbfb8aa3b, v68
	v_exp_f32_e32 v68, v68
	v_cndmask_b32_e64 v77, 0, 32, s[0:1]
	v_ldexp_f32 v64, v64, v77
	v_log_f32_e32 v64, v64
	v_add_f32_e32 v68, 1.0, v68
	v_max_f32_e64 v60, -v60, 0
	v_rcp_f32_e32 v68, v68
	v_mul_f32_e32 v80, 0x3f317217, v64
	v_fma_f32 v80, v64, s57, -v80
	v_fmac_f32_e32 v80, 0x3377d1cf, v64
	v_fmac_f32_e32 v80, 0x3f317217, v64
	v_cmp_lt_f32_e64 s[4:5], |v64|, s58
	v_xor_b32_e32 v151, 0x80000000, v162
	v_xor_b32_e32 v150, 0x80000000, v204
	v_cndmask_b32_e64 v64, v64, v80, s[4:5]
	v_cndmask_b32_e64 v80, 0, v243, s[0:1]
	v_sub_f32_e32 v64, v64, v80
	v_add_f32_e32 v60, v60, v64
	v_add_f32_e32 v64, v81, v69
	v_mul_f32_e32 v64, 0xbfb8aa3b, v64
	v_sub_f32_e32 v60, -0.5, v60
	v_exp_f32_e32 v64, v64
	v_mul_f32_e32 v60, 0x3fb8aa3b, v60
	v_pk_fma_f32 v[154:155], v[0:1], v[166:167], v[150:151] op_sel_hi:[0,1,1]
	v_exp_f32_e32 v60, v60
	v_add_f32_e32 v167, -1.0, v68
	v_mov_b32_e32 v166, v154
	v_sub_f32_e32 v149, v149, v156
	v_pk_fma_f32 v[156:157], v[168:169], v[166:167], v[204:205]
	v_add_f32_e32 v64, 1.0, v64
	v_mul_f32_e32 v56, v56, v156
	v_pk_mul_f32 v[156:157], v[156:157], v[156:157] op_sel:[0,1] op_sel_hi:[1,0]
	v_xor_b32_e32 v151, 0x80000000, v97
	v_xor_b32_e32 v150, 0x80000000, v96
	v_mul_f32_e32 v77, v144, v156
	v_rcp_f32_e32 v69, v64
	v_mul_f32_e32 v60, 0xbfb8aa3b, v60
	v_add_f32_e32 v64, v158, v78
	v_pk_fma_f32 v[150:151], v[0:1], v[170:171], v[150:151] op_sel_hi:[0,1,1]
	s_waitcnt vmcnt(1)
	v_fmac_f32_e32 v1, v72, v77
	v_exp_f32_e32 v77, v60
	v_mov_b32_e32 v60, v65
	v_mul_f32_e64 v65, |v64|, s10
	v_exp_f32_e32 v65, v65
	v_max_f32_e64 v64, -v64, 0
	v_add_f32_e32 v81, -1.0, v69
	v_mov_b32_e32 v80, v155
	v_add_f32_e32 v65, 1.0, v65
	v_cmp_gt_f32_e64 s[0:1], s75, v65
	v_pk_fma_f32 v[60:61], v[60:61], v[80:81], v[162:163]
	v_mov_b32_e32 v81, v62
	v_cndmask_b32_e64 v72, 0, 32, s[0:1]
	v_ldexp_f32 v65, v65, v72
	v_log_f32_e32 v65, v65
	v_mul_f32_e32 v57, v57, v60
	v_pk_mul_f32 v[60:61], v[60:61], v[60:61] op_sel:[0,1] op_sel_hi:[1,0]
	v_max_f32_e64 v76, -v76, 0
	v_mul_f32_e32 v72, 0x3f317217, v65
	v_fma_f32 v72, v65, s57, -v72
	v_fmac_f32_e32 v72, 0x3377d1cf, v65
	v_fmac_f32_e32 v72, 0x3f317217, v65
	v_cmp_lt_f32_e64 s[4:5], |v65|, s58
	v_mul_f32_e32 v61, v145, v60
	v_fmac_f32_e32 v1, v73, v61
	v_cndmask_b32_e64 v65, v65, v72, s[4:5]
	v_cndmask_b32_e64 v72, 0, v243, s[0:1]
	v_sub_f32_e32 v65, v65, v72
	v_add_f32_e32 v64, v64, v65
	v_sub_f32_e32 v64, -0.5, v64
	v_mul_f32_e32 v64, 0x3fb8aa3b, v64
	v_add_f32_e32 v65, v82, v70
	v_exp_f32_e32 v70, v64
	v_mul_f32_e32 v65, 0xbfb8aa3b, v65
	v_exp_f32_e32 v65, v65
	v_add_f32_e32 v76, v76, v149
	v_mul_f32_e32 v61, 0xbfb8aa3b, v70
	v_exp_f32_e32 v78, v61
	v_add_f32_e32 v61, v159, v79
	v_mul_f32_e64 v62, |v61|, s10
	v_exp_f32_e32 v62, v62
	v_add_f32_e32 v64, 1.0, v65
	v_max_f32_e64 v61, -v61, 0
	v_sub_f32_e32 v76, -0.5, v76
	v_add_f32_e32 v62, 1.0, v62
	v_cmp_gt_f32_e64 s[0:1], s75, v62
	v_mfma_f32_16x16x32_bf16 v[48:51], v[48:51], v[8:11], v[52:55]
	v_mul_f32_e32 v76, 0x3fb8aa3b, v76
	v_cndmask_b32_e64 v65, 0, 32, s[0:1]
	v_ldexp_f32 v62, v62, v65
	v_log_f32_e32 v62, v62
	v_exp_f32_e32 v76, v76
	v_rcp_f32_e32 v64, v64
	v_mfma_f32_16x16x32_bf16 v[44:47], v[44:47], v[12:15], v[48:51]
	v_mul_f32_e32 v65, 0x3f317217, v62
	v_fma_f32 v65, v62, s57, -v65
	v_fmac_f32_e32 v65, 0x3377d1cf, v62
	v_fmac_f32_e32 v65, 0x3f317217, v62
	v_cmp_lt_f32_e64 s[4:5], |v62|, s58
	v_mul_f32_e32 v76, 0xbfb8aa3b, v76
	v_exp_f32_e32 v76, v76
	v_cndmask_b32_e64 v62, v62, v65, s[4:5]
	v_cndmask_b32_e64 v65, 0, v243, s[0:1]
	v_sub_f32_e32 v62, v62, v65
	v_add_f32_e32 v61, v61, v62
	v_add_f32_e32 v62, v83, v71
	v_mul_f32_e32 v62, 0xbfb8aa3b, v62
	v_exp_f32_e32 v62, v62
	v_sub_f32_e32 v61, -0.5, v61
	v_mul_f32_e32 v61, 0x3fb8aa3b, v61
	v_exp_f32_e32 v61, v61
	v_add_f32_e32 v62, 1.0, v62
	v_rcp_f32_e32 v65, v62
	v_add_f32_e32 v73, -1.0, v64
	v_mul_f32_e32 v61, 0xbfb8aa3b, v61
	v_mov_b32_e32 v80, v66
	v_mov_b32_e32 v72, v152
	v_mov_b32_e32 v165, v205
	v_exp_f32_e32 v79, v61
	v_fmac_f32_e32 v184, v56, v56
	v_pk_fma_f32 v[72:73], v[80:81], v[72:73], v[164:165]
	v_add_f32_e32 v71, -1.0, v65
	v_mov_b32_e32 v62, v67
	v_mov_b32_e32 v70, v153
	v_mov_b32_e32 v149, v205
	v_mfma_f32_16x16x32_bf16 v[36:39], v[36:39], v[16:19], v[44:47]
	v_fmac_f32_e32 v184, v57, v57
	v_mul_f32_e32 v58, v58, v72
	v_pk_fma_f32 v[52:53], v[62:63], v[70:71], v[148:149]
	v_or_b32_e32 v46, 48, v181
	s_waitcnt vmcnt(0)
	v_pk_fma_f32 v[40:41], v[40:41], v[150:151], v[96:97]
	v_lshlrev_b32_e32 v96, 2, v46
	v_mov_b32_e32 v97, v3
	v_fmac_f32_e32 v184, v58, v58
	v_pk_mul_f32 v[72:73], v[72:73], v[72:73] op_sel:[0,1] op_sel_hi:[1,0]
	v_mul_f32_e32 v59, v59, v52
	v_pk_mul_f32 v[48:49], v[52:53], v[52:53] op_sel:[0,1] op_sel_hi:[1,0]
	v_pk_fma_f32 v[42:43], v[42:43], v[160:161], v[98:99]
	v_lshl_add_u64 v[44:45], v[86:87], 0, v[96:97]
	v_lshlrev_b32_e32 v98, 1, v46
	v_mov_b32_e32 v99, v3
	v_fmac_f32_e32 v184, v59, v59
	v_sub_u32_e32 v233, v44, v230
	ds_write_b128 v233, v[76:79]
	v_lshl_add_u64 v[44:45], v[86:87], 0, v[98:99]
	v_cvt_pk_bf16_f32 v46, v156, v60
	v_cvt_pk_bf16_f32 v47, v72, v48
	v_sub_u32_e32 v233, v44, v230
	ds_write_b64 v233, v[46:47] offset:512
	ds_bpermute_b32 v46, v182, v184
	v_cvt_pk_bf16_f32 v40, v40, v41
	v_cvt_pk_bf16_f32 v41, v42, v43
	v_mul_f32_e32 v66, v142, v72
	v_fmac_f32_e32 v1, v74, v66
	s_waitcnt lgkmcnt(0)
; __device__ __forceinline__ float quad_sum(float v) { v += xor16(v); v += xor32(v); return v; }
; __device__ __forceinline__ void st_bf4(unsigned char* q, f32x4 v) { u32x2 w; w.x = cvt_pk_bf16(v[0], v[1]); w.y = cvt_pk_bf16(v[2], v[3]); *(u32x2*)q = w; }
; __device__ __forceinline__ void rwkv_prep_item(const Params& p, const Lt& lt, int l, int item) {
;     ...
;         nrm = quad_sum(nrm); bon = quad_sum(bon);
;         const float inv = rsqrtf(fmaxf(nrm, 1e-24f));
; #pragma unroll
;         for (int ct = 0; ct < 4; ++ct) {
;             const int cc = ct * 16 + quad * 4;
;             const f32x4 kkn = vkk[ct] * inv;
;             st_bf4(ob + 256 + cc * 2, -kkn);
;             st_bf4(ob + 384 + cc * 2, kkn * va[ct]);
;         }
;         if (quad == 0) bonus[(size_t)t * 16 + h] = bon;
	v_add_f32_e32 v42, v184, v46
	ds_bpermute_b32 v43, v183, v42
	v_mul_f32_e32 v49, v143, v48
	v_fmac_f32_e32 v1, v75, v49
	v_cvt_pk_bf16_f32 v36, v36, v37
	v_cvt_pk_bf16_f32 v37, v38, v39
	s_waitcnt lgkmcnt(0)
	v_add_f32_e32 v38, v42, v43
	ds_bpermute_b32 v39, v182, v1
	v_max_f32_e32 v38, 0x179abe15, v38
	v_rsq_f32_e32 v38, v38
	v_sub_u32_e32 v233, v44, v230
	ds_write_b64 v233, v[40:41] offset:640
	v_cvt_pk_bf16_f32 v40, v144, v145
	v_cvt_pk_bf16_f32 v41, v142, v143
	v_sub_u32_e32 v233, v44, v230
	ds_write_b64 v233, v[40:41] offset:768
	s_waitcnt lgkmcnt(0)
	v_pk_mul_f32 v[40:41], v[84:85], v[38:39] op_sel_hi:[1,0]
	v_pk_mul_f32 v[42:43], v[136:137], v[38:39] op_sel_hi:[1,0]
	global_store_dwordx2 v[124:125], v[36:37], off offset:96
	v_add_f32_e32 v1, v1, v39
	v_xor_b32_e32 v37, 0x80000000, v43
	v_xor_b32_e32 v39, 0x80000000, v42
	v_xor_b32_e32 v44, 0x80000000, v41
	v_xor_b32_e32 v45, 0x80000000, v40
	v_pk_mul_f32 v[42:43], v[120:121], v[42:43]
	v_pk_mul_f32 v[40:41], v[100:101], v[40:41]
	v_cvt_pk_bf16_f32 v44, v45, v44
	v_cvt_pk_bf16_f32 v40, v40, v41
	v_cvt_pk_bf16_f32 v41, v42, v43
	v_cvt_pk_bf16_f32 v45, v39, v37
	v_sub_u32_e32 v233, v122, v230
	ds_write_b64 v233, v[40:41] offset:384
	v_pk_mul_f32 v[40:41], v[132:133], v[38:39] op_sel_hi:[1,0]
	v_pk_mul_f32 v[42:43], v[134:135], v[38:39] op_sel_hi:[1,0]
	v_sub_u32_e32 v233, v122, v230
	ds_write_b64 v233, v[44:45] offset:256
	v_xor_b32_e32 v37, 0x80000000, v43
	v_xor_b32_e32 v39, 0x80000000, v42
	v_xor_b32_e32 v44, 0x80000000, v41
	v_xor_b32_e32 v45, 0x80000000, v40
	v_pk_mul_f32 v[42:43], v[130:131], v[42:43]
	v_pk_mul_f32 v[40:41], v[126:127], v[40:41]
	v_cvt_pk_bf16_f32 v44, v45, v44
	v_cvt_pk_bf16_f32 v40, v40, v41
	v_cvt_pk_bf16_f32 v41, v42, v43
	v_cvt_pk_bf16_f32 v45, v39, v37
	v_sub_u32_e32 v233, v122, v230
	ds_write_b64 v233, v[40:41] offset:416
	v_pk_mul_f32 v[40:41], v[128:129], v[38:39] op_sel_hi:[1,0]
	v_pk_mul_f32 v[42:43], v[138:139], v[38:39] op_sel_hi:[1,0]
	ds_bpermute_b32 v36, v183, v1
	v_sub_u32_e32 v233, v122, v230
	ds_write_b64 v233, v[44:45] offset:288
	v_xor_b32_e32 v37, 0x80000000, v43
	v_xor_b32_e32 v39, 0x80000000, v42
	v_xor_b32_e32 v44, 0x80000000, v41
	v_xor_b32_e32 v45, 0x80000000, v40
	v_pk_mul_f32 v[42:43], v[146:147], v[42:43]
	v_pk_mul_f32 v[40:41], v[140:141], v[40:41]
	v_cvt_pk_bf16_f32 v44, v45, v44
	v_cvt_pk_bf16_f32 v40, v40, v41
	v_cvt_pk_bf16_f32 v41, v42, v43
	v_cvt_pk_bf16_f32 v45, v39, v37
	v_sub_u32_e32 v233, v122, v230
	ds_write_b64 v233, v[40:41] offset:448
	v_pk_mul_f32 v[40:41], v[56:57], v[38:39] op_sel_hi:[1,0]
	v_pk_mul_f32 v[38:39], v[58:59], v[38:39] op_sel_hi:[1,0]
	v_sub_u32_e32 v233, v122, v230
	ds_write_b64 v233, v[44:45] offset:320
	v_xor_b32_e32 v37, 0x80000000, v39
	v_xor_b32_e32 v43, 0x80000000, v38
	v_xor_b32_e32 v42, 0x80000000, v41
	v_xor_b32_e32 v44, 0x80000000, v40
	v_pk_mul_f32 v[38:39], v[64:65], v[38:39]
	v_pk_mul_f32 v[40:41], v[68:69], v[40:41]
	v_cvt_pk_bf16_f32 v42, v44, v42
	v_cvt_pk_bf16_f32 v43, v43, v37
	v_cvt_pk_bf16_f32 v40, v40, v41
	v_cvt_pk_bf16_f32 v41, v38, v39
	v_sub_u32_e32 v233, v122, v230
	ds_write_b64 v233, v[42:43] offset:352
	v_sub_u32_e32 v233, v122, v230
	ds_write_b64 v233, v[40:41] offset:480
	s_waitcnt lgkmcnt(0)
	s_mov_b32 s98, -1
	s_mov_b32 s99, 0xffffff
	s_mov_b64 exec, s[98:99]
	s_movk_i32 s98, 0
	s_mov_b32 s99, 0
	v_lshl_add_u64 v[228:229], v[234:235], 0, s[98:99]
	s_movk_i32 s98, 0x2a00
	ds_read_b128 v[210:213], v226 offset:0
	ds_read_b128 v[214:217], v226 offset:912
	ds_read_b128 v[218:221], v226 offset:1824
	ds_read_b128 v[222:225], v226 offset:2736
	s_waitcnt lgkmcnt(3)
	global_store_dwordx4 v[228:229], v[210:213], off
	v_lshl_add_u64 v[228:229], v[228:229], 0, s[98:99]
	s_waitcnt lgkmcnt(2)
	global_store_dwordx4 v[228:229], v[214:217], off
	v_lshl_add_u64 v[228:229], v[228:229], 0, s[98:99]
	s_waitcnt lgkmcnt(1)
	global_store_dwordx4 v[228:229], v[218:221], off
	v_lshl_add_u64 v[228:229], v[228:229], 0, s[98:99]
	s_waitcnt lgkmcnt(0)
	global_store_dwordx4 v[228:229], v[222:225], off
	v_lshl_add_u64 v[228:229], v[228:229], 0, s[98:99]
	ds_read_b128 v[210:213], v226 offset:3648
	ds_read_b128 v[214:217], v226 offset:4560
	ds_read_b128 v[218:221], v226 offset:5472
	ds_read_b128 v[222:225], v226 offset:6384
	s_waitcnt lgkmcnt(3)
	global_store_dwordx4 v[228:229], v[210:213], off
	v_lshl_add_u64 v[228:229], v[228:229], 0, s[98:99]
	s_waitcnt lgkmcnt(2)
	global_store_dwordx4 v[228:229], v[214:217], off
	v_lshl_add_u64 v[228:229], v[228:229], 0, s[98:99]
	s_waitcnt lgkmcnt(1)
	global_store_dwordx4 v[228:229], v[218:221], off
	v_lshl_add_u64 v[228:229], v[228:229], 0, s[98:99]
	s_waitcnt lgkmcnt(0)
	global_store_dwordx4 v[228:229], v[222:225], off
	v_lshl_add_u64 v[228:229], v[228:229], 0, s[98:99]
	ds_read_b128 v[210:213], v226 offset:7296
	ds_read_b128 v[214:217], v226 offset:8208
	ds_read_b128 v[218:221], v226 offset:9120
	ds_read_b128 v[222:225], v226 offset:10032
	s_waitcnt lgkmcnt(3)
	global_store_dwordx4 v[228:229], v[210:213], off
	v_lshl_add_u64 v[228:229], v[228:229], 0, s[98:99]
	s_waitcnt lgkmcnt(2)
	global_store_dwordx4 v[228:229], v[214:217], off
	v_lshl_add_u64 v[228:229], v[228:229], 0, s[98:99]
	s_waitcnt lgkmcnt(1)
	global_store_dwordx4 v[228:229], v[218:221], off
	v_lshl_add_u64 v[228:229], v[228:229], 0, s[98:99]
	s_waitcnt lgkmcnt(0)
	global_store_dwordx4 v[228:229], v[222:225], off
	v_lshl_add_u64 v[228:229], v[228:229], 0, s[98:99]
	ds_read_b128 v[210:213], v226 offset:10944
	ds_read_b128 v[214:217], v226 offset:11856
	ds_read_b128 v[218:221], v226 offset:12768
	ds_read_b128 v[222:225], v226 offset:13680
	s_waitcnt lgkmcnt(3)
	global_store_dwordx4 v[228:229], v[210:213], off
	v_lshl_add_u64 v[228:229], v[228:229], 0, s[98:99]
	s_waitcnt lgkmcnt(2)
	global_store_dwordx4 v[228:229], v[214:217], off
	v_lshl_add_u64 v[228:229], v[228:229], 0, s[98:99]
	s_waitcnt lgkmcnt(1)
	global_store_dwordx4 v[228:229], v[218:221], off
	v_lshl_add_u64 v[228:229], v[228:229], 0, s[98:99]
	s_waitcnt lgkmcnt(0)
	global_store_dwordx4 v[228:229], v[222:225], off
	v_lshl_add_u64 v[228:229], v[228:229], 0, s[98:99]
	s_mov_b64 exec, -1
	s_and_saveexec_b64 s[0:1], vcc
	s_cbranch_execz .LBB0_345
	s_lshl_b32 s10, s56, 2
	v_lshl_add_u64 v[38:39], v[90:91], 0, s[10:11]
	s_waitcnt lgkmcnt(0)
	v_add_f32_e32 v1, v1, v36
	global_store_dword v[38:39], v1, off
; __device__ __forceinline__ f32x4 ld_bf4(const bf16_t* q) { const u32x2 u = *(const u32x2*)q; return (f32x4){bflo(u.x), bfhi(u.x), bflo(u.y), bfhi(u.y)}; }
; __device__ __forceinline__ void rwkv_prep_item(const Params& p, const Lt& lt, int l, int item) {
;     ...
;     for (int hh = 0; hh < 3; ++hh) {
;         const int h = hg * 3 + hh;
;         f32x4 va[4], vkk[4];
;         float nrm = 0.f, bon = 0.f;
;         unsigned char* ob = opnd + (size_t)t * OPTB + h * OPB;
; #pragma unroll
;         for (int ct = 0; ct < 4; ++ct) {
;             const int crow = h * 64 + ct * 16 + qi;
;             f32x4 aw = {0.f, 0.f, 0.f, 0.f}, aa = aw, ag = aw;
; #pragma unroll
;             for (int ks = 0; ks < 2; ++ks) {
;                 aw = __builtin_amdgcn_mfma_f32_16x16x32_bf16(*(const bf16x8*)(decT + crow * 64 + ks * 32 + quad * 8), fw[ks], aw, 0, 0, 0);
;                 aa = __builtin_amdgcn_mfma_f32_16x16x32_bf16(*(const bf16x8*)(aT + crow * 64 + ks * 32 + quad * 8), fa[ks], aa, 0, 0, 0);
;             }
; #pragma unroll
;             for (int ks = 0; ks < 4; ++ks) ag = __builtin_amdgcn_mfma_f32_16x16x32_bf16(*(const bf16x8*)(gT + crow * 128 + ks * 32 + quad * 8), fg[ks], ag, 0, 0, 0);
;             const int c = h * 64 + ct * 16 + quad * 4;
;             const f32x4 mr = *(const f32x4*)(mu + c), mk = *(const f32x4*)(mu + COL_K + c), mv = *(const f32x4*)(mu + COL_V + c);
;             const f32x4 cr = ld_bf4(pt + c), ck = ld_bf4(pt + COL_K + c), cv = ld_bf4(pt + COL_V + c);
;             const f32x4 qr = ld_bf4(pp + c) * pm, qk = ld_bf4(pp + COL_K + c) * pm, qv = ld_bf4(pp + COL_V + c) * pm;
;             const f32x4 r = cr + (qr - cr) * mr, k = ck + (qk - ck) * mk, v = cv + (qv - cv) * mv;
.LBB0_345:
	s_or_b64 exec, exec, s[0:1]
	s_add_i32 s0, s56, 1
	s_mul_i32 s10, s0, 0x380
	v_lshl_add_u64 v[120:121], v[118:119], 0, s[10:11]
	s_lshl_b32 s10, s0, 6
	v_or_b32_e32 v40, s10, v180
	s_waitcnt lgkmcnt(0)
	v_lshlrev_b32_e32 v36, 7, v40
	v_mov_b32_e32 v37, v3
	v_lshl_add_u64 v[38:39], v[88:89], 0, v[36:37]
	v_lshl_add_u64 v[36:37], v[92:93], 0, v[36:37]
	global_load_dwordx4 v[52:55], v[38:39], off
	global_load_dwordx4 v[56:59], v[36:37], off
	global_load_dwordx4 v[60:63], v[38:39], off offset:64
	global_load_dwordx4 v[68:71], v[36:37], off offset:64
	v_or_b32_e32 v72, s10, v181
	v_lshlrev_b32_e32 v36, 8, v40
	v_mov_b32_e32 v37, v3
	v_lshlrev_b32_e32 v140, 1, v72
	v_mov_b32_e32 v141, v3
	v_lshl_add_u64 v[36:37], v[94:95], 0, v[36:37]
	v_lshlrev_b32_e32 v184, 2, v72
	v_lshl_add_u64 v[134:135], v[114:115], 0, v[140:141]
	global_load_dwordx4 v[48:51], v[36:37], off
	global_load_dwordx4 v[44:47], v[36:37], off offset:64
	global_load_dwordx4 v[40:43], v[36:37], off offset:128
	s_nop 0
	global_load_dwordx4 v[36:39], v[36:37], off offset:192
	v_lshl_add_u64 v[132:133], v[110:111], 0, v[140:141]
	v_mov_b32_e32 v1, v0
	v_mov_b32_e32 v100, v0
	v_mov_b32_e32 v101, v0
	s_mov_b32 s57, 0xbfb8aa3b
	s_mov_b32 s58, 0x3f317217
	s_mov_b32 s59, 0x7f800000
	v_lshl_add_u64 v[140:141], v[116:117], 0, v[140:141]
	s_waitcnt vmcnt(7)
	v_mfma_f32_16x16x32_bf16 v[52:55], v[52:55], v[20:23], 0
	s_waitcnt vmcnt(6)
	v_mfma_f32_16x16x32_bf16 v[56:59], v[56:59], v[28:31], 0
	s_waitcnt vmcnt(5)
	v_mfma_f32_16x16x32_bf16 v[64:67], v[60:63], v[24:27], v[52:55]
	s_waitcnt vmcnt(4)
	v_mfma_f32_16x16x32_bf16 v[56:59], v[68:71], v[32:35], v[56:59]
	global_load_dwordx4 v[68:71], v184, s[8:9]
	global_load_dwordx4 v[60:63], v184, s[8:9] offset:3072
	global_load_dwordx4 v[52:55], v184, s[52:53]
	global_load_dwordx2 v[72:73], v[134:135], off
	global_load_dwordx2 v[126:127], v[134:135], off offset:1536
	global_load_dwordx2 v[76:77], v[134:135], off offset:3072
	s_waitcnt vmcnt(9)
	v_mfma_f32_16x16x32_bf16 v[48:51], v[48:51], v[4:7], 0
	global_load_dwordx2 v[80:81], v[132:133], off offset:1536
	s_waitcnt vmcnt(3)
	v_lshlrev_b32_e32 v74, 16, v72
	s_waitcnt vmcnt(1)
	v_lshlrev_b32_e32 v130, 16, v76
	v_and_b32_e32 v131, 0xffff0000, v76
	v_lshlrev_b32_e32 v142, 16, v77
	v_and_b32_e32 v143, 0xffff0000, v77
	global_load_dwordx2 v[76:77], v[132:133], off
	v_and_b32_e32 v75, 0xffff0000, v72
	v_xor_b32_e32 v85, 0x80000000, v75
	v_xor_b32_e32 v84, 0x80000000, v74
	v_lshlrev_b32_e32 v72, 16, v73
	v_and_b32_e32 v73, 0xffff0000, v73
	v_mfma_f32_16x16x32_bf16 v[44:47], v[44:47], v[8:11], v[48:51]
	s_waitcnt vmcnt(1)
	v_lshlrev_b32_e32 v128, 16, v80
	v_and_b32_e32 v129, 0xffff0000, v80
	v_lshlrev_b32_e32 v136, 16, v81
	v_and_b32_e32 v137, 0xffff0000, v81
	global_load_dwordx2 v[80:81], v[132:133], off offset:3072
	v_mfma_f32_16x16x32_bf16 v[40:43], v[40:43], v[12:15], v[44:47]
	s_waitcnt vmcnt(1)
	v_lshlrev_b32_e32 v78, 16, v76
	v_and_b32_e32 v79, 0xffff0000, v76
	v_pk_fma_f32 v[78:79], v[0:1], v[78:79], v[84:85]
	v_lshlrev_b32_e32 v76, 16, v77
	v_and_b32_e32 v77, 0xffff0000, v77
	v_xor_b32_e32 v85, 0x80000000, v73
	v_xor_b32_e32 v84, 0x80000000, v72
	v_pk_fma_f32 v[146:147], v[68:69], v[78:79], v[74:75]
	v_xor_b32_e32 v69, 0x80000000, v131
	v_xor_b32_e32 v68, 0x80000000, v130
	v_pk_fma_f32 v[76:77], v[100:101], v[76:77], v[84:85]
	v_mfma_f32_16x16x32_bf16 v[36:39], v[36:39], v[16:19], v[40:43]
	v_fma_f32 v144, v70, v76, v72
	v_fma_f32 v145, v71, v77, v73
	v_lshl_add_u64 v[44:45], v[120:121], 0, v[112:113]
	s_waitcnt vmcnt(0)
	v_lshlrev_b32_e32 v82, 16, v80
	v_and_b32_e32 v83, 0xffff0000, v80
	v_lshlrev_b32_e32 v80, 16, v81
	v_and_b32_e32 v81, 0xffff0000, v81
	v_cvt_pk_bf16_f32 v36, v36, v37
	v_cvt_pk_bf16_f32 v37, v38, v39
	v_pk_fma_f32 v[148:149], v[0:1], v[82:83], v[68:69]
	v_xor_b32_e32 v69, 0x80000000, v143
	v_xor_b32_e32 v68, 0x80000000, v142
	v_pk_fma_f32 v[150:151], v[100:101], v[80:81], v[68:69]
	global_load_dwordx4 v[84:87], v184, s[42:43]
	global_load_dwordx4 v[80:83], v184, s[44:45]
	global_load_dwordx4 v[68:71], v184, s[46:47]
	global_load_dwordx4 v[76:79], v184, s[48:49]
	global_load_dwordx4 v[72:75], v184, s[50:51]
	v_pk_fma_f32 v[42:43], v[52:53], v[148:149], v[130:131]
	v_lshl_add_u64 v[130:131], v[120:121], 0, v[2:3]
	v_pk_fma_f32 v[40:41], v[54:55], v[150:151], v[142:143]
	v_cvt_pk_bf16_f32 v42, v42, v43
	v_cvt_pk_bf16_f32 v43, v40, v41
	v_cvt_pk_bf16_f32 v40, v146, v147
	v_cvt_pk_bf16_f32 v41, v144, v145
	v_sub_u32_e32 v233, v130, v231
	ds_write_b64 v233, v[42:43] offset:640
	v_sub_u32_e32 v233, v130, v231
	ds_write_b64 v233, v[40:41] offset:768
	s_waitcnt vmcnt(4)
	v_add_f32_e32 v64, v64, v84
	v_max_f32_e64 v84, -v64, 0
	v_mul_f32_e64 v64, |v64|, s57
	s_waitcnt vmcnt(3)
; __device__ __forceinline__ void rwkv_prep_item(const Params& p, const Lt& lt, int l, int item) {
;     ...
;         for (int ct = 0; ct < 4; ++ct) {
;             const int crow = h * 64 + ct * 16 + qi;
;             f32x4 aw = {0.f, 0.f, 0.f, 0.f}, aa = aw, ag = aw;
; #pragma unroll
;             for (int ks = 0; ks < 2; ++ks) {
;                 aw = __builtin_amdgcn_mfma_f32_16x16x32_bf16(*(const bf16x8*)(decT + crow * 64 + ks * 32 + quad * 8), fw[ks], aw, 0, 0, 0);
;                 aa = __builtin_amdgcn_mfma_f32_16x16x32_bf16(*(const bf16x8*)(aT + crow * 64 + ks * 32 + quad * 8), fa[ks], aa, 0, 0, 0);
;             }
; #pragma unroll
;             for (int ks = 0; ks < 4; ++ks) ag = __builtin_amdgcn_mfma_f32_16x16x32_bf16(*(const bf16x8*)(gT + crow * 128 + ks * 32 + quad * 8), fg[ks], ag, 0, 0, 0);
;             const int c = h * 64 + ct * 16 + quad * 4;
;             const f32x4 mr = *(const f32x4*)(mu + c), mk = *(const f32x4*)(mu + COL_K + c), mv = *(const f32x4*)(mu + COL_V + c);
;             const f32x4 cr = ld_bf4(pt + c), ck = ld_bf4(pt + COL_K + c), cv = ld_bf4(pt + COL_V + c);
;             const f32x4 qr = ld_bf4(pp + c) * pm, qk = ld_bf4(pp + COL_K + c) * pm, qv = ld_bf4(pp + COL_V + c) * pm;
;             const f32x4 r = cr + (qr - cr) * mr, k = ck + (qk - ck) * mk, v = cv + (qv - cv) * mv;
;             const f32x4 w0v = *(const f32x4*)(w0 + c), a0v = *(const f32x4*)(a0 + c), kkv = *(const f32x4*)(kkp + c), kav = *(const f32x4*)(kap + c), rkv = *(const f32x4*)(rkp + c);
;             f32x4 dec, a, kk, k2;
; #pragma unroll
;             for (int j = 0; j < 4; ++j) {
;                 const float z = -(w0v[j] + aw[j]);
;                 const float sp = fmaxf(z, 0.f) + __logf(1.0f + __expf(-fabsf(z)));
;                 dec[j] = __expf(-__expf(-sp - 0.5f));
;                 a[j] = sigmoidf_(a0v[j] + aa[j]);
;                 kk[j] = k[j] * kkv[j];
;                 nrm += kk[j] * kk[j];
;                 k2[j] = k[j] * (1.0f + (a[j] - 1.0f) * kav[j]);
;                 bon += r[j] * k2[j] * rkv[j];
;             }
;             va[ct] = a; vkk[ct] = kk;
;             { const int cc = ct * 16 + quad * 4; *(f32x4*)(ob + cc * 4) = dec; st_bf4(ob + 512 + cc * 2, k2); st_bf4(ob + 640 + cc * 2, v); st_bf4(ob + 768 + cc * 2, r); }
;             st_bf4((unsigned char*)((bf16_t*)gate + (size_t)t * RW + c), ag);
;         }
	v_add_f32_e32 v56, v56, v80
	v_exp_f32_e32 v64, v64
	v_mul_f32_e32 v56, 0xbfb8aa3b, v56
	v_exp_f32_e32 v56, v56
	v_add_f32_e32 v64, 1.0, v64
	v_cmp_gt_f32_e64 s[0:1], s75, v64
	v_add_f32_e32 v56, 1.0, v56
	s_nop 0
	v_cndmask_b32_e64 v122, 0, 32, s[0:1]
	v_ldexp_f32 v64, v64, v122
	v_log_f32_e32 v64, v64
	s_nop 0
	v_mul_f32_e32 v122, 0x3f317217, v64
	v_cmp_lt_f32_e64 s[4:5], |v64|, s59
	v_fma_f32 v122, v64, s58, -v122
	v_fmac_f32_e32 v122, 0x3377d1cf, v64
	v_fmac_f32_e32 v122, 0x3f317217, v64
	v_cndmask_b32_e64 v64, v64, v122, s[4:5]
	v_cndmask_b32_e64 v122, 0, v243, s[0:1]
	v_sub_f32_e32 v64, v64, v122
	v_rcp_f32_e32 v122, v56
	v_add_f32_e32 v56, v65, v85
	v_max_f32_e64 v65, -v56, 0
	v_mul_f32_e64 v56, |v56|, s57
	v_add_f32_e32 v64, v84, v64
	v_exp_f32_e32 v56, v56
	v_sub_f32_e32 v64, -0.5, v64
	v_mul_f32_e32 v64, 0x3fb8aa3b, v64
	v_exp_f32_e32 v64, v64
	v_add_f32_e32 v56, 1.0, v56
	v_cmp_gt_f32_e64 s[0:1], s75, v56
	v_mul_f32_e32 v64, 0xbfb8aa3b, v64
	s_nop 0
	v_cndmask_b32_e64 v80, 0, 32, s[0:1]
	v_ldexp_f32 v56, v56, v80
	v_exp_f32_e32 v64, v64
	v_log_f32_e32 v56, v56
	s_nop 0
	v_mul_f32_e32 v80, 0x3f317217, v56
	v_cmp_lt_f32_e64 s[4:5], |v56|, s59
	v_fma_f32 v80, v56, s58, -v80
	v_fmac_f32_e32 v80, 0x3377d1cf, v56
	v_fmac_f32_e32 v80, 0x3f317217, v56
	v_cndmask_b32_e64 v56, v56, v80, s[4:5]
	v_cndmask_b32_e64 v80, 0, v243, s[0:1]
	v_sub_f32_e32 v56, v56, v80
	v_add_f32_e32 v56, v65, v56
	v_sub_f32_e32 v56, -0.5, v56
	v_mul_f32_e32 v56, 0x3fb8aa3b, v56
	v_exp_f32_e32 v56, v56
	s_nop 0
	v_mul_f32_e32 v56, 0xbfb8aa3b, v56
	v_exp_f32_e32 v65, v56
	v_add_f32_e32 v56, v57, v81
	v_mul_f32_e32 v56, 0xbfb8aa3b, v56
	v_exp_f32_e32 v56, v56
	s_nop 0
	v_add_f32_e32 v56, 1.0, v56
	v_rcp_f32_e32 v123, v56
	v_add_f32_e32 v56, v66, v86
	v_max_f32_e64 v57, -v56, 0
	v_mul_f32_e64 v56, |v56|, s57
	v_exp_f32_e32 v56, v56
	s_nop 0
	v_add_f32_e32 v56, 1.0, v56
	v_cmp_gt_f32_e64 s[0:1], s75, v56
	s_nop 1
	v_cndmask_b32_e64 v66, 0, 32, s[0:1]
	v_ldexp_f32 v56, v56, v66
	v_log_f32_e32 v56, v56
	s_nop 0
	v_mul_f32_e32 v66, 0x3f317217, v56
	v_cmp_lt_f32_e64 s[4:5], |v56|, s59
	v_fma_f32 v66, v56, s58, -v66
	v_fmac_f32_e32 v66, 0x3377d1cf, v56
	v_fmac_f32_e32 v66, 0x3f317217, v56
	v_cndmask_b32_e64 v56, v56, v66, s[4:5]
	v_cndmask_b32_e64 v66, 0, v243, s[0:1]
	v_sub_f32_e32 v56, v56, v66
	v_add_f32_e32 v56, v57, v56
	v_sub_f32_e32 v56, -0.5, v56
	v_mul_f32_e32 v56, 0x3fb8aa3b, v56
	v_exp_f32_e32 v56, v56
	s_nop 0
	v_mul_f32_e32 v56, 0xbfb8aa3b, v56
	v_exp_f32_e32 v66, v56
	v_add_f32_e32 v56, v58, v82
	v_mul_f32_e32 v56, 0xbfb8aa3b, v56
	v_exp_f32_e32 v56, v56
	s_nop 0
	v_add_f32_e32 v56, 1.0, v56
	v_rcp_f32_e32 v124, v56
	v_add_f32_e32 v56, v67, v87
	v_max_f32_e64 v57, -v56, 0
	v_mul_f32_e64 v56, |v56|, s57
	v_exp_f32_e32 v56, v56
	s_nop 0
	v_add_f32_e32 v56, 1.0, v56
	v_cmp_gt_f32_e64 s[0:1], s75, v56
	s_nop 1
	v_cndmask_b32_e64 v58, 0, 32, s[0:1]
	v_ldexp_f32 v56, v56, v58
	v_log_f32_e32 v56, v56
	s_nop 0
	v_mul_f32_e32 v58, 0x3f317217, v56
	v_cmp_lt_f32_e64 s[4:5], |v56|, s59
	v_fma_f32 v58, v56, s58, -v58
	v_fmac_f32_e32 v58, 0x3377d1cf, v56
	v_fmac_f32_e32 v58, 0x3f317217, v56
	v_cndmask_b32_e64 v56, v56, v58, s[4:5]
	v_cndmask_b32_e64 v58, 0, v243, s[0:1]
	s_or_b32 s0, s10, 16
	v_sub_f32_e32 v56, v56, v58
	v_lshlrev_b32_e32 v58, 16, v126
	v_add_f32_e32 v56, v57, v56
	v_xor_b32_e32 v82, 0x80000000, v58
	v_and_b32_e32 v57, 0xffff0000, v127
	v_sub_f32_e32 v56, -0.5, v56
	v_xor_b32_e32 v81, 0x80000000, v57
	v_mul_f32_e32 v56, 0x3fb8aa3b, v56
	v_exp_f32_e32 v56, v56
	s_nop 0
	v_mul_f32_e32 v56, 0xbfb8aa3b, v56
	v_exp_f32_e32 v67, v56
	v_add_f32_e32 v56, v59, v83
	v_and_b32_e32 v59, 0xffff0000, v126
	v_mul_f32_e32 v56, 0xbfb8aa3b, v56
	v_xor_b32_e32 v83, 0x80000000, v59
	v_exp_f32_e32 v56, v56
	v_pk_fma_f32 v[82:83], v[0:1], v[128:129], v[82:83]
	v_sub_u32_e32 v233, v44, v231
	ds_write_b128 v233, v[64:67]
	v_pk_fma_f32 v[58:59], v[60:61], v[82:83], v[58:59]
	v_pk_add_f32 v[60:61], v[122:123], -1.0 op_sel_hi:[1,0]
	v_add_f32_e32 v56, 1.0, v56
	s_waitcnt vmcnt(1)
	v_pk_fma_f32 v[60:61], v[76:77], v[60:61], 1.0 op_sel_hi:[1,1,0]
	v_rcp_f32_e32 v125, v56
	v_lshlrev_b32_e32 v56, 16, v127
	v_pk_mul_f32 v[126:127], v[68:69], v[58:59]
	v_pk_mul_f32 v[58:59], v[58:59], v[60:61]
	v_xor_b32_e32 v80, 0x80000000, v56
	v_mul_f32_e32 v60, v146, v58
	s_waitcnt vmcnt(0)
	v_fma_f32 v185, v72, v60, 0
	v_mul_f32_e32 v60, v147, v59
	v_pk_fma_f32 v[80:81], v[100:101], v[136:137], v[80:81]
	v_fmac_f32_e32 v185, v73, v60
	v_pk_add_f32 v[60:61], v[124:125], -1.0 op_sel_hi:[1,0]
	v_pk_fma_f32 v[56:57], v[62:63], v[80:81], v[56:57]
	v_pk_fma_f32 v[60:61], v[78:79], v[60:61], 1.0 op_sel_hi:[1,1,0]
	v_cvt_pk_bf16_f32 v44, v58, v59
	v_pk_mul_f32 v[60:61], v[56:57], v[60:61]
	v_pk_mul_f32 v[128:129], v[70:71], v[56:57]
	v_cvt_pk_bf16_f32 v45, v60, v61
	v_sub_u32_e32 v233, v130, v231
	ds_write_b64 v233, v[44:45] offset:512
	v_or_b32_e32 v44, s0, v180
	v_mul_f32_e32 v62, v144, v60
	global_store_dwordx2 v[140:141], v[36:37], off
	v_lshlrev_b32_e32 v36, 7, v44
	v_mov_b32_e32 v37, v3
	v_fmac_f32_e32 v185, v74, v62
	v_mul_f32_e32 v56, v145, v61
	v_lshl_add_u64 v[38:39], v[88:89], 0, v[36:37]
	v_fmac_f32_e32 v185, v75, v56
	v_lshl_add_u64 v[36:37], v[92:93], 0, v[36:37]
	global_load_dwordx4 v[210:213], v184, s[8:9] offset:64
	global_load_dwordx4 v[214:217], v184, s[8:9] offset:3136
	global_load_dwordx4 v[218:221], v184, s[52:53] offset:64
	global_load_dwordx2 v[236:237], v[134:135], off offset:32
	global_load_dwordx2 v[194:195], v[134:135], off offset:1568
	global_load_dwordx2 v[198:199], v[134:135], off offset:3104
	global_load_dwordx2 v[206:207], v[132:133], off offset:1568
	global_load_dwordx2 v[248:249], v[132:133], off offset:32
	global_load_dwordx4 v[222:225], v184, s[42:43] offset:64
	global_load_dwordx4 v[40:43], v[38:39], off
	global_load_dwordx4 v[56:59], v[36:37], off
	global_load_dwordx4 v[60:63], v[38:39], off offset:64
	global_load_dwordx4 v[68:71], v[36:37], off offset:64
	v_lshlrev_b32_e32 v36, 8, v44
	v_mov_b32_e32 v37, v3
	v_lshl_add_u64 v[36:37], v[94:95], 0, v[36:37]
	global_load_dwordx4 v[52:55], v[36:37], off
	global_load_dwordx4 v[48:51], v[36:37], off offset:64
	global_load_dwordx4 v[44:47], v[36:37], off offset:128
	s_nop 0
	global_load_dwordx4 v[36:39], v[36:37], off offset:192
	v_pk_mul_f32 v[136:137], v[126:127], v[126:127]
	v_pk_mul_f32 v[138:139], v[128:129], v[128:129]
	s_waitcnt vmcnt(7)
; __device__ __forceinline__ void rwkv_prep_item(const Params& p, const Lt& lt, int l, int item) {
;     ...
;         for (int ct = 0; ct < 4; ++ct) {
;             const int crow = h * 64 + ct * 16 + qi;
;             f32x4 aw = {0.f, 0.f, 0.f, 0.f}, aa = aw, ag = aw;
; #pragma unroll
;             for (int ks = 0; ks < 2; ++ks) {
;                 aw = __builtin_amdgcn_mfma_f32_16x16x32_bf16(*(const bf16x8*)(decT + crow * 64 + ks * 32 + quad * 8), fw[ks], aw, 0, 0, 0);
;                 aa = __builtin_amdgcn_mfma_f32_16x16x32_bf16(*(const bf16x8*)(aT + crow * 64 + ks * 32 + quad * 8), fa[ks], aa, 0, 0, 0);
;             }
; #pragma unroll
;             for (int ks = 0; ks < 4; ++ks) ag = __builtin_amdgcn_mfma_f32_16x16x32_bf16(*(const bf16x8*)(gT + crow * 128 + ks * 32 + quad * 8), fg[ks], ag, 0, 0, 0);
;             const int c = h * 64 + ct * 16 + quad * 4;
;             const f32x4 mr = *(const f32x4*)(mu + c), mk = *(const f32x4*)(mu + COL_K + c), mv = *(const f32x4*)(mu + COL_V + c);
;             const f32x4 cr = ld_bf4(pt + c), ck = ld_bf4(pt + COL_K + c), cv = ld_bf4(pt + COL_V + c);
;             const f32x4 qr = ld_bf4(pp + c) * pm, qk = ld_bf4(pp + COL_K + c) * pm, qv = ld_bf4(pp + COL_V + c) * pm;
;             const f32x4 r = cr + (qr - cr) * mr, k = ck + (qk - ck) * mk, v = cv + (qv - cv) * mv;
;             const f32x4 w0v = *(const f32x4*)(w0 + c), a0v = *(const f32x4*)(a0 + c), kkv = *(const f32x4*)(kkp + c), kav = *(const f32x4*)(kap + c), rkv = *(const f32x4*)(rkp + c);
;             f32x4 dec, a, kk, k2;
; #pragma unroll
;             for (int j = 0; j < 4; ++j) {
;                 const float z = -(w0v[j] + aw[j]);
;                 const float sp = fmaxf(z, 0.f) + __logf(1.0f + __expf(-fabsf(z)));
;                 dec[j] = __expf(-__expf(-sp - 0.5f));
;                 a[j] = sigmoidf_(a0v[j] + aa[j]);
;                 kk[j] = k[j] * kkv[j];
;                 nrm += kk[j] * kk[j];
;                 k2[j] = k[j] * (1.0f + (a[j] - 1.0f) * kav[j]);
;                 bon += r[j] * k2[j] * rkv[j];
;             }
;             va[ct] = a; vkk[ct] = kk;
;             { const int cc = ct * 16 + quad * 4; *(f32x4*)(ob + cc * 4) = dec; st_bf4(ob + 512 + cc * 2, k2); st_bf4(ob + 640 + cc * 2, v); st_bf4(ob + 768 + cc * 2, r); }
;             st_bf4((unsigned char*)((bf16_t*)gate + (size_t)t * RW + c), ag);
;         }
	v_mfma_f32_16x16x32_bf16 v[40:43], v[40:43], v[20:23], 0
	s_waitcnt vmcnt(6)
	v_mfma_f32_16x16x32_bf16 v[56:59], v[56:59], v[28:31], 0
	s_waitcnt vmcnt(5)
	v_mfma_f32_16x16x32_bf16 v[64:67], v[60:63], v[24:27], v[40:43]
	s_nop 3
	v_or_b32_e32 v40, s0, v181
	v_lshlrev_b32_e32 v40, 2, v40
	s_waitcnt vmcnt(4)
	v_mfma_f32_16x16x32_bf16 v[60:63], v[68:71], v[32:35], v[56:59]
	s_waitcnt vmcnt(16)
	v_mov_b64_e32 v[68:69], v[210:211]
	v_mov_b64_e32 v[70:71], v[212:213]
	s_nop 1
	s_waitcnt vmcnt(15)
	v_mov_b64_e32 v[56:57], v[214:215]
	v_mov_b64_e32 v[58:59], v[216:217]
	s_nop 0
	s_waitcnt vmcnt(14)
	v_mov_b64_e32 v[40:41], v[218:219]
	v_mov_b64_e32 v[42:43], v[220:221]
	s_nop 0
	s_waitcnt vmcnt(13)
	v_mov_b64_e32 v[72:73], v[236:237]
	s_waitcnt vmcnt(12)
	v_mov_b64_e32 v[146:147], v[194:195]
	s_waitcnt vmcnt(11)
	v_mov_b64_e32 v[76:77], v[198:199]
	s_waitcnt vmcnt(3)
	v_mfma_f32_16x16x32_bf16 v[52:55], v[52:55], v[4:7], 0
	s_waitcnt vmcnt(10)
	v_mov_b64_e32 v[80:81], v[206:207]
	s_waitcnt vmcnt(0)
	v_lshlrev_b32_e32 v74, 16, v72
	s_waitcnt vmcnt(0)
	v_lshlrev_b32_e32 v154, 16, v76
	v_and_b32_e32 v155, 0xffff0000, v76
	v_lshlrev_b32_e32 v156, 16, v77
	v_and_b32_e32 v157, 0xffff0000, v77
	s_waitcnt vmcnt(9)
	v_mov_b64_e32 v[76:77], v[248:249]
	v_and_b32_e32 v75, 0xffff0000, v72
	v_xor_b32_e32 v85, 0x80000000, v75
	v_xor_b32_e32 v84, 0x80000000, v74
	v_lshlrev_b32_e32 v72, 16, v73
	v_and_b32_e32 v73, 0xffff0000, v73
	v_mfma_f32_16x16x32_bf16 v[48:51], v[48:51], v[8:11], v[52:55]
	s_waitcnt vmcnt(0)
	v_lshlrev_b32_e32 v148, 16, v80
	v_and_b32_e32 v149, 0xffff0000, v80
	v_lshlrev_b32_e32 v150, 16, v81
	v_and_b32_e32 v151, 0xffff0000, v81
	global_load_dwordx2 v[80:81], v[132:133], off offset:3104
	v_mfma_f32_16x16x32_bf16 v[44:47], v[44:47], v[12:15], v[48:51]
	s_waitcnt vmcnt(1)
	v_lshlrev_b32_e32 v78, 16, v76
	v_and_b32_e32 v79, 0xffff0000, v76
	v_pk_fma_f32 v[78:79], v[0:1], v[78:79], v[84:85]
	v_lshlrev_b32_e32 v76, 16, v77
	v_and_b32_e32 v77, 0xffff0000, v77
	v_xor_b32_e32 v85, 0x80000000, v73
	v_xor_b32_e32 v84, 0x80000000, v72
	v_pk_fma_f32 v[160:161], v[68:69], v[78:79], v[74:75]
	v_xor_b32_e32 v69, 0x80000000, v155
	v_xor_b32_e32 v68, 0x80000000, v154
	v_pk_fma_f32 v[76:77], v[100:101], v[76:77], v[84:85]
	v_mfma_f32_16x16x32_bf16 v[36:39], v[36:39], v[16:19], v[44:47]
	v_fma_f32 v158, v70, v76, v72
	v_fma_f32 v159, v71, v77, v73
	s_waitcnt vmcnt(0)
	v_lshlrev_b32_e32 v82, 16, v80
	v_and_b32_e32 v83, 0xffff0000, v80
	v_lshlrev_b32_e32 v80, 16, v81
	v_and_b32_e32 v81, 0xffff0000, v81
	v_lshl_add_u64 v[44:45], v[120:121], 0, v[106:107]
	v_cvt_pk_bf16_f32 v36, v36, v37
	v_cvt_pk_bf16_f32 v37, v38, v39
	v_pk_fma_f32 v[162:163], v[0:1], v[82:83], v[68:69]
	v_xor_b32_e32 v69, 0x80000000, v157
	v_xor_b32_e32 v68, 0x80000000, v156
	v_pk_fma_f32 v[164:165], v[100:101], v[80:81], v[68:69]
	s_waitcnt vmcnt(9)
	v_mov_b64_e32 v[84:85], v[222:223]
	v_mov_b64_e32 v[86:87], v[224:225]
	global_load_dwordx4 v[80:83], v184, s[44:45] offset:64
	global_load_dwordx4 v[72:75], v184, s[46:47] offset:64
	global_load_dwordx4 v[76:79], v184, s[48:49] offset:64
	global_load_dwordx4 v[68:71], v184, s[50:51] offset:64
	v_pk_fma_f32 v[40:41], v[40:41], v[162:163], v[154:155]
	v_pk_fma_f32 v[42:43], v[42:43], v[164:165], v[156:157]
	v_cvt_pk_bf16_f32 v40, v40, v41
	v_cvt_pk_bf16_f32 v41, v42, v43
	s_waitcnt vmcnt(4)
	v_add_f32_e32 v64, v64, v84
	v_max_f32_e64 v84, -v64, 0
	v_mul_f32_e64 v64, |v64|, s57
	s_waitcnt vmcnt(3)
	v_add_f32_e32 v60, v60, v80
	v_exp_f32_e32 v64, v64
	v_mul_f32_e32 v60, 0xbfb8aa3b, v60
	v_exp_f32_e32 v60, v60
	v_add_f32_e32 v64, 1.0, v64
	v_cmp_gt_f32_e64 s[0:1], s75, v64
	v_add_f32_e32 v60, 1.0, v60
	s_nop 0
	v_cndmask_b32_e64 v142, 0, 32, s[0:1]
	v_ldexp_f32 v64, v64, v142
	v_log_f32_e32 v64, v64
	s_nop 0
	v_mul_f32_e32 v142, 0x3f317217, v64
	v_cmp_lt_f32_e64 s[4:5], |v64|, s59
	v_fma_f32 v142, v64, s58, -v142
	v_fmac_f32_e32 v142, 0x3377d1cf, v64
	v_fmac_f32_e32 v142, 0x3f317217, v64
	v_cndmask_b32_e64 v64, v64, v142, s[4:5]
	v_cndmask_b32_e64 v142, 0, v243, s[0:1]
	v_sub_f32_e32 v64, v64, v142
	v_rcp_f32_e32 v142, v60
	v_add_f32_e32 v60, v65, v85
	v_max_f32_e64 v65, -v60, 0
	v_mul_f32_e64 v60, |v60|, s57
	v_add_f32_e32 v64, v84, v64
	v_exp_f32_e32 v60, v60
	v_sub_f32_e32 v64, -0.5, v64
	v_mul_f32_e32 v64, 0x3fb8aa3b, v64
	v_exp_f32_e32 v64, v64
	v_add_f32_e32 v60, 1.0, v60
	v_cmp_gt_f32_e64 s[0:1], s75, v60
	v_mul_f32_e32 v64, 0xbfb8aa3b, v64
	s_nop 0
	v_cndmask_b32_e64 v80, 0, 32, s[0:1]
	v_ldexp_f32 v60, v60, v80
	v_exp_f32_e32 v64, v64
	v_log_f32_e32 v60, v60
	s_nop 0
	v_mul_f32_e32 v80, 0x3f317217, v60
	v_cmp_lt_f32_e64 s[4:5], |v60|, s59
	v_fma_f32 v80, v60, s58, -v80
	v_fmac_f32_e32 v80, 0x3377d1cf, v60
	v_fmac_f32_e32 v80, 0x3f317217, v60
	v_cndmask_b32_e64 v60, v60, v80, s[4:5]
	v_cndmask_b32_e64 v80, 0, v243, s[0:1]
	v_sub_f32_e32 v60, v60, v80
	v_add_f32_e32 v60, v65, v60
	v_sub_f32_e32 v60, -0.5, v60
	v_mul_f32_e32 v60, 0x3fb8aa3b, v60
	v_exp_f32_e32 v60, v60
	s_nop 0
	v_mul_f32_e32 v60, 0xbfb8aa3b, v60
	v_exp_f32_e32 v65, v60
	v_add_f32_e32 v60, v61, v81
	v_mul_f32_e32 v60, 0xbfb8aa3b, v60
	v_exp_f32_e32 v60, v60
	s_nop 0
	v_add_f32_e32 v60, 1.0, v60
	v_rcp_f32_e32 v143, v60
	v_add_f32_e32 v60, v66, v86
	v_max_f32_e64 v61, -v60, 0
	v_mul_f32_e64 v60, |v60|, s57
	v_exp_f32_e32 v60, v60
	s_nop 0
	v_add_f32_e32 v60, 1.0, v60
	v_cmp_gt_f32_e64 s[0:1], s75, v60
	s_nop 1
	v_cndmask_b32_e64 v66, 0, 32, s[0:1]
	v_ldexp_f32 v60, v60, v66
	v_log_f32_e32 v60, v60
	s_nop 0
	v_mul_f32_e32 v66, 0x3f317217, v60
	v_cmp_lt_f32_e64 s[4:5], |v60|, s59
	v_fma_f32 v66, v60, s58, -v66
	v_fmac_f32_e32 v66, 0x3377d1cf, v60
	v_fmac_f32_e32 v66, 0x3f317217, v60
; __device__ __forceinline__ void rwkv_prep_item(const Params& p, const Lt& lt, int l, int item) {
;     ...
;         for (int ct = 0; ct < 4; ++ct) {
;             const int crow = h * 64 + ct * 16 + qi;
;             f32x4 aw = {0.f, 0.f, 0.f, 0.f}, aa = aw, ag = aw;
; #pragma unroll
;             for (int ks = 0; ks < 2; ++ks) {
;                 aw = __builtin_amdgcn_mfma_f32_16x16x32_bf16(*(const bf16x8*)(decT + crow * 64 + ks * 32 + quad * 8), fw[ks], aw, 0, 0, 0);
;                 aa = __builtin_amdgcn_mfma_f32_16x16x32_bf16(*(const bf16x8*)(aT + crow * 64 + ks * 32 + quad * 8), fa[ks], aa, 0, 0, 0);
;             }
; #pragma unroll
;             for (int ks = 0; ks < 4; ++ks) ag = __builtin_amdgcn_mfma_f32_16x16x32_bf16(*(const bf16x8*)(gT + crow * 128 + ks * 32 + quad * 8), fg[ks], ag, 0, 0, 0);
;             const int c = h * 64 + ct * 16 + quad * 4;
;             const f32x4 mr = *(const f32x4*)(mu + c), mk = *(const f32x4*)(mu + COL_K + c), mv = *(const f32x4*)(mu + COL_V + c);
;             const f32x4 cr = ld_bf4(pt + c), ck = ld_bf4(pt + COL_K + c), cv = ld_bf4(pt + COL_V + c);
;             const f32x4 qr = ld_bf4(pp + c) * pm, qk = ld_bf4(pp + COL_K + c) * pm, qv = ld_bf4(pp + COL_V + c) * pm;
;             const f32x4 r = cr + (qr - cr) * mr, k = ck + (qk - ck) * mk, v = cv + (qv - cv) * mv;
;             const f32x4 w0v = *(const f32x4*)(w0 + c), a0v = *(const f32x4*)(a0 + c), kkv = *(const f32x4*)(kkp + c), kav = *(const f32x4*)(kap + c), rkv = *(const f32x4*)(rkp + c);
;             f32x4 dec, a, kk, k2;
; #pragma unroll
;             for (int j = 0; j < 4; ++j) {
;                 const float z = -(w0v[j] + aw[j]);
;                 const float sp = fmaxf(z, 0.f) + __logf(1.0f + __expf(-fabsf(z)));
;                 dec[j] = __expf(-__expf(-sp - 0.5f));
;                 a[j] = sigmoidf_(a0v[j] + aa[j]);
;                 kk[j] = k[j] * kkv[j];
;                 nrm += kk[j] * kk[j];
;                 k2[j] = k[j] * (1.0f + (a[j] - 1.0f) * kav[j]);
;                 bon += r[j] * k2[j] * rkv[j];
;             }
;             va[ct] = a; vkk[ct] = kk;
;             { const int cc = ct * 16 + quad * 4; *(f32x4*)(ob + cc * 4) = dec; st_bf4(ob + 512 + cc * 2, k2); st_bf4(ob + 640 + cc * 2, v); st_bf4(ob + 768 + cc * 2, r); }
;             st_bf4((unsigned char*)((bf16_t*)gate + (size_t)t * RW + c), ag);
;         }
	v_cndmask_b32_e64 v60, v60, v66, s[4:5]
	v_cndmask_b32_e64 v66, 0, v243, s[0:1]
	v_sub_f32_e32 v60, v60, v66
	v_add_f32_e32 v60, v61, v60
	v_sub_f32_e32 v60, -0.5, v60
	v_mul_f32_e32 v60, 0x3fb8aa3b, v60
	v_exp_f32_e32 v60, v60
	s_nop 0
	v_mul_f32_e32 v60, 0xbfb8aa3b, v60
	v_exp_f32_e32 v66, v60
	v_add_f32_e32 v60, v62, v82
	v_mul_f32_e32 v60, 0xbfb8aa3b, v60
	v_exp_f32_e32 v60, v60
	s_nop 0
	v_add_f32_e32 v60, 1.0, v60
	v_rcp_f32_e32 v144, v60
	v_add_f32_e32 v60, v67, v87
	v_max_f32_e64 v61, -v60, 0
	v_mul_f32_e64 v60, |v60|, s57
	v_exp_f32_e32 v60, v60
	s_nop 0
	v_add_f32_e32 v60, 1.0, v60
	v_cmp_gt_f32_e64 s[0:1], s75, v60
	s_nop 1
	v_cndmask_b32_e64 v62, 0, 32, s[0:1]
	v_ldexp_f32 v60, v60, v62
	v_log_f32_e32 v60, v60
	s_nop 0
	v_mul_f32_e32 v62, 0x3f317217, v60
	v_cmp_lt_f32_e64 s[4:5], |v60|, s59
	v_fma_f32 v62, v60, s58, -v62
	v_fmac_f32_e32 v62, 0x3377d1cf, v60
	v_fmac_f32_e32 v62, 0x3f317217, v60
	v_cndmask_b32_e64 v60, v60, v62, s[4:5]
	v_cndmask_b32_e64 v62, 0, v243, s[0:1]
	v_sub_f32_e32 v60, v60, v62
	v_add_f32_e32 v60, v61, v60
	v_sub_f32_e32 v60, -0.5, v60
	v_mul_f32_e32 v60, 0x3fb8aa3b, v60
	v_exp_f32_e32 v60, v60
	v_and_b32_e32 v61, 0xffff0000, v147
	v_lshlrev_b32_e32 v62, 16, v146
	v_xor_b32_e32 v81, 0x80000000, v61
	v_mul_f32_e32 v60, 0xbfb8aa3b, v60
	v_exp_f32_e32 v67, v60
	v_add_f32_e32 v60, v63, v83
	v_mul_f32_e32 v60, 0xbfb8aa3b, v60
	v_exp_f32_e32 v60, v60
	v_and_b32_e32 v63, 0xffff0000, v146
	v_xor_b32_e32 v83, 0x80000000, v63
	v_xor_b32_e32 v82, 0x80000000, v62
	v_add_f32_e32 v60, 1.0, v60
	v_rcp_f32_e32 v145, v60
	v_lshlrev_b32_e32 v60, 16, v147
	v_xor_b32_e32 v80, 0x80000000, v60
	v_pk_fma_f32 v[80:81], v[100:101], v[150:151], v[80:81]
	v_pk_fma_f32 v[82:83], v[0:1], v[148:149], v[82:83]
	v_pk_fma_f32 v[58:59], v[58:59], v[80:81], v[60:61]
	v_pk_fma_f32 v[56:57], v[56:57], v[82:83], v[62:63]
	v_pk_add_f32 v[62:63], v[142:143], -1.0 op_sel_hi:[1,0]
	v_pk_add_f32 v[60:61], v[144:145], -1.0 op_sel_hi:[1,0]
	s_waitcnt vmcnt(1)
	v_pk_fma_f32 v[62:63], v[76:77], v[62:63], 1.0 op_sel_hi:[1,1,0]
	v_pk_fma_f32 v[60:61], v[78:79], v[60:61], 1.0 op_sel_hi:[1,1,0]
	v_pk_mul_f32 v[146:147], v[72:73], v[56:57]
	v_pk_mul_f32 v[56:57], v[56:57], v[62:63]
	v_pk_mul_f32 v[60:61], v[58:59], v[60:61]
	v_sub_u32_e32 v233, v44, v231
	ds_write_b128 v233, v[64:67]
	v_lshl_add_u64 v[44:45], v[120:121], 0, v[108:109]
	v_mul_f32_e32 v62, v160, v56
	v_cvt_pk_bf16_f32 v46, v56, v57
	v_cvt_pk_bf16_f32 v47, v60, v61
	v_sub_u32_e32 v233, v44, v231
	ds_write_b64 v233, v[40:41] offset:640
	v_cvt_pk_bf16_f32 v40, v160, v161
	v_cvt_pk_bf16_f32 v41, v158, v159
	s_or_b32 s0, s10, 32
	s_waitcnt vmcnt(0)
	v_fmac_f32_e32 v185, v68, v62
	v_mul_f32_e32 v62, v161, v57
	v_sub_u32_e32 v233, v44, v231
	ds_write_b64 v233, v[46:47] offset:512
	v_sub_u32_e32 v233, v44, v231
	ds_write_b64 v233, v[40:41] offset:768
	v_or_b32_e32 v44, s0, v180
	v_fmac_f32_e32 v185, v69, v62
	v_mul_f32_e32 v62, v158, v60
	global_store_dwordx2 v[140:141], v[36:37], off offset:32
	v_lshlrev_b32_e32 v36, 7, v44
	v_mov_b32_e32 v37, v3
	v_fmac_f32_e32 v185, v70, v62
	v_pk_mul_f32 v[148:149], v[74:75], v[58:59]
	v_mul_f32_e32 v58, v159, v61
	v_lshl_add_u64 v[38:39], v[88:89], 0, v[36:37]
	v_fmac_f32_e32 v185, v71, v58
	v_lshl_add_u64 v[36:37], v[92:93], 0, v[36:37]
	global_load_dwordx4 v[210:213], v184, s[8:9] offset:128
	global_load_dwordx4 v[214:217], v184, s[8:9] offset:3200
	global_load_dwordx4 v[218:221], v184, s[52:53] offset:128
	global_load_dwordx2 v[236:237], v[134:135], off offset:64
	global_load_dwordx2 v[194:195], v[134:135], off offset:1600
	global_load_dwordx2 v[198:199], v[134:135], off offset:3136
	global_load_dwordx2 v[206:207], v[132:133], off offset:1600
	global_load_dwordx2 v[248:249], v[132:133], off offset:64
	global_load_dwordx4 v[222:225], v184, s[42:43] offset:128
	global_load_dwordx4 v[40:43], v[38:39], off
	global_load_dwordx4 v[56:59], v[36:37], off
	global_load_dwordx4 v[60:63], v[38:39], off offset:64
	global_load_dwordx4 v[68:71], v[36:37], off offset:64
	v_lshlrev_b32_e32 v36, 8, v44
	v_mov_b32_e32 v37, v3
	v_lshl_add_u64 v[36:37], v[94:95], 0, v[36:37]
	global_load_dwordx4 v[52:55], v[36:37], off
	global_load_dwordx4 v[48:51], v[36:37], off offset:64
	global_load_dwordx4 v[44:47], v[36:37], off offset:128
	s_nop 0
	global_load_dwordx4 v[36:39], v[36:37], off offset:192
	v_pk_mul_f32 v[150:151], v[146:147], v[146:147]
	v_pk_mul_f32 v[152:153], v[148:149], v[148:149]
	s_waitcnt vmcnt(7)
	v_mfma_f32_16x16x32_bf16 v[40:43], v[40:43], v[20:23], 0
	s_waitcnt vmcnt(6)
	v_mfma_f32_16x16x32_bf16 v[56:59], v[56:59], v[28:31], 0
	s_waitcnt vmcnt(5)
	v_mfma_f32_16x16x32_bf16 v[64:67], v[60:63], v[24:27], v[40:43]
	s_nop 3
	v_or_b32_e32 v40, s0, v181
	v_lshlrev_b32_e32 v40, 2, v40
	s_waitcnt vmcnt(4)
	v_mfma_f32_16x16x32_bf16 v[60:63], v[68:71], v[32:35], v[56:59]
	s_waitcnt vmcnt(16)
	v_mov_b64_e32 v[68:69], v[210:211]
	v_mov_b64_e32 v[70:71], v[212:213]
	s_nop 1
	s_waitcnt vmcnt(15)
	v_mov_b64_e32 v[56:57], v[214:215]
	v_mov_b64_e32 v[58:59], v[216:217]
	s_nop 0
	s_waitcnt vmcnt(14)
	v_mov_b64_e32 v[40:41], v[218:219]
	v_mov_b64_e32 v[42:43], v[220:221]
	s_nop 0
	s_waitcnt vmcnt(13)
	v_mov_b64_e32 v[72:73], v[236:237]
	s_waitcnt vmcnt(12)
	v_mov_b64_e32 v[158:159], v[194:195]
	s_waitcnt vmcnt(11)
	v_mov_b64_e32 v[76:77], v[198:199]
	s_waitcnt vmcnt(3)
	v_mfma_f32_16x16x32_bf16 v[52:55], v[52:55], v[4:7], 0
	s_waitcnt vmcnt(10)
	v_mov_b64_e32 v[80:81], v[206:207]
	s_waitcnt vmcnt(0)
	v_lshlrev_b32_e32 v74, 16, v72
	s_waitcnt vmcnt(0)
	v_lshlrev_b32_e32 v166, 16, v76
	v_and_b32_e32 v167, 0xffff0000, v76
	v_lshlrev_b32_e32 v168, 16, v77
	v_and_b32_e32 v169, 0xffff0000, v77
	s_waitcnt vmcnt(9)
; __device__ __forceinline__ void rwkv_prep_item(const Params& p, const Lt& lt, int l, int item) {
;     ...
;         for (int ct = 0; ct < 4; ++ct) {
;             const int crow = h * 64 + ct * 16 + qi;
;             f32x4 aw = {0.f, 0.f, 0.f, 0.f}, aa = aw, ag = aw;
; #pragma unroll
;             for (int ks = 0; ks < 2; ++ks) {
;                 aw = __builtin_amdgcn_mfma_f32_16x16x32_bf16(*(const bf16x8*)(decT + crow * 64 + ks * 32 + quad * 8), fw[ks], aw, 0, 0, 0);
;                 aa = __builtin_amdgcn_mfma_f32_16x16x32_bf16(*(const bf16x8*)(aT + crow * 64 + ks * 32 + quad * 8), fa[ks], aa, 0, 0, 0);
;             }
; #pragma unroll
;             for (int ks = 0; ks < 4; ++ks) ag = __builtin_amdgcn_mfma_f32_16x16x32_bf16(*(const bf16x8*)(gT + crow * 128 + ks * 32 + quad * 8), fg[ks], ag, 0, 0, 0);
;             const int c = h * 64 + ct * 16 + quad * 4;
;             const f32x4 mr = *(const f32x4*)(mu + c), mk = *(const f32x4*)(mu + COL_K + c), mv = *(const f32x4*)(mu + COL_V + c);
;             const f32x4 cr = ld_bf4(pt + c), ck = ld_bf4(pt + COL_K + c), cv = ld_bf4(pt + COL_V + c);
;             const f32x4 qr = ld_bf4(pp + c) * pm, qk = ld_bf4(pp + COL_K + c) * pm, qv = ld_bf4(pp + COL_V + c) * pm;
;             const f32x4 r = cr + (qr - cr) * mr, k = ck + (qk - ck) * mk, v = cv + (qv - cv) * mv;
;             const f32x4 w0v = *(const f32x4*)(w0 + c), a0v = *(const f32x4*)(a0 + c), kkv = *(const f32x4*)(kkp + c), kav = *(const f32x4*)(kap + c), rkv = *(const f32x4*)(rkp + c);
;             f32x4 dec, a, kk, k2;
; #pragma unroll
;             for (int j = 0; j < 4; ++j) {
;                 const float z = -(w0v[j] + aw[j]);
;                 const float sp = fmaxf(z, 0.f) + __logf(1.0f + __expf(-fabsf(z)));
;                 dec[j] = __expf(-__expf(-sp - 0.5f));
;                 a[j] = sigmoidf_(a0v[j] + aa[j]);
;                 kk[j] = k[j] * kkv[j];
;                 nrm += kk[j] * kk[j];
;                 k2[j] = k[j] * (1.0f + (a[j] - 1.0f) * kav[j]);
;                 bon += r[j] * k2[j] * rkv[j];
;             }
;             va[ct] = a; vkk[ct] = kk;
;             { const int cc = ct * 16 + quad * 4; *(f32x4*)(ob + cc * 4) = dec; st_bf4(ob + 512 + cc * 2, k2); st_bf4(ob + 640 + cc * 2, v); st_bf4(ob + 768 + cc * 2, r); }
;             st_bf4((unsigned char*)((bf16_t*)gate + (size_t)t * RW + c), ag);
;         }
	v_mov_b64_e32 v[76:77], v[248:249]
	v_and_b32_e32 v75, 0xffff0000, v72
	v_xor_b32_e32 v85, 0x80000000, v75
	v_xor_b32_e32 v84, 0x80000000, v74
	v_lshlrev_b32_e32 v72, 16, v73
	v_and_b32_e32 v73, 0xffff0000, v73
	v_mfma_f32_16x16x32_bf16 v[48:51], v[48:51], v[8:11], v[52:55]
	s_waitcnt vmcnt(0)
	v_lshlrev_b32_e32 v160, 16, v80
	v_and_b32_e32 v161, 0xffff0000, v80
	v_lshlrev_b32_e32 v162, 16, v81
	v_and_b32_e32 v163, 0xffff0000, v81
	global_load_dwordx2 v[80:81], v[132:133], off offset:3136
	v_mfma_f32_16x16x32_bf16 v[44:47], v[44:47], v[12:15], v[48:51]
	s_waitcnt vmcnt(1)
	v_lshlrev_b32_e32 v78, 16, v76
	v_and_b32_e32 v79, 0xffff0000, v76
	v_pk_fma_f32 v[78:79], v[0:1], v[78:79], v[84:85]
	v_lshlrev_b32_e32 v76, 16, v77
	v_and_b32_e32 v77, 0xffff0000, v77
	v_xor_b32_e32 v85, 0x80000000, v73
	v_xor_b32_e32 v84, 0x80000000, v72
	v_pk_fma_f32 v[172:173], v[68:69], v[78:79], v[74:75]
	v_xor_b32_e32 v69, 0x80000000, v167
	v_xor_b32_e32 v68, 0x80000000, v166
	v_pk_fma_f32 v[76:77], v[100:101], v[76:77], v[84:85]
	v_mfma_f32_16x16x32_bf16 v[36:39], v[36:39], v[16:19], v[44:47]
	v_fma_f32 v170, v70, v76, v72
	v_fma_f32 v171, v71, v77, v73
	s_waitcnt vmcnt(0)
	v_lshlrev_b32_e32 v82, 16, v80
	v_and_b32_e32 v83, 0xffff0000, v80
	v_lshlrev_b32_e32 v80, 16, v81
	v_and_b32_e32 v81, 0xffff0000, v81
	v_lshl_add_u64 v[44:45], v[120:121], 0, v[102:103]
	v_cvt_pk_bf16_f32 v36, v36, v37
	v_cvt_pk_bf16_f32 v37, v38, v39
	v_pk_fma_f32 v[174:175], v[0:1], v[82:83], v[68:69]
	v_xor_b32_e32 v69, 0x80000000, v169
	v_xor_b32_e32 v68, 0x80000000, v168
	v_pk_fma_f32 v[176:177], v[100:101], v[80:81], v[68:69]
	s_waitcnt vmcnt(9)
	v_mov_b64_e32 v[84:85], v[222:223]
	v_mov_b64_e32 v[86:87], v[224:225]
	global_load_dwordx4 v[80:83], v184, s[44:45] offset:128
	global_load_dwordx4 v[72:75], v184, s[46:47] offset:128
	global_load_dwordx4 v[76:79], v184, s[48:49] offset:128
	global_load_dwordx4 v[68:71], v184, s[50:51] offset:128
	v_pk_fma_f32 v[40:41], v[40:41], v[174:175], v[166:167]
	v_pk_fma_f32 v[42:43], v[42:43], v[176:177], v[168:169]
	v_cvt_pk_bf16_f32 v40, v40, v41
	v_cvt_pk_bf16_f32 v41, v42, v43
	s_waitcnt vmcnt(4)
	v_add_f32_e32 v64, v64, v84
	v_max_f32_e64 v84, -v64, 0
	v_mul_f32_e64 v64, |v64|, s57
	s_waitcnt vmcnt(3)
	v_add_f32_e32 v60, v60, v80
	v_exp_f32_e32 v64, v64
	v_mul_f32_e32 v60, 0xbfb8aa3b, v60
	v_exp_f32_e32 v60, v60
	v_add_f32_e32 v64, 1.0, v64
	v_cmp_gt_f32_e64 s[0:1], s75, v64
	v_add_f32_e32 v60, 1.0, v60
	s_nop 0
	v_cndmask_b32_e64 v154, 0, 32, s[0:1]
	v_ldexp_f32 v64, v64, v154
	v_log_f32_e32 v64, v64
	s_nop 0
	v_mul_f32_e32 v154, 0x3f317217, v64
	v_cmp_lt_f32_e64 s[4:5], |v64|, s59
	v_fma_f32 v154, v64, s58, -v154
	v_fmac_f32_e32 v154, 0x3377d1cf, v64
	v_fmac_f32_e32 v154, 0x3f317217, v64
	v_cndmask_b32_e64 v64, v64, v154, s[4:5]
	v_cndmask_b32_e64 v154, 0, v243, s[0:1]
	v_sub_f32_e32 v64, v64, v154
	v_rcp_f32_e32 v154, v60
	v_add_f32_e32 v60, v65, v85
	v_max_f32_e64 v65, -v60, 0
	v_mul_f32_e64 v60, |v60|, s57
	v_add_f32_e32 v64, v84, v64
	v_exp_f32_e32 v60, v60
	v_sub_f32_e32 v64, -0.5, v64
	v_mul_f32_e32 v64, 0x3fb8aa3b, v64
	v_exp_f32_e32 v64, v64
	v_add_f32_e32 v60, 1.0, v60
	v_cmp_gt_f32_e64 s[0:1], s75, v60
	v_mul_f32_e32 v64, 0xbfb8aa3b, v64
	s_nop 0
	v_cndmask_b32_e64 v80, 0, 32, s[0:1]
	v_ldexp_f32 v60, v60, v80
	v_exp_f32_e32 v64, v64
	v_log_f32_e32 v60, v60
	s_nop 0
	v_mul_f32_e32 v80, 0x3f317217, v60
	v_fma_f32 v80, v60, s58, -v80
	v_fmac_f32_e32 v80, 0x3377d1cf, v60
	v_fmac_f32_e32 v80, 0x3f317217, v60
	v_cmp_lt_f32_e64 s[4:5], |v60|, s59
	s_nop 1
	v_cndmask_b32_e64 v60, v60, v80, s[4:5]
	v_cndmask_b32_e64 v80, 0, v243, s[0:1]
	v_sub_f32_e32 v60, v60, v80
	v_add_f32_e32 v60, v65, v60
	v_sub_f32_e32 v60, -0.5, v60
	v_mul_f32_e32 v60, 0x3fb8aa3b, v60
	v_exp_f32_e32 v60, v60
	s_nop 0
	v_mul_f32_e32 v60, 0xbfb8aa3b, v60
	v_exp_f32_e32 v65, v60
	v_add_f32_e32 v60, v61, v81
	v_mul_f32_e32 v60, 0xbfb8aa3b, v60
	v_exp_f32_e32 v60, v60
	s_nop 0
	v_add_f32_e32 v60, 1.0, v60
	v_rcp_f32_e32 v155, v60
	v_add_f32_e32 v60, v66, v86
	v_max_f32_e64 v61, -v60, 0
	v_mul_f32_e64 v60, |v60|, s57
	v_exp_f32_e32 v60, v60
	s_nop 0
	v_add_f32_e32 v60, 1.0, v60
	v_cmp_gt_f32_e64 s[0:1], s75, v60
	s_nop 1
	v_cndmask_b32_e64 v66, 0, 32, s[0:1]
	v_ldexp_f32 v60, v60, v66
	v_log_f32_e32 v60, v60
	s_nop 0
	v_mul_f32_e32 v66, 0x3f317217, v60
	v_fma_f32 v66, v60, s58, -v66
	v_fmac_f32_e32 v66, 0x3377d1cf, v60
	v_fmac_f32_e32 v66, 0x3f317217, v60
	v_cmp_lt_f32_e64 s[4:5], |v60|, s59
	s_nop 1
	v_cndmask_b32_e64 v60, v60, v66, s[4:5]
	v_cndmask_b32_e64 v66, 0, v243, s[0:1]
	v_sub_f32_e32 v60, v60, v66
	v_add_f32_e32 v60, v61, v60
	v_sub_f32_e32 v60, -0.5, v60
	v_mul_f32_e32 v60, 0x3fb8aa3b, v60
	v_exp_f32_e32 v60, v60
	s_nop 0
	v_mul_f32_e32 v60, 0xbfb8aa3b, v60
	v_exp_f32_e32 v66, v60
	v_add_f32_e32 v60, v62, v82
	v_mul_f32_e32 v60, 0xbfb8aa3b, v60
	v_exp_f32_e32 v60, v60
	s_nop 0
	v_add_f32_e32 v60, 1.0, v60
	v_rcp_f32_e32 v156, v60
	v_add_f32_e32 v60, v67, v87
	v_max_f32_e64 v61, -v60, 0
	v_mul_f32_e64 v60, |v60|, s57
	v_exp_f32_e32 v60, v60
	s_nop 0
	v_add_f32_e32 v60, 1.0, v60
	v_cmp_gt_f32_e64 s[0:1], s75, v60
	s_nop 1
	v_cndmask_b32_e64 v62, 0, 32, s[0:1]
	v_ldexp_f32 v60, v60, v62
	v_log_f32_e32 v60, v60
	s_nop 0
	v_mul_f32_e32 v62, 0x3f317217, v60
	v_fma_f32 v62, v60, s58, -v62
	v_fmac_f32_e32 v62, 0x3377d1cf, v60
	v_fmac_f32_e32 v62, 0x3f317217, v60
	v_cmp_lt_f32_e64 s[4:5], |v60|, s59
	s_nop 1
	v_cndmask_b32_e64 v60, v60, v62, s[4:5]
	v_cndmask_b32_e64 v62, 0, v243, s[0:1]
	v_sub_f32_e32 v60, v60, v62
	v_add_f32_e32 v60, v61, v60
	v_sub_f32_e32 v60, -0.5, v60
	v_mul_f32_e32 v60, 0x3fb8aa3b, v60
	v_exp_f32_e32 v60, v60
	v_and_b32_e32 v61, 0xffff0000, v159
	v_lshlrev_b32_e32 v62, 16, v158
	v_xor_b32_e32 v81, 0x80000000, v61
	v_mul_f32_e32 v60, 0xbfb8aa3b, v60
	v_exp_f32_e32 v67, v60
	v_add_f32_e32 v60, v63, v83
	v_mul_f32_e32 v60, 0xbfb8aa3b, v60
	v_exp_f32_e32 v60, v60
	v_and_b32_e32 v63, 0xffff0000, v158
	v_xor_b32_e32 v83, 0x80000000, v63
	v_xor_b32_e32 v82, 0x80000000, v62
	v_add_f32_e32 v60, 1.0, v60
	v_rcp_f32_e32 v157, v60
	v_lshlrev_b32_e32 v60, 16, v159
	v_xor_b32_e32 v80, 0x80000000, v60
	v_pk_fma_f32 v[80:81], v[100:101], v[162:163], v[80:81]
	v_pk_fma_f32 v[82:83], v[0:1], v[160:161], v[82:83]
	v_pk_fma_f32 v[58:59], v[58:59], v[80:81], v[60:61]
	v_pk_fma_f32 v[56:57], v[56:57], v[82:83], v[62:63]
	v_pk_add_f32 v[62:63], v[154:155], -1.0 op_sel_hi:[1,0]
	v_pk_add_f32 v[60:61], v[156:157], -1.0 op_sel_hi:[1,0]
	s_waitcnt vmcnt(1)
; __device__ __forceinline__ void rwkv_prep_item(const Params& p, const Lt& lt, int l, int item) {
;     ...
;         for (int ct = 0; ct < 4; ++ct) {
;             const int crow = h * 64 + ct * 16 + qi;
;             f32x4 aw = {0.f, 0.f, 0.f, 0.f}, aa = aw, ag = aw;
; #pragma unroll
;             for (int ks = 0; ks < 2; ++ks) {
;                 aw = __builtin_amdgcn_mfma_f32_16x16x32_bf16(*(const bf16x8*)(decT + crow * 64 + ks * 32 + quad * 8), fw[ks], aw, 0, 0, 0);
;                 aa = __builtin_amdgcn_mfma_f32_16x16x32_bf16(*(const bf16x8*)(aT + crow * 64 + ks * 32 + quad * 8), fa[ks], aa, 0, 0, 0);
;             }
; #pragma unroll
;             for (int ks = 0; ks < 4; ++ks) ag = __builtin_amdgcn_mfma_f32_16x16x32_bf16(*(const bf16x8*)(gT + crow * 128 + ks * 32 + quad * 8), fg[ks], ag, 0, 0, 0);
;             const int c = h * 64 + ct * 16 + quad * 4;
;             const f32x4 mr = *(const f32x4*)(mu + c), mk = *(const f32x4*)(mu + COL_K + c), mv = *(const f32x4*)(mu + COL_V + c);
;             const f32x4 cr = ld_bf4(pt + c), ck = ld_bf4(pt + COL_K + c), cv = ld_bf4(pt + COL_V + c);
;             const f32x4 qr = ld_bf4(pp + c) * pm, qk = ld_bf4(pp + COL_K + c) * pm, qv = ld_bf4(pp + COL_V + c) * pm;
;             const f32x4 r = cr + (qr - cr) * mr, k = ck + (qk - ck) * mk, v = cv + (qv - cv) * mv;
;             const f32x4 w0v = *(const f32x4*)(w0 + c), a0v = *(const f32x4*)(a0 + c), kkv = *(const f32x4*)(kkp + c), kav = *(const f32x4*)(kap + c), rkv = *(const f32x4*)(rkp + c);
;             f32x4 dec, a, kk, k2;
; #pragma unroll
;             for (int j = 0; j < 4; ++j) {
;                 const float z = -(w0v[j] + aw[j]);
;                 const float sp = fmaxf(z, 0.f) + __logf(1.0f + __expf(-fabsf(z)));
;                 dec[j] = __expf(-__expf(-sp - 0.5f));
;                 a[j] = sigmoidf_(a0v[j] + aa[j]);
;                 kk[j] = k[j] * kkv[j];
;                 nrm += kk[j] * kk[j];
;                 k2[j] = k[j] * (1.0f + (a[j] - 1.0f) * kav[j]);
;                 bon += r[j] * k2[j] * rkv[j];
;             }
;             va[ct] = a; vkk[ct] = kk;
;             { const int cc = ct * 16 + quad * 4; *(f32x4*)(ob + cc * 4) = dec; st_bf4(ob + 512 + cc * 2, k2); st_bf4(ob + 640 + cc * 2, v); st_bf4(ob + 768 + cc * 2, r); }
;             st_bf4((unsigned char*)((bf16_t*)gate + (size_t)t * RW + c), ag);
;         }
	v_pk_fma_f32 v[62:63], v[76:77], v[62:63], 1.0 op_sel_hi:[1,1,0]
	v_pk_fma_f32 v[60:61], v[78:79], v[60:61], 1.0 op_sel_hi:[1,1,0]
	v_pk_mul_f32 v[158:159], v[72:73], v[56:57]
	v_pk_mul_f32 v[56:57], v[56:57], v[62:63]
	v_pk_mul_f32 v[60:61], v[58:59], v[60:61]
	v_sub_u32_e32 v233, v44, v231
	ds_write_b128 v233, v[64:67]
	v_lshl_add_u64 v[44:45], v[120:121], 0, v[104:105]
	v_mul_f32_e32 v62, v172, v56
	v_cvt_pk_bf16_f32 v46, v56, v57
	v_cvt_pk_bf16_f32 v47, v60, v61
	v_sub_u32_e32 v233, v44, v231
	ds_write_b64 v233, v[40:41] offset:640
	v_cvt_pk_bf16_f32 v40, v172, v173
	v_cvt_pk_bf16_f32 v41, v170, v171
	s_or_b32 s0, s10, 48
	s_waitcnt vmcnt(0)
	v_fmac_f32_e32 v185, v68, v62
	v_mul_f32_e32 v62, v173, v57
	v_sub_u32_e32 v233, v44, v231
	ds_write_b64 v233, v[46:47] offset:512
	v_sub_u32_e32 v233, v44, v231
	ds_write_b64 v233, v[40:41] offset:768
	v_or_b32_e32 v44, s0, v180
	v_fmac_f32_e32 v185, v69, v62
	v_mul_f32_e32 v62, v170, v60
	global_store_dwordx2 v[140:141], v[36:37], off offset:64
	v_lshlrev_b32_e32 v36, 7, v44
	v_mov_b32_e32 v37, v3
	v_fmac_f32_e32 v185, v70, v62
	v_pk_mul_f32 v[160:161], v[74:75], v[58:59]
	v_mul_f32_e32 v58, v171, v61
	v_lshl_add_u64 v[38:39], v[88:89], 0, v[36:37]
	v_fmac_f32_e32 v185, v71, v58
	v_lshl_add_u64 v[36:37], v[92:93], 0, v[36:37]
	global_load_dwordx4 v[210:213], v184, s[8:9] offset:192
	global_load_dwordx4 v[214:217], v184, s[8:9] offset:3264
	global_load_dwordx4 v[218:221], v184, s[52:53] offset:192
	global_load_dwordx2 v[236:237], v[134:135], off offset:96
	global_load_dwordx2 v[194:195], v[134:135], off offset:1632
	global_load_dwordx2 v[198:199], v[134:135], off offset:3168
	global_load_dwordx2 v[206:207], v[132:133], off offset:1632
	global_load_dwordx2 v[248:249], v[132:133], off offset:96
	global_load_dwordx4 v[222:225], v184, s[42:43] offset:192
	global_load_dwordx4 v[40:43], v[38:39], off
	global_load_dwordx4 v[56:59], v[36:37], off
	global_load_dwordx4 v[60:63], v[38:39], off offset:64
	global_load_dwordx4 v[68:71], v[36:37], off offset:64
	v_lshlrev_b32_e32 v36, 8, v44
	v_mov_b32_e32 v37, v3
	v_lshl_add_u64 v[36:37], v[94:95], 0, v[36:37]
	global_load_dwordx4 v[52:55], v[36:37], off
	global_load_dwordx4 v[48:51], v[36:37], off offset:64
	global_load_dwordx4 v[44:47], v[36:37], off offset:128
	s_nop 0
	global_load_dwordx4 v[36:39], v[36:37], off offset:192
	v_pk_mul_f32 v[162:163], v[158:159], v[158:159]
	v_pk_mul_f32 v[164:165], v[160:161], v[160:161]
	s_waitcnt vmcnt(7)
	v_mfma_f32_16x16x32_bf16 v[40:43], v[40:43], v[20:23], 0
	s_waitcnt vmcnt(6)
	v_mfma_f32_16x16x32_bf16 v[56:59], v[56:59], v[28:31], 0
	s_waitcnt vmcnt(5)
	v_mfma_f32_16x16x32_bf16 v[64:67], v[60:63], v[24:27], v[40:43]
	s_nop 3
	v_or_b32_e32 v40, s0, v181
	v_lshlrev_b32_e32 v40, 2, v40
	s_waitcnt vmcnt(4)
	v_mfma_f32_16x16x32_bf16 v[60:63], v[68:71], v[32:35], v[56:59]
	s_waitcnt vmcnt(16)
	v_mov_b64_e32 v[68:69], v[210:211]
	v_mov_b64_e32 v[70:71], v[212:213]
	s_nop 1
	s_waitcnt vmcnt(15)
	v_mov_b64_e32 v[56:57], v[214:215]
	v_mov_b64_e32 v[58:59], v[216:217]
	s_nop 0
	s_waitcnt vmcnt(14)
	v_mov_b64_e32 v[40:41], v[218:219]
	v_mov_b64_e32 v[42:43], v[220:221]
	s_nop 0
	s_waitcnt vmcnt(13)
	v_mov_b64_e32 v[72:73], v[236:237]
	s_waitcnt vmcnt(12)
	v_mov_b64_e32 v[174:175], v[194:195]
	s_waitcnt vmcnt(11)
	v_mov_b64_e32 v[76:77], v[198:199]
	s_waitcnt vmcnt(3)
	v_mfma_f32_16x16x32_bf16 v[52:55], v[52:55], v[4:7], 0
	s_waitcnt vmcnt(10)
	v_mov_b64_e32 v[80:81], v[206:207]
	s_waitcnt vmcnt(0)
	v_lshlrev_b32_e32 v74, 16, v72
	s_waitcnt vmcnt(0)
	v_lshlrev_b32_e32 v134, 16, v76
	v_and_b32_e32 v135, 0xffff0000, v76
	v_lshlrev_b32_e32 v166, 16, v77
	v_and_b32_e32 v167, 0xffff0000, v77
	s_waitcnt vmcnt(9)
	v_mov_b64_e32 v[76:77], v[248:249]
	v_and_b32_e32 v75, 0xffff0000, v72
	v_xor_b32_e32 v85, 0x80000000, v75
	v_xor_b32_e32 v84, 0x80000000, v74
	v_lshlrev_b32_e32 v72, 16, v73
	v_and_b32_e32 v73, 0xffff0000, v73
	v_mfma_f32_16x16x32_bf16 v[48:51], v[48:51], v[8:11], v[52:55]
	s_waitcnt vmcnt(0)
	v_lshlrev_b32_e32 v176, 16, v80
	v_and_b32_e32 v177, 0xffff0000, v80
	v_lshlrev_b32_e32 v178, 16, v81
	v_and_b32_e32 v179, 0xffff0000, v81
	global_load_dwordx2 v[80:81], v[132:133], off offset:3168
	v_mfma_f32_16x16x32_bf16 v[44:47], v[44:47], v[12:15], v[48:51]
	s_waitcnt vmcnt(1)
	v_lshlrev_b32_e32 v78, 16, v76
	v_and_b32_e32 v79, 0xffff0000, v76
	v_pk_fma_f32 v[78:79], v[0:1], v[78:79], v[84:85]
	v_lshlrev_b32_e32 v76, 16, v77
	v_and_b32_e32 v77, 0xffff0000, v77
	v_xor_b32_e32 v85, 0x80000000, v73
	v_xor_b32_e32 v84, 0x80000000, v72
	v_pk_fma_f32 v[168:169], v[68:69], v[78:79], v[74:75]
	v_xor_b32_e32 v69, 0x80000000, v135
	v_xor_b32_e32 v68, 0x80000000, v134
	v_pk_fma_f32 v[76:77], v[100:101], v[76:77], v[84:85]
	v_mfma_f32_16x16x32_bf16 v[36:39], v[36:39], v[16:19], v[44:47]
	v_fma_f32 v132, v70, v76, v72
	v_fma_f32 v133, v71, v77, v73
	s_waitcnt vmcnt(0)
	v_lshlrev_b32_e32 v82, 16, v80
	v_and_b32_e32 v83, 0xffff0000, v80
	v_lshlrev_b32_e32 v80, 16, v81
	v_and_b32_e32 v81, 0xffff0000, v81
	v_pk_fma_f32 v[170:171], v[0:1], v[82:83], v[68:69]
	v_xor_b32_e32 v69, 0x80000000, v167
	v_xor_b32_e32 v68, 0x80000000, v166
	v_pk_fma_f32 v[172:173], v[100:101], v[80:81], v[68:69]
	s_waitcnt vmcnt(9)
	v_mov_b64_e32 v[76:77], v[222:223]
	v_mov_b64_e32 v[78:79], v[224:225]
	global_load_dwordx4 v[84:87], v184, s[44:45] offset:192
	global_load_dwordx4 v[72:75], v184, s[46:47] offset:192
	global_load_dwordx4 v[80:83], v184, s[48:49] offset:192
	global_load_dwordx4 v[68:71], v184, s[50:51] offset:192
	v_pk_fma_f32 v[42:43], v[42:43], v[172:173], v[166:167]
	v_pk_fma_f32 v[40:41], v[40:41], v[170:171], v[134:135]
	v_lshl_add_u64 v[44:45], v[120:121], 0, v[96:97]
	v_cvt_pk_bf16_f32 v40, v40, v41
	v_cvt_pk_bf16_f32 v41, v42, v43
	v_cvt_pk_bf16_f32 v36, v36, v37
	v_cvt_pk_bf16_f32 v37, v38, v39
	s_waitcnt vmcnt(4)
; __device__ __forceinline__ float quad_sum(float v) { v += xor16(v); v += xor32(v); return v; }
; __device__ __forceinline__ float sigmoidf_(float x) { return __builtin_amdgcn_rcpf(1.0f + __expf(-x)); }
; __device__ __forceinline__ void st_bf4(unsigned char* q, f32x4 v) { u32x2 w; w.x = cvt_pk_bf16(v[0], v[1]); w.y = cvt_pk_bf16(v[2], v[3]); *(u32x2*)q = w; }
; __device__ __forceinline__ f32x4 ld_bf4(const bf16_t* q) { const u32x2 u = *(const u32x2*)q; return (f32x4){bflo(u.x), bfhi(u.x), bflo(u.y), bfhi(u.y)}; }
; __device__ __forceinline__ void rwkv_prep_item(const Params& p, const Lt& lt, int l, int item) {
;     ...
;             const f32x4 mr = *(const f32x4*)(mu + c), mk = *(const f32x4*)(mu + COL_K + c), mv = *(const f32x4*)(mu + COL_V + c);
;             const f32x4 cr = ld_bf4(pt + c), ck = ld_bf4(pt + COL_K + c), cv = ld_bf4(pt + COL_V + c);
;             const f32x4 qr = ld_bf4(pp + c) * pm, qk = ld_bf4(pp + COL_K + c) * pm, qv = ld_bf4(pp + COL_V + c) * pm;
;             const f32x4 r = cr + (qr - cr) * mr, k = ck + (qk - ck) * mk, v = cv + (qv - cv) * mv;
;             const f32x4 w0v = *(const f32x4*)(w0 + c), a0v = *(const f32x4*)(a0 + c), kkv = *(const f32x4*)(kkp + c), kav = *(const f32x4*)(kap + c), rkv = *(const f32x4*)(rkp + c);
;             f32x4 dec, a, kk, k2;
; #pragma unroll
;             for (int j = 0; j < 4; ++j) {
;                 const float z = -(w0v[j] + aw[j]);
;                 const float sp = fmaxf(z, 0.f) + __logf(1.0f + __expf(-fabsf(z)));
;                 dec[j] = __expf(-__expf(-sp - 0.5f));
;                 a[j] = sigmoidf_(a0v[j] + aa[j]);
;                 kk[j] = k[j] * kkv[j];
;                 nrm += kk[j] * kk[j];
;                 k2[j] = k[j] * (1.0f + (a[j] - 1.0f) * kav[j]);
;                 bon += r[j] * k2[j] * rkv[j];
;             }
;             va[ct] = a; vkk[ct] = kk;
;             { const int cc = ct * 16 + quad * 4; *(f32x4*)(ob + cc * 4) = dec; st_bf4(ob + 512 + cc * 2, k2); st_bf4(ob + 640 + cc * 2, v); st_bf4(ob + 768 + cc * 2, r); }
;             st_bf4((unsigned char*)((bf16_t*)gate + (size_t)t * RW + c), ag);
;         }
;         nrm = quad_sum(nrm); bon = quad_sum(bon);
	v_add_f32_e32 v64, v64, v76
	v_max_f32_e64 v76, -v64, 0
	v_mul_f32_e64 v64, |v64|, s57
	v_exp_f32_e32 v64, v64
	v_add_f32_e32 v65, v65, v77
	v_add_f32_e32 v66, v66, v78
	v_add_f32_e32 v67, v67, v79
	v_add_f32_e32 v64, 1.0, v64
	v_cmp_gt_f32_e64 s[0:1], s75, v64
	s_waitcnt vmcnt(3)
	v_add_f32_e32 v60, v60, v84
	v_add_f32_e32 v61, v61, v85
	v_cndmask_b32_e64 v184, 0, 32, s[0:1]
	v_ldexp_f32 v64, v64, v184
	v_log_f32_e32 v64, v64
	v_mul_f32_e32 v60, 0xbfb8aa3b, v60
	v_mul_f32_e32 v61, 0xbfb8aa3b, v61
	v_exp_f32_e32 v60, v60
	v_mul_f32_e32 v184, 0x3f317217, v64
	v_fma_f32 v184, v64, s58, -v184
	v_fmac_f32_e32 v184, 0x3377d1cf, v64
	v_fmac_f32_e32 v184, 0x3f317217, v64
	v_cmp_lt_f32_e64 s[4:5], |v64|, s59
	v_exp_f32_e32 v61, v61
	v_add_f32_e32 v62, v62, v86
	v_cndmask_b32_e64 v64, v64, v184, s[4:5]
	v_cndmask_b32_e64 v184, 0, v243, s[0:1]
	v_sub_f32_e32 v64, v64, v184
	v_add_f32_e32 v64, v76, v64
	v_max_f32_e64 v76, -v65, 0
	v_mul_f32_e64 v65, |v65|, s57
	v_exp_f32_e32 v65, v65
	v_add_f32_e32 v63, v63, v87
	v_add_f32_e32 v60, 1.0, v60
	v_add_f32_e32 v61, 1.0, v61
	v_add_f32_e32 v65, 1.0, v65
	v_cmp_gt_f32_e64 s[0:1], s75, v65
	v_mul_f32_e32 v62, 0xbfb8aa3b, v62
	v_mul_f32_e32 v63, 0xbfb8aa3b, v63
	v_cndmask_b32_e64 v77, 0, 32, s[0:1]
	v_ldexp_f32 v65, v65, v77
	v_log_f32_e32 v65, v65
	v_rcp_f32_e32 v60, v60
	v_rcp_f32_e32 v61, v61
	v_exp_f32_e32 v62, v62
	v_mul_f32_e32 v77, 0x3f317217, v65
	v_fma_f32 v77, v65, s58, -v77
	v_fmac_f32_e32 v77, 0x3377d1cf, v65
	v_fmac_f32_e32 v77, 0x3f317217, v65
	v_cmp_lt_f32_e64 s[4:5], |v65|, s59
	v_exp_f32_e32 v63, v63
	v_lshlrev_b32_e32 v78, 16, v174
	v_cndmask_b32_e64 v65, v65, v77, s[4:5]
	v_cndmask_b32_e64 v77, 0, v243, s[0:1]
	v_sub_f32_e32 v65, v65, v77
	v_add_f32_e32 v65, v76, v65
	v_max_f32_e64 v76, -v66, 0
	v_mul_f32_e64 v66, |v66|, s57
	v_exp_f32_e32 v66, v66
	v_and_b32_e32 v79, 0xffff0000, v174
	v_xor_b32_e32 v87, 0x80000000, v79
	v_xor_b32_e32 v86, 0x80000000, v78
	v_add_f32_e32 v66, 1.0, v66
	v_cmp_gt_f32_e64 s[0:1], s75, v66
	v_pk_fma_f32 v[86:87], v[0:1], v[176:177], v[86:87]
	v_add_f32_e32 v62, 1.0, v62
	v_cndmask_b32_e64 v77, 0, 32, s[0:1]
	v_ldexp_f32 v66, v66, v77
	v_log_f32_e32 v66, v66
	v_add_f32_e32 v63, 1.0, v63
	v_pk_fma_f32 v[78:79], v[56:57], v[86:87], v[78:79]
	v_pk_add_f32 v[86:87], v[60:61], -1.0 op_sel_hi:[1,0]
	v_mul_f32_e32 v77, 0x3f317217, v66
	v_fma_f32 v77, v66, s58, -v77
	v_fmac_f32_e32 v77, 0x3377d1cf, v66
	v_fmac_f32_e32 v77, 0x3f317217, v66
	v_cmp_lt_f32_e64 s[4:5], |v66|, s59
	v_rcp_f32_e32 v62, v62
	v_rcp_f32_e32 v63, v63
	v_cndmask_b32_e64 v66, v66, v77, s[4:5]
	v_cndmask_b32_e64 v77, 0, v243, s[0:1]
	v_sub_f32_e32 v66, v66, v77
	v_add_f32_e32 v66, v76, v66
	v_max_f32_e64 v76, -v67, 0
	v_mul_f32_e64 v67, |v67|, s57
	v_exp_f32_e32 v67, v67
	s_waitcnt vmcnt(1)
	v_pk_fma_f32 v[80:81], v[80:81], v[86:87], 1.0 op_sel_hi:[1,1,0]
	v_pk_mul_f32 v[56:57], v[72:73], v[78:79]
	v_pk_mul_f32 v[78:79], v[78:79], v[80:81]
	v_add_f32_e32 v67, 1.0, v67
	v_cmp_gt_f32_e64 s[0:1], s75, v67
	v_mul_f32_e32 v80, v168, v78
	s_waitcnt vmcnt(0)
	v_fmac_f32_e32 v185, v68, v80
	v_cndmask_b32_e64 v77, 0, 32, s[0:1]
	v_ldexp_f32 v67, v67, v77
	v_log_f32_e32 v67, v67
	v_mul_f32_e32 v68, v169, v79
	v_fmac_f32_e32 v185, v69, v68
	v_pk_add_f32 v[68:69], v[62:63], -1.0 op_sel_hi:[1,0]
	v_mul_f32_e32 v77, 0x3f317217, v67
	v_fma_f32 v77, v67, s58, -v77
	v_fmac_f32_e32 v77, 0x3377d1cf, v67
	v_fmac_f32_e32 v77, 0x3f317217, v67
	v_cmp_lt_f32_e64 s[4:5], |v67|, s59
	v_pk_fma_f32 v[68:69], v[82:83], v[68:69], 1.0 op_sel_hi:[1,1,0]
	v_sub_f32_e32 v64, -0.5, v64
	v_cndmask_b32_e64 v67, v67, v77, s[4:5]
	v_cndmask_b32_e64 v77, 0, v243, s[0:1]
	v_sub_f32_e32 v67, v67, v77
	v_add_f32_e32 v67, v76, v67
	v_lshlrev_b32_e32 v76, 16, v175
	v_and_b32_e32 v77, 0xffff0000, v175
	v_xor_b32_e32 v85, 0x80000000, v77
	v_xor_b32_e32 v84, 0x80000000, v76
	v_pk_fma_f32 v[84:85], v[100:101], v[178:179], v[84:85]
	v_sub_f32_e32 v65, -0.5, v65
	v_pk_fma_f32 v[58:59], v[58:59], v[84:85], v[76:77]
	v_sub_f32_e32 v66, -0.5, v66
	v_pk_mul_f32 v[68:69], v[58:59], v[68:69]
	v_sub_f32_e32 v67, -0.5, v67
	v_mul_f32_e32 v76, v132, v68
	v_fmac_f32_e32 v185, v70, v76
	v_add_f32_e32 v70, v136, v137
	v_add_f32_e32 v70, v138, v70
	v_add_f32_e32 v70, v139, v70
	v_mul_f32_e32 v64, 0x3fb8aa3b, v64
	v_mul_f32_e32 v65, 0x3fb8aa3b, v65
	v_mul_f32_e32 v66, 0x3fb8aa3b, v66
	v_mul_f32_e32 v67, 0x3fb8aa3b, v67
	v_add_f32_e32 v70, v70, v150
	v_exp_f32_e32 v64, v64
	v_exp_f32_e32 v65, v65
	v_exp_f32_e32 v66, v66
	v_exp_f32_e32 v67, v67
	v_add_f32_e32 v70, v151, v70
	v_add_f32_e32 v70, v152, v70
	v_add_f32_e32 v70, v153, v70
	v_add_f32_e32 v70, v70, v162
	v_mul_f32_e32 v64, 0xbfb8aa3b, v64
	v_mul_f32_e32 v65, 0xbfb8aa3b, v65
	v_mul_f32_e32 v66, 0xbfb8aa3b, v66
	v_mul_f32_e32 v67, 0xbfb8aa3b, v67
	v_add_f32_e32 v70, v163, v70
	v_exp_f32_e32 v64, v64
	v_exp_f32_e32 v65, v65
	v_exp_f32_e32 v66, v66
	v_exp_f32_e32 v67, v67
	v_add_f32_e32 v70, v164, v70
	v_pk_mul_f32 v[72:73], v[56:57], v[56:57]
	v_add_f32_e32 v70, v165, v70
	v_pk_mul_f32 v[58:59], v[74:75], v[58:59]
	v_add_f32_e32 v70, v70, v72
	v_pk_mul_f32 v[74:75], v[58:59], v[58:59]
	v_add_f32_e32 v70, v73, v70
	v_add_f32_e32 v70, v74, v70
	v_sub_u32_e32 v233, v44, v231
	ds_write_b128 v233, v[64:67]
	v_lshl_add_u64 v[44:45], v[120:121], 0, v[98:99]
	v_add_f32_e32 v70, v75, v70
	v_cvt_pk_bf16_f32 v46, v78, v79
	v_cvt_pk_bf16_f32 v47, v68, v69
	v_sub_u32_e32 v233, v44, v231
	ds_write_b64 v233, v[40:41] offset:640
	v_cvt_pk_bf16_f32 v40, v168, v169
	v_cvt_pk_bf16_f32 v41, v132, v133
	v_sub_u32_e32 v233, v44, v231
	ds_write_b64 v233, v[46:47] offset:512
	v_sub_u32_e32 v233, v44, v231
	ds_write_b64 v233, v[40:41] offset:768
	global_store_dwordx2 v[140:141], v[36:37], off offset:96
	ds_bpermute_b32 v36, v182, v70
	v_mul_f32_e32 v72, v133, v69
	v_fmac_f32_e32 v185, v71, v72
	s_waitcnt lgkmcnt(0)
; __device__ __forceinline__ float quad_sum(float v) { v += xor16(v); v += xor32(v); return v; }
; __device__ __forceinline__ void st_bf4(unsigned char* q, f32x4 v) { u32x2 w; w.x = cvt_pk_bf16(v[0], v[1]); w.y = cvt_pk_bf16(v[2], v[3]); *(u32x2*)q = w; }
; __device__ __forceinline__ void rwkv_prep_item(const Params& p, const Lt& lt, int l, int item) {
;     ...
;         nrm = quad_sum(nrm); bon = quad_sum(bon);
;         const float inv = rsqrtf(fmaxf(nrm, 1e-24f));
; #pragma unroll
;         for (int ct = 0; ct < 4; ++ct) {
;             const int cc = ct * 16 + quad * 4;
;             const f32x4 kkn = vkk[ct] * inv;
;             st_bf4(ob + 256 + cc * 2, -kkn);
;             st_bf4(ob + 384 + cc * 2, kkn * va[ct]);
;         }
;         if (quad == 0) bonus[(size_t)t * 16 + h] = bon;
	v_add_f32_e32 v36, v70, v36
	ds_bpermute_b32 v37, v183, v36
	s_waitcnt lgkmcnt(0)
	v_add_f32_e32 v38, v36, v37
	v_max_f32_e32 v38, 0x179abe15, v38
	v_rsq_f32_e32 v38, v38
	ds_bpermute_b32 v36, v182, v185
	v_pk_mul_f32 v[40:41], v[126:127], v[38:39] op_sel_hi:[1,0]
	v_pk_mul_f32 v[42:43], v[128:129], v[38:39] op_sel_hi:[1,0]
	v_xor_b32_e32 v44, 0x80000000, v41
	v_xor_b32_e32 v39, 0x80000000, v43
	v_xor_b32_e32 v45, 0x80000000, v42
	v_xor_b32_e32 v46, 0x80000000, v40
	v_pk_mul_f32 v[42:43], v[124:125], v[42:43]
	v_pk_mul_f32 v[40:41], v[122:123], v[40:41]
	v_cvt_pk_bf16_f32 v44, v46, v44
	v_cvt_pk_bf16_f32 v40, v40, v41
	v_cvt_pk_bf16_f32 v41, v42, v43
	v_cvt_pk_bf16_f32 v45, v45, v39
	v_sub_u32_e32 v233, v130, v231
	ds_write_b64 v233, v[40:41] offset:384
	v_pk_mul_f32 v[40:41], v[146:147], v[38:39] op_sel_hi:[1,0]
	v_pk_mul_f32 v[42:43], v[148:149], v[38:39] op_sel_hi:[1,0]
	v_sub_u32_e32 v233, v130, v231
	ds_write_b64 v233, v[44:45] offset:256
	v_xor_b32_e32 v39, 0x80000000, v43
	v_xor_b32_e32 v45, 0x80000000, v42
	v_xor_b32_e32 v44, 0x80000000, v41
	v_xor_b32_e32 v46, 0x80000000, v40
	v_pk_mul_f32 v[42:43], v[144:145], v[42:43]
	v_pk_mul_f32 v[40:41], v[142:143], v[40:41]
	s_waitcnt lgkmcnt(0)
	v_add_f32_e32 v36, v185, v36
	v_cvt_pk_bf16_f32 v40, v40, v41
	v_cvt_pk_bf16_f32 v41, v42, v43
	v_cvt_pk_bf16_f32 v44, v46, v44
	v_cvt_pk_bf16_f32 v45, v45, v39
	v_sub_u32_e32 v233, v130, v231
	ds_write_b64 v233, v[40:41] offset:416
	v_pk_mul_f32 v[40:41], v[158:159], v[38:39] op_sel_hi:[1,0]
	v_pk_mul_f32 v[42:43], v[160:161], v[38:39] op_sel_hi:[1,0]
	ds_bpermute_b32 v37, v183, v36
	v_sub_u32_e32 v233, v130, v231
	ds_write_b64 v233, v[44:45] offset:288
	v_xor_b32_e32 v39, 0x80000000, v43
	v_xor_b32_e32 v45, 0x80000000, v42
	v_xor_b32_e32 v44, 0x80000000, v41
	v_xor_b32_e32 v46, 0x80000000, v40
	v_pk_mul_f32 v[42:43], v[156:157], v[42:43]
	v_pk_mul_f32 v[40:41], v[154:155], v[40:41]
	v_cvt_pk_bf16_f32 v44, v46, v44
	v_cvt_pk_bf16_f32 v40, v40, v41
	v_cvt_pk_bf16_f32 v41, v42, v43
	v_cvt_pk_bf16_f32 v45, v45, v39
	v_sub_u32_e32 v233, v130, v231
	ds_write_b64 v233, v[40:41] offset:448
	v_pk_mul_f32 v[40:41], v[56:57], v[38:39] op_sel_hi:[1,0]
	v_pk_mul_f32 v[38:39], v[58:59], v[38:39] op_sel_hi:[1,0]
	v_sub_u32_e32 v233, v130, v231
	ds_write_b64 v233, v[44:45] offset:320
	v_xor_b32_e32 v43, 0x80000000, v39
	v_xor_b32_e32 v44, 0x80000000, v38
	v_xor_b32_e32 v42, 0x80000000, v41
	v_xor_b32_e32 v45, 0x80000000, v40
	v_pk_mul_f32 v[38:39], v[62:63], v[38:39]
	v_pk_mul_f32 v[40:41], v[60:61], v[40:41]
	v_cvt_pk_bf16_f32 v42, v45, v42
	v_cvt_pk_bf16_f32 v43, v44, v43
	v_cvt_pk_bf16_f32 v40, v40, v41
	v_cvt_pk_bf16_f32 v41, v38, v39
	v_sub_u32_e32 v233, v130, v231
	ds_write_b64 v233, v[42:43] offset:352
	v_sub_u32_e32 v233, v130, v231
	ds_write_b64 v233, v[40:41] offset:480
	s_waitcnt lgkmcnt(0)
	s_mov_b32 s98, -1
	s_mov_b32 s99, 0xffffff
	s_mov_b64 exec, s[98:99]
	s_movk_i32 s98, 896
	s_mov_b32 s99, 0
	v_lshl_add_u64 v[228:229], v[234:235], 0, s[98:99]
	s_movk_i32 s98, 0x2a00
	ds_read_b128 v[210:213], v226 offset:0
	ds_read_b128 v[214:217], v226 offset:912
	ds_read_b128 v[218:221], v226 offset:1824
	ds_read_b128 v[222:225], v226 offset:2736
	s_waitcnt lgkmcnt(3)
	global_store_dwordx4 v[228:229], v[210:213], off
	v_lshl_add_u64 v[228:229], v[228:229], 0, s[98:99]
	s_waitcnt lgkmcnt(2)
	global_store_dwordx4 v[228:229], v[214:217], off
	v_lshl_add_u64 v[228:229], v[228:229], 0, s[98:99]
	s_waitcnt lgkmcnt(1)
	global_store_dwordx4 v[228:229], v[218:221], off
	v_lshl_add_u64 v[228:229], v[228:229], 0, s[98:99]
	s_waitcnt lgkmcnt(0)
	global_store_dwordx4 v[228:229], v[222:225], off
	v_lshl_add_u64 v[228:229], v[228:229], 0, s[98:99]
	ds_read_b128 v[210:213], v226 offset:3648
	ds_read_b128 v[214:217], v226 offset:4560
	ds_read_b128 v[218:221], v226 offset:5472
	ds_read_b128 v[222:225], v226 offset:6384
	s_waitcnt lgkmcnt(3)
	global_store_dwordx4 v[228:229], v[210:213], off
	v_lshl_add_u64 v[228:229], v[228:229], 0, s[98:99]
	s_waitcnt lgkmcnt(2)
	global_store_dwordx4 v[228:229], v[214:217], off
	v_lshl_add_u64 v[228:229], v[228:229], 0, s[98:99]
	s_waitcnt lgkmcnt(1)
	global_store_dwordx4 v[228:229], v[218:221], off
	v_lshl_add_u64 v[228:229], v[228:229], 0, s[98:99]
	s_waitcnt lgkmcnt(0)
	global_store_dwordx4 v[228:229], v[222:225], off
	v_lshl_add_u64 v[228:229], v[228:229], 0, s[98:99]
	ds_read_b128 v[210:213], v226 offset:7296
	ds_read_b128 v[214:217], v226 offset:8208
	ds_read_b128 v[218:221], v226 offset:9120
	ds_read_b128 v[222:225], v226 offset:10032
	s_waitcnt lgkmcnt(3)
	global_store_dwordx4 v[228:229], v[210:213], off
	v_lshl_add_u64 v[228:229], v[228:229], 0, s[98:99]
	s_waitcnt lgkmcnt(2)
	global_store_dwordx4 v[228:229], v[214:217], off
	v_lshl_add_u64 v[228:229], v[228:229], 0, s[98:99]
	s_waitcnt lgkmcnt(1)
	global_store_dwordx4 v[228:229], v[218:221], off
	v_lshl_add_u64 v[228:229], v[228:229], 0, s[98:99]
	s_waitcnt lgkmcnt(0)
	global_store_dwordx4 v[228:229], v[222:225], off
	v_lshl_add_u64 v[228:229], v[228:229], 0, s[98:99]
	ds_read_b128 v[210:213], v226 offset:10944
	ds_read_b128 v[214:217], v226 offset:11856
	ds_read_b128 v[218:221], v226 offset:12768
	ds_read_b128 v[222:225], v226 offset:13680
	s_waitcnt lgkmcnt(3)
	global_store_dwordx4 v[228:229], v[210:213], off
	v_lshl_add_u64 v[228:229], v[228:229], 0, s[98:99]
	s_waitcnt lgkmcnt(2)
	global_store_dwordx4 v[228:229], v[214:217], off
	v_lshl_add_u64 v[228:229], v[228:229], 0, s[98:99]
	s_waitcnt lgkmcnt(1)
	global_store_dwordx4 v[228:229], v[218:221], off
	v_lshl_add_u64 v[228:229], v[228:229], 0, s[98:99]
	s_waitcnt lgkmcnt(0)
	global_store_dwordx4 v[228:229], v[222:225], off
	v_lshl_add_u64 v[228:229], v[228:229], 0, s[98:99]
	s_mov_b64 exec, -1
	s_and_saveexec_b64 s[0:1], vcc
	s_cbranch_execz .LBB0_347
	s_lshl_b32 s10, s56, 2
	v_lshl_add_u64 v[38:39], v[90:91], 0, s[10:11]
	s_waitcnt lgkmcnt(0)
	v_add_f32_e32 v36, v36, v37
	global_store_dword v[38:39], v36, off offset:4
; __device__ __forceinline__ f32x4 ld_bf4(const bf16_t* q) { const u32x2 u = *(const u32x2*)q; return (f32x4){bflo(u.x), bfhi(u.x), bflo(u.y), bfhi(u.y)}; }
; __device__ __forceinline__ void rwkv_prep_item(const Params& p, const Lt& lt, int l, int item) {
;     ...
;     for (int hh = 0; hh < 3; ++hh) {
;         const int h = hg * 3 + hh;
;         f32x4 va[4], vkk[4];
;         float nrm = 0.f, bon = 0.f;
;         unsigned char* ob = opnd + (size_t)t * OPTB + h * OPB;
; #pragma unroll
;         for (int ct = 0; ct < 4; ++ct) {
;             const int crow = h * 64 + ct * 16 + qi;
;             f32x4 aw = {0.f, 0.f, 0.f, 0.f}, aa = aw, ag = aw;
; #pragma unroll
;             for (int ks = 0; ks < 2; ++ks) {
;                 aw = __builtin_amdgcn_mfma_f32_16x16x32_bf16(*(const bf16x8*)(decT + crow * 64 + ks * 32 + quad * 8), fw[ks], aw, 0, 0, 0);
;                 aa = __builtin_amdgcn_mfma_f32_16x16x32_bf16(*(const bf16x8*)(aT + crow * 64 + ks * 32 + quad * 8), fa[ks], aa, 0, 0, 0);
;             }
; #pragma unroll
;             for (int ks = 0; ks < 4; ++ks) ag = __builtin_amdgcn_mfma_f32_16x16x32_bf16(*(const bf16x8*)(gT + crow * 128 + ks * 32 + quad * 8), fg[ks], ag, 0, 0, 0);
;             const int c = h * 64 + ct * 16 + quad * 4;
;             const f32x4 mr = *(const f32x4*)(mu + c), mk = *(const f32x4*)(mu + COL_K + c), mv = *(const f32x4*)(mu + COL_V + c);
;             const f32x4 cr = ld_bf4(pt + c), ck = ld_bf4(pt + COL_K + c), cv = ld_bf4(pt + COL_V + c);
;             const f32x4 qr = ld_bf4(pp + c) * pm, qk = ld_bf4(pp + COL_K + c) * pm, qv = ld_bf4(pp + COL_V + c) * pm;
;             const f32x4 r = cr + (qr - cr) * mr, k = ck + (qk - ck) * mk, v = cv + (qv - cv) * mv;
.LBB0_347:
	s_or_b64 exec, exec, s[0:1]
	s_add_i32 s0, s56, 2
	s_mul_i32 s10, s0, 0x380
	v_lshl_add_u64 v[118:119], v[118:119], 0, s[10:11]
	s_lshl_b32 s10, s0, 6
	v_or_b32_e32 v40, s10, v180
	v_lshlrev_b32_e32 v36, 7, v40
	s_waitcnt lgkmcnt(0)
	v_mov_b32_e32 v37, v3
	v_lshl_add_u64 v[38:39], v[88:89], 0, v[36:37]
	v_lshl_add_u64 v[36:37], v[92:93], 0, v[36:37]
	global_load_dwordx4 v[52:55], v[38:39], off
	global_load_dwordx4 v[56:59], v[36:37], off
	global_load_dwordx4 v[60:63], v[38:39], off offset:64
	global_load_dwordx4 v[68:71], v[36:37], off offset:64
	v_or_b32_e32 v72, s10, v181
	v_lshlrev_b32_e32 v36, 8, v40
	v_mov_b32_e32 v37, v3
	v_lshlrev_b32_e32 v132, 1, v72
	v_mov_b32_e32 v133, v3
	v_lshl_add_u64 v[36:37], v[94:95], 0, v[36:37]
	v_lshlrev_b32_e32 v158, 2, v72
	v_lshl_add_u64 v[126:127], v[114:115], 0, v[132:133]
	global_load_dwordx4 v[48:51], v[36:37], off
	global_load_dwordx4 v[44:47], v[36:37], off offset:64
	global_load_dwordx4 v[40:43], v[36:37], off offset:128
	s_nop 0
	global_load_dwordx4 v[36:39], v[36:37], off offset:192
	v_lshl_add_u64 v[124:125], v[110:111], 0, v[132:133]
	v_lshl_add_u64 v[116:117], v[116:117], 0, v[132:133]
	s_waitcnt vmcnt(7)
	v_mfma_f32_16x16x32_bf16 v[52:55], v[52:55], v[20:23], 0
	s_waitcnt vmcnt(6)
	v_mfma_f32_16x16x32_bf16 v[56:59], v[56:59], v[28:31], 0
	s_waitcnt vmcnt(5)
	v_mfma_f32_16x16x32_bf16 v[64:67], v[60:63], v[24:27], v[52:55]
	s_waitcnt vmcnt(4)
	v_mfma_f32_16x16x32_bf16 v[56:59], v[68:71], v[32:35], v[56:59]
	global_load_dwordx4 v[68:71], v158, s[8:9]
	global_load_dwordx4 v[60:63], v158, s[8:9] offset:3072
	global_load_dwordx4 v[52:55], v158, s[52:53]
	global_load_dwordx2 v[72:73], v[126:127], off
	global_load_dwordx2 v[120:121], v[126:127], off offset:1536
	global_load_dwordx2 v[76:77], v[126:127], off offset:3072
	s_waitcnt vmcnt(9)
	v_mfma_f32_16x16x32_bf16 v[48:51], v[48:51], v[4:7], 0
	global_load_dwordx2 v[80:81], v[124:125], off offset:1536
	s_waitcnt vmcnt(3)
	v_lshlrev_b32_e32 v74, 16, v72
	s_waitcnt vmcnt(1)
	v_lshlrev_b32_e32 v134, 16, v76
	v_and_b32_e32 v135, 0xffff0000, v76
	v_lshlrev_b32_e32 v136, 16, v77
	v_and_b32_e32 v137, 0xffff0000, v77
	global_load_dwordx2 v[76:77], v[124:125], off
	v_and_b32_e32 v75, 0xffff0000, v72
	v_xor_b32_e32 v85, 0x80000000, v75
	v_xor_b32_e32 v84, 0x80000000, v74
	v_lshlrev_b32_e32 v72, 16, v73
	v_and_b32_e32 v73, 0xffff0000, v73
	v_mfma_f32_16x16x32_bf16 v[44:47], v[44:47], v[8:11], v[48:51]
	s_waitcnt vmcnt(1)
	v_lshlrev_b32_e32 v122, 16, v80
	v_and_b32_e32 v123, 0xffff0000, v80
	v_lshlrev_b32_e32 v128, 16, v81
	v_and_b32_e32 v129, 0xffff0000, v81
	global_load_dwordx2 v[80:81], v[124:125], off offset:3072
	v_mfma_f32_16x16x32_bf16 v[40:43], v[40:43], v[12:15], v[44:47]
	s_waitcnt vmcnt(1)
	v_lshlrev_b32_e32 v78, 16, v76
	v_and_b32_e32 v79, 0xffff0000, v76
	v_pk_fma_f32 v[78:79], v[0:1], v[78:79], v[84:85]
	v_lshlrev_b32_e32 v76, 16, v77
	v_and_b32_e32 v77, 0xffff0000, v77
	v_xor_b32_e32 v85, 0x80000000, v73
	v_xor_b32_e32 v84, 0x80000000, v72
	v_pk_fma_f32 v[140:141], v[68:69], v[78:79], v[74:75]
	v_xor_b32_e32 v69, 0x80000000, v135
	v_xor_b32_e32 v68, 0x80000000, v134
	v_pk_fma_f32 v[76:77], v[100:101], v[76:77], v[84:85]
	v_mfma_f32_16x16x32_bf16 v[36:39], v[36:39], v[16:19], v[40:43]
	v_fma_f32 v138, v70, v76, v72
	v_fma_f32 v139, v71, v77, v73
	v_lshl_add_u64 v[44:45], v[118:119], 0, v[112:113]
	v_lshl_add_u64 v[112:113], v[118:119], 0, v[2:3]
	s_waitcnt vmcnt(0)
	v_lshlrev_b32_e32 v82, 16, v80
	v_and_b32_e32 v83, 0xffff0000, v80
	v_lshlrev_b32_e32 v80, 16, v81
	v_and_b32_e32 v81, 0xffff0000, v81
	v_cvt_pk_bf16_f32 v36, v36, v37
	v_cvt_pk_bf16_f32 v37, v38, v39
	v_pk_fma_f32 v[142:143], v[0:1], v[82:83], v[68:69]
	v_xor_b32_e32 v69, 0x80000000, v137
	v_xor_b32_e32 v68, 0x80000000, v136
	v_pk_fma_f32 v[144:145], v[100:101], v[80:81], v[68:69]
	global_load_dwordx4 v[84:87], v158, s[42:43]
	global_load_dwordx4 v[80:83], v158, s[44:45]
	global_load_dwordx4 v[68:71], v158, s[46:47]
	global_load_dwordx4 v[76:79], v158, s[48:49]
	global_load_dwordx4 v[72:75], v158, s[50:51]
	v_pk_fma_f32 v[42:43], v[52:53], v[142:143], v[134:135]
	v_pk_fma_f32 v[40:41], v[54:55], v[144:145], v[136:137]
	v_cvt_pk_bf16_f32 v42, v42, v43
	v_cvt_pk_bf16_f32 v43, v40, v41
	v_cvt_pk_bf16_f32 v40, v140, v141
	v_cvt_pk_bf16_f32 v41, v138, v139
	v_sub_u32_e32 v233, v112, v232
	ds_write_b64 v233, v[42:43] offset:640
	v_sub_u32_e32 v233, v112, v232
	ds_write_b64 v233, v[40:41] offset:768
	s_waitcnt vmcnt(4)
	v_add_f32_e32 v64, v64, v84
	v_max_f32_e64 v84, -v64, 0
	v_mul_f32_e64 v64, |v64|, s57
	s_waitcnt vmcnt(3)
; __device__ __forceinline__ void rwkv_prep_item(const Params& p, const Lt& lt, int l, int item) {
;     ...
;         for (int ct = 0; ct < 4; ++ct) {
;             const int crow = h * 64 + ct * 16 + qi;
;             f32x4 aw = {0.f, 0.f, 0.f, 0.f}, aa = aw, ag = aw;
; #pragma unroll
;             for (int ks = 0; ks < 2; ++ks) {
;                 aw = __builtin_amdgcn_mfma_f32_16x16x32_bf16(*(const bf16x8*)(decT + crow * 64 + ks * 32 + quad * 8), fw[ks], aw, 0, 0, 0);
;                 aa = __builtin_amdgcn_mfma_f32_16x16x32_bf16(*(const bf16x8*)(aT + crow * 64 + ks * 32 + quad * 8), fa[ks], aa, 0, 0, 0);
;             }
; #pragma unroll
;             for (int ks = 0; ks < 4; ++ks) ag = __builtin_amdgcn_mfma_f32_16x16x32_bf16(*(const bf16x8*)(gT + crow * 128 + ks * 32 + quad * 8), fg[ks], ag, 0, 0, 0);
;             const int c = h * 64 + ct * 16 + quad * 4;
;             const f32x4 mr = *(const f32x4*)(mu + c), mk = *(const f32x4*)(mu + COL_K + c), mv = *(const f32x4*)(mu + COL_V + c);
;             const f32x4 cr = ld_bf4(pt + c), ck = ld_bf4(pt + COL_K + c), cv = ld_bf4(pt + COL_V + c);
;             const f32x4 qr = ld_bf4(pp + c) * pm, qk = ld_bf4(pp + COL_K + c) * pm, qv = ld_bf4(pp + COL_V + c) * pm;
;             const f32x4 r = cr + (qr - cr) * mr, k = ck + (qk - ck) * mk, v = cv + (qv - cv) * mv;
;             const f32x4 w0v = *(const f32x4*)(w0 + c), a0v = *(const f32x4*)(a0 + c), kkv = *(const f32x4*)(kkp + c), kav = *(const f32x4*)(kap + c), rkv = *(const f32x4*)(rkp + c);
;             f32x4 dec, a, kk, k2;
; #pragma unroll
;             for (int j = 0; j < 4; ++j) {
;                 const float z = -(w0v[j] + aw[j]);
;                 const float sp = fmaxf(z, 0.f) + __logf(1.0f + __expf(-fabsf(z)));
;                 dec[j] = __expf(-__expf(-sp - 0.5f));
;                 a[j] = sigmoidf_(a0v[j] + aa[j]);
;                 kk[j] = k[j] * kkv[j];
;                 nrm += kk[j] * kk[j];
;                 k2[j] = k[j] * (1.0f + (a[j] - 1.0f) * kav[j]);
;                 bon += r[j] * k2[j] * rkv[j];
;             }
;             va[ct] = a; vkk[ct] = kk;
;             { const int cc = ct * 16 + quad * 4; *(f32x4*)(ob + cc * 4) = dec; st_bf4(ob + 512 + cc * 2, k2); st_bf4(ob + 640 + cc * 2, v); st_bf4(ob + 768 + cc * 2, r); }
;             st_bf4((unsigned char*)((bf16_t*)gate + (size_t)t * RW + c), ag);
;         }
	v_add_f32_e32 v56, v56, v80
	v_exp_f32_e32 v64, v64
	v_mul_f32_e32 v56, 0xbfb8aa3b, v56
	v_exp_f32_e32 v56, v56
	v_add_f32_e32 v64, 1.0, v64
	v_cmp_gt_f32_e64 s[0:1], s75, v64
	v_add_f32_e32 v56, 1.0, v56
	s_nop 0
	v_cndmask_b32_e64 v110, 0, 32, s[0:1]
	v_ldexp_f32 v64, v64, v110
	v_log_f32_e32 v64, v64
	s_nop 0
	v_mul_f32_e32 v110, 0x3f317217, v64
	v_cmp_lt_f32_e64 s[4:5], |v64|, s59
	v_fma_f32 v110, v64, s58, -v110
	v_fmac_f32_e32 v110, 0x3377d1cf, v64
	v_fmac_f32_e32 v110, 0x3f317217, v64
	v_cndmask_b32_e64 v64, v64, v110, s[4:5]
	v_cndmask_b32_e64 v110, 0, v243, s[0:1]
	v_sub_f32_e32 v64, v64, v110
	v_rcp_f32_e32 v110, v56
	v_add_f32_e32 v56, v65, v85
	v_max_f32_e64 v65, -v56, 0
	v_mul_f32_e64 v56, |v56|, s57
	v_add_f32_e32 v64, v84, v64
	v_exp_f32_e32 v56, v56
	v_sub_f32_e32 v64, -0.5, v64
	v_mul_f32_e32 v64, 0x3fb8aa3b, v64
	v_exp_f32_e32 v64, v64
	v_add_f32_e32 v56, 1.0, v56
	v_cmp_gt_f32_e64 s[0:1], s75, v56
	v_mul_f32_e32 v64, 0xbfb8aa3b, v64
	s_nop 0
	v_cndmask_b32_e64 v80, 0, 32, s[0:1]
	v_ldexp_f32 v56, v56, v80
	v_exp_f32_e32 v64, v64
	v_log_f32_e32 v56, v56
	s_nop 0
	v_mul_f32_e32 v80, 0x3f317217, v56
	v_cmp_lt_f32_e64 s[4:5], |v56|, s59
	v_fma_f32 v80, v56, s58, -v80
	v_fmac_f32_e32 v80, 0x3377d1cf, v56
	v_fmac_f32_e32 v80, 0x3f317217, v56
	v_cndmask_b32_e64 v56, v56, v80, s[4:5]
	v_cndmask_b32_e64 v80, 0, v243, s[0:1]
	v_sub_f32_e32 v56, v56, v80
	v_add_f32_e32 v56, v65, v56
	v_sub_f32_e32 v56, -0.5, v56
	v_mul_f32_e32 v56, 0x3fb8aa3b, v56
	v_exp_f32_e32 v56, v56
	s_nop 0
	v_mul_f32_e32 v56, 0xbfb8aa3b, v56
	v_exp_f32_e32 v65, v56
	v_add_f32_e32 v56, v57, v81
	v_mul_f32_e32 v56, 0xbfb8aa3b, v56
	v_exp_f32_e32 v56, v56
	s_nop 0
	v_add_f32_e32 v56, 1.0, v56
	v_rcp_f32_e32 v111, v56
	v_add_f32_e32 v56, v66, v86
	v_max_f32_e64 v57, -v56, 0
	v_mul_f32_e64 v56, |v56|, s57
	v_exp_f32_e32 v56, v56
	s_nop 0
	v_add_f32_e32 v56, 1.0, v56
	v_cmp_gt_f32_e64 s[0:1], s75, v56
	s_nop 1
	v_cndmask_b32_e64 v66, 0, 32, s[0:1]
	v_ldexp_f32 v56, v56, v66
	v_log_f32_e32 v56, v56
	s_nop 0
	v_mul_f32_e32 v66, 0x3f317217, v56
	v_cmp_lt_f32_e64 s[4:5], |v56|, s59
	v_fma_f32 v66, v56, s58, -v66
	v_fmac_f32_e32 v66, 0x3377d1cf, v56
	v_fmac_f32_e32 v66, 0x3f317217, v56
	v_cndmask_b32_e64 v56, v56, v66, s[4:5]
	v_cndmask_b32_e64 v66, 0, v243, s[0:1]
	v_sub_f32_e32 v56, v56, v66
	v_add_f32_e32 v56, v57, v56
	v_sub_f32_e32 v56, -0.5, v56
	v_mul_f32_e32 v56, 0x3fb8aa3b, v56
	v_exp_f32_e32 v56, v56
	s_nop 0
	v_mul_f32_e32 v56, 0xbfb8aa3b, v56
	v_exp_f32_e32 v66, v56
	v_add_f32_e32 v56, v58, v82
	v_mul_f32_e32 v56, 0xbfb8aa3b, v56
	v_exp_f32_e32 v56, v56
	s_nop 0
	v_add_f32_e32 v56, 1.0, v56
	v_rcp_f32_e32 v114, v56
	v_add_f32_e32 v56, v67, v87
	v_max_f32_e64 v57, -v56, 0
	v_mul_f32_e64 v56, |v56|, s57
	v_exp_f32_e32 v56, v56
	s_nop 0
	v_add_f32_e32 v56, 1.0, v56
	v_cmp_gt_f32_e64 s[0:1], s75, v56
	s_nop 1
	v_cndmask_b32_e64 v58, 0, 32, s[0:1]
	v_ldexp_f32 v56, v56, v58
	v_log_f32_e32 v56, v56
	s_nop 0
	v_mul_f32_e32 v58, 0x3f317217, v56
	v_cmp_lt_f32_e64 s[4:5], |v56|, s59
	v_fma_f32 v58, v56, s58, -v58
	v_fmac_f32_e32 v58, 0x3377d1cf, v56
	v_fmac_f32_e32 v58, 0x3f317217, v56
	v_cndmask_b32_e64 v56, v56, v58, s[4:5]
	v_cndmask_b32_e64 v58, 0, v243, s[0:1]
	s_or_b32 s0, s10, 16
	v_sub_f32_e32 v56, v56, v58
	v_lshlrev_b32_e32 v58, 16, v120
	v_add_f32_e32 v56, v57, v56
	v_xor_b32_e32 v82, 0x80000000, v58
	v_and_b32_e32 v57, 0xffff0000, v121
	v_sub_f32_e32 v56, -0.5, v56
	v_xor_b32_e32 v81, 0x80000000, v57
	v_mul_f32_e32 v56, 0x3fb8aa3b, v56
	v_exp_f32_e32 v56, v56
	s_nop 0
	v_mul_f32_e32 v56, 0xbfb8aa3b, v56
	v_exp_f32_e32 v67, v56
	v_add_f32_e32 v56, v59, v83
	v_and_b32_e32 v59, 0xffff0000, v120
	v_mul_f32_e32 v56, 0xbfb8aa3b, v56
	v_xor_b32_e32 v83, 0x80000000, v59
	v_exp_f32_e32 v56, v56
	v_pk_fma_f32 v[82:83], v[0:1], v[122:123], v[82:83]
	v_sub_u32_e32 v233, v44, v232
	ds_write_b128 v233, v[64:67]
	v_pk_fma_f32 v[58:59], v[60:61], v[82:83], v[58:59]
	v_pk_add_f32 v[60:61], v[110:111], -1.0 op_sel_hi:[1,0]
	v_add_f32_e32 v56, 1.0, v56
	s_waitcnt vmcnt(1)
	v_pk_fma_f32 v[60:61], v[76:77], v[60:61], 1.0 op_sel_hi:[1,1,0]
	v_rcp_f32_e32 v115, v56
	v_lshlrev_b32_e32 v56, 16, v121
	v_pk_mul_f32 v[120:121], v[68:69], v[58:59]
	v_pk_mul_f32 v[58:59], v[58:59], v[60:61]
	v_xor_b32_e32 v80, 0x80000000, v56
	v_mul_f32_e32 v60, v140, v58
	s_waitcnt vmcnt(0)
	v_fma_f32 v159, v72, v60, 0
	v_mul_f32_e32 v60, v141, v59
	v_pk_fma_f32 v[80:81], v[100:101], v[128:129], v[80:81]
	v_fmac_f32_e32 v159, v73, v60
	v_pk_add_f32 v[60:61], v[114:115], -1.0 op_sel_hi:[1,0]
	v_pk_fma_f32 v[56:57], v[62:63], v[80:81], v[56:57]
	v_pk_fma_f32 v[60:61], v[78:79], v[60:61], 1.0 op_sel_hi:[1,1,0]
	v_cvt_pk_bf16_f32 v44, v58, v59
	v_pk_mul_f32 v[60:61], v[56:57], v[60:61]
	v_pk_mul_f32 v[122:123], v[70:71], v[56:57]
	v_cvt_pk_bf16_f32 v45, v60, v61
	v_sub_u32_e32 v233, v112, v232
	ds_write_b64 v233, v[44:45] offset:512
	v_or_b32_e32 v44, s0, v180
	v_mul_f32_e32 v62, v138, v60
	v_lshlrev_b32_e32 v2, 7, v44
	v_fmac_f32_e32 v159, v74, v62
	v_mul_f32_e32 v56, v139, v61
	global_store_dwordx2 v[116:117], v[36:37], off
	v_lshl_add_u64 v[36:37], v[88:89], 0, v[2:3]
	v_fmac_f32_e32 v159, v75, v56
	v_lshl_add_u64 v[38:39], v[92:93], 0, v[2:3]
	global_load_dwordx4 v[210:213], v158, s[8:9] offset:64
	global_load_dwordx4 v[214:217], v158, s[8:9] offset:3136
	global_load_dwordx2 v[236:237], v[126:127], off offset:32
	global_load_dwordx2 v[194:195], v[126:127], off offset:1568
	global_load_dwordx2 v[198:199], v[126:127], off offset:3104
	global_load_dwordx2 v[206:207], v[124:125], off offset:1568
	global_load_dwordx2 v[248:249], v[124:125], off offset:32
	global_load_dwordx4 v[218:221], v158, s[42:43] offset:64
	global_load_dwordx4 v[222:225], v158, s[44:45] offset:64
	global_load_dwordx4 v[40:43], v[36:37], off
	global_load_dwordx4 v[56:59], v[38:39], off
	global_load_dwordx4 v[60:63], v[36:37], off offset:64
	global_load_dwordx4 v[68:71], v[38:39], off offset:64
	v_lshlrev_b32_e32 v2, 8, v44
	v_lshl_add_u64 v[36:37], v[94:95], 0, v[2:3]
	v_or_b32_e32 v2, s0, v181
	v_lshlrev_b32_e32 v2, 2, v2
	global_load_dwordx4 v[52:55], v[36:37], off
	global_load_dwordx4 v[48:51], v[36:37], off offset:64
	global_load_dwordx4 v[44:47], v[36:37], off offset:128
	s_nop 0
	global_load_dwordx4 v[36:39], v[36:37], off offset:192
	v_pk_mul_f32 v[128:129], v[120:121], v[120:121]
	v_pk_mul_f32 v[130:131], v[122:123], v[122:123]
	s_waitcnt vmcnt(7)
; __device__ __forceinline__ void rwkv_prep_item(const Params& p, const Lt& lt, int l, int item) {
;     ...
;         for (int ct = 0; ct < 4; ++ct) {
;             const int crow = h * 64 + ct * 16 + qi;
;             f32x4 aw = {0.f, 0.f, 0.f, 0.f}, aa = aw, ag = aw;
; #pragma unroll
;             for (int ks = 0; ks < 2; ++ks) {
;                 aw = __builtin_amdgcn_mfma_f32_16x16x32_bf16(*(const bf16x8*)(decT + crow * 64 + ks * 32 + quad * 8), fw[ks], aw, 0, 0, 0);
;                 aa = __builtin_amdgcn_mfma_f32_16x16x32_bf16(*(const bf16x8*)(aT + crow * 64 + ks * 32 + quad * 8), fa[ks], aa, 0, 0, 0);
;             }
; #pragma unroll
;             for (int ks = 0; ks < 4; ++ks) ag = __builtin_amdgcn_mfma_f32_16x16x32_bf16(*(const bf16x8*)(gT + crow * 128 + ks * 32 + quad * 8), fg[ks], ag, 0, 0, 0);
;             const int c = h * 64 + ct * 16 + quad * 4;
;             const f32x4 mr = *(const f32x4*)(mu + c), mk = *(const f32x4*)(mu + COL_K + c), mv = *(const f32x4*)(mu + COL_V + c);
;             const f32x4 cr = ld_bf4(pt + c), ck = ld_bf4(pt + COL_K + c), cv = ld_bf4(pt + COL_V + c);
;             const f32x4 qr = ld_bf4(pp + c) * pm, qk = ld_bf4(pp + COL_K + c) * pm, qv = ld_bf4(pp + COL_V + c) * pm;
;             const f32x4 r = cr + (qr - cr) * mr, k = ck + (qk - ck) * mk, v = cv + (qv - cv) * mv;
;             const f32x4 w0v = *(const f32x4*)(w0 + c), a0v = *(const f32x4*)(a0 + c), kkv = *(const f32x4*)(kkp + c), kav = *(const f32x4*)(kap + c), rkv = *(const f32x4*)(rkp + c);
;             f32x4 dec, a, kk, k2;
; #pragma unroll
;             for (int j = 0; j < 4; ++j) {
;                 const float z = -(w0v[j] + aw[j]);
;                 const float sp = fmaxf(z, 0.f) + __logf(1.0f + __expf(-fabsf(z)));
;                 dec[j] = __expf(-__expf(-sp - 0.5f));
;                 a[j] = sigmoidf_(a0v[j] + aa[j]);
;                 kk[j] = k[j] * kkv[j];
;                 nrm += kk[j] * kk[j];
;                 k2[j] = k[j] * (1.0f + (a[j] - 1.0f) * kav[j]);
;                 bon += r[j] * k2[j] * rkv[j];
;             }
;             va[ct] = a; vkk[ct] = kk;
;             { const int cc = ct * 16 + quad * 4; *(f32x4*)(ob + cc * 4) = dec; st_bf4(ob + 512 + cc * 2, k2); st_bf4(ob + 640 + cc * 2, v); st_bf4(ob + 768 + cc * 2, r); }
;             st_bf4((unsigned char*)((bf16_t*)gate + (size_t)t * RW + c), ag);
;         }
	v_mfma_f32_16x16x32_bf16 v[40:43], v[40:43], v[20:23], 0
	s_waitcnt vmcnt(6)
	v_mfma_f32_16x16x32_bf16 v[56:59], v[56:59], v[28:31], 0
	s_waitcnt vmcnt(5)
	v_mfma_f32_16x16x32_bf16 v[64:67], v[60:63], v[24:27], v[40:43]
	s_waitcnt vmcnt(4)
	v_mfma_f32_16x16x32_bf16 v[60:63], v[68:71], v[32:35], v[56:59]
	s_waitcnt vmcnt(16)
	v_mov_b64_e32 v[68:69], v[210:211]
	v_mov_b64_e32 v[70:71], v[212:213]
	s_nop 2
	s_waitcnt vmcnt(15)
	v_mov_b64_e32 v[56:57], v[214:215]
	v_mov_b64_e32 v[58:59], v[216:217]
	global_load_dwordx4 v[40:43], v2, s[52:53]
	s_waitcnt vmcnt(15)
	v_mov_b64_e32 v[72:73], v[236:237]
	s_waitcnt vmcnt(14)
	v_mov_b64_e32 v[136:137], v[194:195]
	s_waitcnt vmcnt(13)
	v_mov_b64_e32 v[76:77], v[198:199]
	s_waitcnt vmcnt(4)
	v_mfma_f32_16x16x32_bf16 v[52:55], v[52:55], v[4:7], 0
	s_waitcnt vmcnt(12)
	v_mov_b64_e32 v[80:81], v[206:207]
	s_waitcnt vmcnt(0)
	v_lshlrev_b32_e32 v74, 16, v72
	s_waitcnt vmcnt(0)
	v_lshlrev_b32_e32 v144, 16, v76
	v_and_b32_e32 v145, 0xffff0000, v76
	v_lshlrev_b32_e32 v146, 16, v77
	v_and_b32_e32 v147, 0xffff0000, v77
	s_waitcnt vmcnt(11)
	v_mov_b64_e32 v[76:77], v[248:249]
	v_and_b32_e32 v75, 0xffff0000, v72
	v_xor_b32_e32 v85, 0x80000000, v75
	v_xor_b32_e32 v84, 0x80000000, v74
	v_lshlrev_b32_e32 v72, 16, v73
	v_and_b32_e32 v73, 0xffff0000, v73
	v_mfma_f32_16x16x32_bf16 v[48:51], v[48:51], v[8:11], v[52:55]
	s_waitcnt vmcnt(0)
	v_lshlrev_b32_e32 v138, 16, v80
	v_and_b32_e32 v139, 0xffff0000, v80
	v_lshlrev_b32_e32 v140, 16, v81
	v_and_b32_e32 v141, 0xffff0000, v81
	global_load_dwordx2 v[80:81], v[124:125], off offset:3104
	v_mfma_f32_16x16x32_bf16 v[44:47], v[44:47], v[12:15], v[48:51]
	s_waitcnt vmcnt(1)
	v_lshlrev_b32_e32 v78, 16, v76
	v_and_b32_e32 v79, 0xffff0000, v76
	v_pk_fma_f32 v[78:79], v[0:1], v[78:79], v[84:85]
	v_lshlrev_b32_e32 v76, 16, v77
	v_and_b32_e32 v77, 0xffff0000, v77
	v_xor_b32_e32 v85, 0x80000000, v73
	v_xor_b32_e32 v84, 0x80000000, v72
	v_pk_fma_f32 v[150:151], v[68:69], v[78:79], v[74:75]
	v_xor_b32_e32 v69, 0x80000000, v145
	v_xor_b32_e32 v68, 0x80000000, v144
	v_pk_fma_f32 v[76:77], v[100:101], v[76:77], v[84:85]
	v_mfma_f32_16x16x32_bf16 v[36:39], v[36:39], v[16:19], v[44:47]
	v_fma_f32 v148, v70, v76, v72
	v_fma_f32 v149, v71, v77, v73
	s_waitcnt vmcnt(0)
	v_lshlrev_b32_e32 v82, 16, v80
	v_and_b32_e32 v83, 0xffff0000, v80
	v_lshlrev_b32_e32 v80, 16, v81
	v_and_b32_e32 v81, 0xffff0000, v81
	v_lshl_add_u64 v[44:45], v[118:119], 0, v[106:107]
	v_cvt_pk_bf16_f32 v36, v36, v37
	v_cvt_pk_bf16_f32 v37, v38, v39
	v_pk_fma_f32 v[152:153], v[0:1], v[82:83], v[68:69]
	v_xor_b32_e32 v69, 0x80000000, v147
	v_xor_b32_e32 v68, 0x80000000, v146
	v_pk_fma_f32 v[154:155], v[100:101], v[80:81], v[68:69]
	s_waitcnt vmcnt(11)
	v_mov_b64_e32 v[84:85], v[218:219]
	v_mov_b64_e32 v[86:87], v[220:221]
	s_waitcnt vmcnt(10)
	v_mov_b64_e32 v[80:81], v[222:223]
	v_mov_b64_e32 v[82:83], v[224:225]
	global_load_dwordx4 v[72:75], v158, s[46:47] offset:64
	global_load_dwordx4 v[76:79], v158, s[48:49] offset:64
	global_load_dwordx4 v[68:71], v158, s[50:51] offset:64
	v_pk_fma_f32 v[40:41], v[40:41], v[152:153], v[144:145]
	v_pk_fma_f32 v[42:43], v[42:43], v[154:155], v[146:147]
	v_cvt_pk_bf16_f32 v40, v40, v41
	v_cvt_pk_bf16_f32 v41, v42, v43
	s_waitcnt vmcnt(3)
	v_add_f32_e32 v2, v64, v84
	v_max_f32_e64 v64, -v2, 0
	v_mul_f32_e64 v2, |v2|, s57
	v_exp_f32_e32 v2, v2
	s_nop 0
	v_add_f32_e32 v2, 1.0, v2
	v_cmp_gt_f32_e64 s[0:1], s75, v2
	s_nop 1
	v_cndmask_b32_e64 v84, 0, 32, s[0:1]
	v_ldexp_f32 v2, v2, v84
	v_log_f32_e32 v2, v2
	s_nop 0
	v_mul_f32_e32 v84, 0x3f317217, v2
	v_cmp_lt_f32_e64 s[4:5], |v2|, s59
	v_fma_f32 v84, v2, s58, -v84
	v_fmac_f32_e32 v84, 0x3377d1cf, v2
	v_fmac_f32_e32 v84, 0x3f317217, v2
	v_cndmask_b32_e64 v2, v2, v84, s[4:5]
	v_cndmask_b32_e64 v84, 0, v243, s[0:1]
	v_sub_f32_e32 v2, v2, v84
	v_add_f32_e32 v2, v64, v2
	v_sub_f32_e32 v2, -0.5, v2
	v_mul_f32_e32 v2, 0x3fb8aa3b, v2
	v_exp_f32_e32 v2, v2
	s_nop 0
	v_mul_f32_e32 v2, 0xbfb8aa3b, v2
	v_exp_f32_e32 v64, v2
	s_waitcnt vmcnt(3)
	v_add_f32_e32 v2, v60, v80
	v_mul_f32_e32 v2, 0xbfb8aa3b, v2
	v_exp_f32_e32 v2, v2
	s_nop 0
	v_add_f32_e32 v2, 1.0, v2
	v_rcp_f32_e32 v132, v2
	v_add_f32_e32 v2, v65, v85
	v_max_f32_e64 v60, -v2, 0
	v_mul_f32_e64 v2, |v2|, s57
	v_exp_f32_e32 v2, v2
	s_nop 0
	v_add_f32_e32 v2, 1.0, v2
	v_cmp_gt_f32_e64 s[0:1], s75, v2
	s_nop 1
	v_cndmask_b32_e64 v65, 0, 32, s[0:1]
	v_ldexp_f32 v2, v2, v65
	v_log_f32_e32 v2, v2
	s_nop 0
	v_mul_f32_e32 v65, 0x3f317217, v2
	v_cmp_lt_f32_e64 s[4:5], |v2|, s59
	v_fma_f32 v65, v2, s58, -v65
	v_fmac_f32_e32 v65, 0x3377d1cf, v2
	v_fmac_f32_e32 v65, 0x3f317217, v2
	v_cndmask_b32_e64 v2, v2, v65, s[4:5]
	v_cndmask_b32_e64 v65, 0, v243, s[0:1]
	v_sub_f32_e32 v2, v2, v65
	v_add_f32_e32 v2, v60, v2
	v_sub_f32_e32 v2, -0.5, v2
	v_mul_f32_e32 v2, 0x3fb8aa3b, v2
	v_exp_f32_e32 v2, v2
	s_nop 0
	v_mul_f32_e32 v2, 0xbfb8aa3b, v2
	v_exp_f32_e32 v65, v2
	v_add_f32_e32 v2, v61, v81
	v_mul_f32_e32 v2, 0xbfb8aa3b, v2
	v_exp_f32_e32 v2, v2
	s_nop 0
	v_add_f32_e32 v2, 1.0, v2
	v_rcp_f32_e32 v133, v2
	v_add_f32_e32 v2, v66, v86
	v_max_f32_e64 v60, -v2, 0
	v_mul_f32_e64 v2, |v2|, s57
	v_exp_f32_e32 v2, v2
	s_nop 0
	v_add_f32_e32 v2, 1.0, v2
	v_cmp_gt_f32_e64 s[0:1], s75, v2
	s_nop 1
	v_cndmask_b32_e64 v61, 0, 32, s[0:1]
	v_ldexp_f32 v2, v2, v61
	v_log_f32_e32 v2, v2
	s_nop 0
	v_mul_f32_e32 v61, 0x3f317217, v2
	v_cmp_lt_f32_e64 s[4:5], |v2|, s59
	v_fma_f32 v61, v2, s58, -v61
	v_fmac_f32_e32 v61, 0x3377d1cf, v2
	v_fmac_f32_e32 v61, 0x3f317217, v2
	v_cndmask_b32_e64 v2, v2, v61, s[4:5]
	v_cndmask_b32_e64 v61, 0, v243, s[0:1]
	v_sub_f32_e32 v2, v2, v61
	v_add_f32_e32 v2, v60, v2
	v_sub_f32_e32 v2, -0.5, v2
; __device__ __forceinline__ void rwkv_prep_item(const Params& p, const Lt& lt, int l, int item) {
;     ...
;         for (int ct = 0; ct < 4; ++ct) {
;             const int crow = h * 64 + ct * 16 + qi;
;             f32x4 aw = {0.f, 0.f, 0.f, 0.f}, aa = aw, ag = aw;
; #pragma unroll
;             for (int ks = 0; ks < 2; ++ks) {
;                 aw = __builtin_amdgcn_mfma_f32_16x16x32_bf16(*(const bf16x8*)(decT + crow * 64 + ks * 32 + quad * 8), fw[ks], aw, 0, 0, 0);
;                 aa = __builtin_amdgcn_mfma_f32_16x16x32_bf16(*(const bf16x8*)(aT + crow * 64 + ks * 32 + quad * 8), fa[ks], aa, 0, 0, 0);
;             }
; #pragma unroll
;             for (int ks = 0; ks < 4; ++ks) ag = __builtin_amdgcn_mfma_f32_16x16x32_bf16(*(const bf16x8*)(gT + crow * 128 + ks * 32 + quad * 8), fg[ks], ag, 0, 0, 0);
;             const int c = h * 64 + ct * 16 + quad * 4;
;             const f32x4 mr = *(const f32x4*)(mu + c), mk = *(const f32x4*)(mu + COL_K + c), mv = *(const f32x4*)(mu + COL_V + c);
;             const f32x4 cr = ld_bf4(pt + c), ck = ld_bf4(pt + COL_K + c), cv = ld_bf4(pt + COL_V + c);
;             const f32x4 qr = ld_bf4(pp + c) * pm, qk = ld_bf4(pp + COL_K + c) * pm, qv = ld_bf4(pp + COL_V + c) * pm;
;             const f32x4 r = cr + (qr - cr) * mr, k = ck + (qk - ck) * mk, v = cv + (qv - cv) * mv;
;             const f32x4 w0v = *(const f32x4*)(w0 + c), a0v = *(const f32x4*)(a0 + c), kkv = *(const f32x4*)(kkp + c), kav = *(const f32x4*)(kap + c), rkv = *(const f32x4*)(rkp + c);
;             f32x4 dec, a, kk, k2;
; #pragma unroll
;             for (int j = 0; j < 4; ++j) {
;                 const float z = -(w0v[j] + aw[j]);
;                 const float sp = fmaxf(z, 0.f) + __logf(1.0f + __expf(-fabsf(z)));
;                 dec[j] = __expf(-__expf(-sp - 0.5f));
;                 a[j] = sigmoidf_(a0v[j] + aa[j]);
;                 kk[j] = k[j] * kkv[j];
;                 nrm += kk[j] * kk[j];
;                 k2[j] = k[j] * (1.0f + (a[j] - 1.0f) * kav[j]);
;                 bon += r[j] * k2[j] * rkv[j];
;             }
;             va[ct] = a; vkk[ct] = kk;
;             { const int cc = ct * 16 + quad * 4; *(f32x4*)(ob + cc * 4) = dec; st_bf4(ob + 512 + cc * 2, k2); st_bf4(ob + 640 + cc * 2, v); st_bf4(ob + 768 + cc * 2, r); }
;             st_bf4((unsigned char*)((bf16_t*)gate + (size_t)t * RW + c), ag);
;         }
	v_mul_f32_e32 v2, 0x3fb8aa3b, v2
	v_exp_f32_e32 v2, v2
	s_nop 0
	v_mul_f32_e32 v2, 0xbfb8aa3b, v2
	v_exp_f32_e32 v66, v2
	v_add_f32_e32 v2, v62, v82
	v_lshlrev_b32_e32 v62, 16, v136
	v_mul_f32_e32 v2, 0xbfb8aa3b, v2
	v_xor_b32_e32 v82, 0x80000000, v62
	v_exp_f32_e32 v2, v2
	s_nop 0
	v_add_f32_e32 v2, 1.0, v2
	v_rcp_f32_e32 v134, v2
	v_add_f32_e32 v2, v67, v87
	v_max_f32_e64 v60, -v2, 0
	v_mul_f32_e64 v2, |v2|, s57
	v_exp_f32_e32 v2, v2
	s_nop 0
	v_add_f32_e32 v2, 1.0, v2
	v_cmp_gt_f32_e64 s[0:1], s75, v2
	s_nop 1
	v_cndmask_b32_e64 v61, 0, 32, s[0:1]
	v_ldexp_f32 v2, v2, v61
	v_log_f32_e32 v2, v2
	s_nop 0
	v_mul_f32_e32 v61, 0x3f317217, v2
	v_cmp_lt_f32_e64 s[4:5], |v2|, s59
	v_fma_f32 v61, v2, s58, -v61
	v_fmac_f32_e32 v61, 0x3377d1cf, v2
	v_fmac_f32_e32 v61, 0x3f317217, v2
	v_cndmask_b32_e64 v2, v2, v61, s[4:5]
	v_cndmask_b32_e64 v61, 0, v243, s[0:1]
	s_or_b32 s0, s10, 32
	v_sub_f32_e32 v2, v2, v61
	v_add_f32_e32 v2, v60, v2
	v_sub_f32_e32 v2, -0.5, v2
	v_mul_f32_e32 v2, 0x3fb8aa3b, v2
	v_exp_f32_e32 v2, v2
	v_lshlrev_b32_e32 v60, 16, v137
	v_and_b32_e32 v61, 0xffff0000, v137
	v_xor_b32_e32 v81, 0x80000000, v61
	v_mul_f32_e32 v2, 0xbfb8aa3b, v2
	v_exp_f32_e32 v67, v2
	v_add_f32_e32 v2, v63, v83
	v_mul_f32_e32 v2, 0xbfb8aa3b, v2
	v_exp_f32_e32 v2, v2
	v_and_b32_e32 v63, 0xffff0000, v136
	v_xor_b32_e32 v83, 0x80000000, v63
	v_pk_fma_f32 v[82:83], v[0:1], v[138:139], v[82:83]
	v_add_f32_e32 v2, 1.0, v2
	v_rcp_f32_e32 v135, v2
	v_xor_b32_e32 v80, 0x80000000, v60
	v_pk_fma_f32 v[56:57], v[56:57], v[82:83], v[62:63]
	v_pk_add_f32 v[62:63], v[132:133], -1.0 op_sel_hi:[1,0]
	v_pk_fma_f32 v[80:81], v[100:101], v[140:141], v[80:81]
	s_waitcnt vmcnt(1)
	v_pk_fma_f32 v[62:63], v[76:77], v[62:63], 1.0 op_sel_hi:[1,1,0]
	v_pk_mul_f32 v[136:137], v[72:73], v[56:57]
	v_pk_mul_f32 v[56:57], v[56:57], v[62:63]
	v_pk_fma_f32 v[58:59], v[58:59], v[80:81], v[60:61]
	v_pk_add_f32 v[60:61], v[134:135], -1.0 op_sel_hi:[1,0]
	v_mul_f32_e32 v2, v150, v56
	v_pk_fma_f32 v[60:61], v[78:79], v[60:61], 1.0 op_sel_hi:[1,1,0]
	s_waitcnt vmcnt(0)
	v_fmac_f32_e32 v159, v68, v2
	v_mul_f32_e32 v2, v151, v57
	v_pk_mul_f32 v[60:61], v[58:59], v[60:61]
	v_sub_u32_e32 v233, v44, v232
	ds_write_b128 v233, v[64:67]
	v_lshl_add_u64 v[44:45], v[118:119], 0, v[108:109]
	v_fmac_f32_e32 v159, v69, v2
	v_mul_f32_e32 v2, v148, v60
	v_cvt_pk_bf16_f32 v46, v56, v57
	v_cvt_pk_bf16_f32 v47, v60, v61
	v_sub_u32_e32 v233, v44, v232
	ds_write_b64 v233, v[40:41] offset:640
	v_cvt_pk_bf16_f32 v40, v150, v151
	v_cvt_pk_bf16_f32 v41, v148, v149
	v_fmac_f32_e32 v159, v70, v2
	v_mul_f32_e32 v2, v149, v61
	v_sub_u32_e32 v233, v44, v232
	ds_write_b64 v233, v[46:47] offset:512
	v_sub_u32_e32 v233, v44, v232
	ds_write_b64 v233, v[40:41] offset:768
	v_or_b32_e32 v44, s0, v180
	v_fmac_f32_e32 v159, v71, v2
	v_lshlrev_b32_e32 v2, 7, v44
	global_store_dwordx2 v[116:117], v[36:37], off offset:32
	v_lshl_add_u64 v[36:37], v[88:89], 0, v[2:3]
	v_pk_mul_f32 v[138:139], v[74:75], v[58:59]
	v_lshl_add_u64 v[38:39], v[92:93], 0, v[2:3]
	global_load_dwordx4 v[210:213], v158, s[8:9] offset:128
	global_load_dwordx4 v[214:217], v158, s[8:9] offset:3200
	global_load_dwordx2 v[236:237], v[126:127], off offset:64
	global_load_dwordx2 v[194:195], v[126:127], off offset:1600
	global_load_dwordx2 v[198:199], v[126:127], off offset:3136
	global_load_dwordx2 v[206:207], v[124:125], off offset:1600
	global_load_dwordx2 v[248:249], v[124:125], off offset:64
	global_load_dwordx4 v[218:221], v158, s[42:43] offset:128
	global_load_dwordx4 v[222:225], v158, s[44:45] offset:128
	global_load_dwordx4 v[40:43], v[36:37], off
	global_load_dwordx4 v[56:59], v[38:39], off
	global_load_dwordx4 v[60:63], v[36:37], off offset:64
	global_load_dwordx4 v[68:71], v[38:39], off offset:64
	v_lshlrev_b32_e32 v2, 8, v44
	v_lshl_add_u64 v[36:37], v[94:95], 0, v[2:3]
	v_or_b32_e32 v2, s0, v181
	v_lshlrev_b32_e32 v2, 2, v2
	global_load_dwordx4 v[52:55], v[36:37], off
	global_load_dwordx4 v[48:51], v[36:37], off offset:64
	global_load_dwordx4 v[44:47], v[36:37], off offset:128
	s_nop 0
	global_load_dwordx4 v[36:39], v[36:37], off offset:192
	v_pk_mul_f32 v[140:141], v[136:137], v[136:137]
	v_pk_mul_f32 v[142:143], v[138:139], v[138:139]
	s_waitcnt vmcnt(7)
	v_mfma_f32_16x16x32_bf16 v[40:43], v[40:43], v[20:23], 0
	s_waitcnt vmcnt(6)
	v_mfma_f32_16x16x32_bf16 v[56:59], v[56:59], v[28:31], 0
	s_waitcnt vmcnt(5)
	v_mfma_f32_16x16x32_bf16 v[64:67], v[60:63], v[24:27], v[40:43]
	s_waitcnt vmcnt(4)
	v_mfma_f32_16x16x32_bf16 v[60:63], v[68:71], v[32:35], v[56:59]
	s_waitcnt vmcnt(16)
	v_mov_b64_e32 v[68:69], v[210:211]
	v_mov_b64_e32 v[70:71], v[212:213]
	s_nop 2
	s_waitcnt vmcnt(15)
	v_mov_b64_e32 v[56:57], v[214:215]
	v_mov_b64_e32 v[58:59], v[216:217]
	global_load_dwordx4 v[40:43], v2, s[52:53]
	s_waitcnt vmcnt(15)
	v_mov_b64_e32 v[72:73], v[236:237]
	s_waitcnt vmcnt(14)
	v_mov_b64_e32 v[152:153], v[194:195]
	s_waitcnt vmcnt(13)
	v_mov_b64_e32 v[76:77], v[198:199]
	s_waitcnt vmcnt(4)
	v_mfma_f32_16x16x32_bf16 v[52:55], v[52:55], v[4:7], 0
	s_waitcnt vmcnt(12)
	v_mov_b64_e32 v[80:81], v[206:207]
	s_waitcnt vmcnt(0)
	v_lshlrev_b32_e32 v74, 16, v72
	s_waitcnt vmcnt(0)
	v_lshlrev_b32_e32 v106, 16, v76
	v_and_b32_e32 v107, 0xffff0000, v76
	v_lshlrev_b32_e32 v108, 16, v77
	v_and_b32_e32 v109, 0xffff0000, v77
	s_waitcnt vmcnt(11)
	v_mov_b64_e32 v[76:77], v[248:249]
	v_and_b32_e32 v75, 0xffff0000, v72
	v_xor_b32_e32 v85, 0x80000000, v75
	v_xor_b32_e32 v84, 0x80000000, v74
	v_lshlrev_b32_e32 v72, 16, v73
	v_and_b32_e32 v73, 0xffff0000, v73
	v_mfma_f32_16x16x32_bf16 v[48:51], v[48:51], v[8:11], v[52:55]
	s_waitcnt vmcnt(0)
; __device__ __forceinline__ float sigmoidf_(float x) { return __builtin_amdgcn_rcpf(1.0f + __expf(-x)); }
; __device__ __forceinline__ f32x4 ld_bf4(const bf16_t* q) { const u32x2 u = *(const u32x2*)q; return (f32x4){bflo(u.x), bfhi(u.x), bflo(u.y), bfhi(u.y)}; }
; __device__ __forceinline__ void rwkv_prep_item(const Params& p, const Lt& lt, int l, int item) {
;     ...
;             const f32x4 mr = *(const f32x4*)(mu + c), mk = *(const f32x4*)(mu + COL_K + c), mv = *(const f32x4*)(mu + COL_V + c);
;             const f32x4 cr = ld_bf4(pt + c), ck = ld_bf4(pt + COL_K + c), cv = ld_bf4(pt + COL_V + c);
;             const f32x4 qr = ld_bf4(pp + c) * pm, qk = ld_bf4(pp + COL_K + c) * pm, qv = ld_bf4(pp + COL_V + c) * pm;
;             const f32x4 r = cr + (qr - cr) * mr, k = ck + (qk - ck) * mk, v = cv + (qv - cv) * mv;
;             const f32x4 w0v = *(const f32x4*)(w0 + c), a0v = *(const f32x4*)(a0 + c), kkv = *(const f32x4*)(kkp + c), kav = *(const f32x4*)(kap + c), rkv = *(const f32x4*)(rkp + c);
;             f32x4 dec, a, kk, k2;
; #pragma unroll
;             for (int j = 0; j < 4; ++j) {
;                 const float z = -(w0v[j] + aw[j]);
;                 const float sp = fmaxf(z, 0.f) + __logf(1.0f + __expf(-fabsf(z)));
;                 dec[j] = __expf(-__expf(-sp - 0.5f));
;                 a[j] = sigmoidf_(a0v[j] + aa[j]);
;                 kk[j] = k[j] * kkv[j];
;                 nrm += kk[j] * kk[j];
;                 k2[j] = k[j] * (1.0f + (a[j] - 1.0f) * kav[j]);
;                 bon += r[j] * k2[j] * rkv[j];
	v_lshlrev_b32_e32 v154, 16, v80
	v_and_b32_e32 v155, 0xffff0000, v80
	v_lshlrev_b32_e32 v156, 16, v81
	v_and_b32_e32 v157, 0xffff0000, v81
	global_load_dwordx2 v[80:81], v[124:125], off offset:3136
	v_mfma_f32_16x16x32_bf16 v[44:47], v[44:47], v[12:15], v[48:51]
	s_waitcnt vmcnt(1)
	v_lshlrev_b32_e32 v78, 16, v76
	v_and_b32_e32 v79, 0xffff0000, v76
	v_pk_fma_f32 v[78:79], v[0:1], v[78:79], v[84:85]
	v_lshlrev_b32_e32 v76, 16, v77
	v_and_b32_e32 v77, 0xffff0000, v77
	v_xor_b32_e32 v85, 0x80000000, v73
	v_xor_b32_e32 v84, 0x80000000, v72
	v_pk_fma_f32 v[146:147], v[68:69], v[78:79], v[74:75]
	v_xor_b32_e32 v69, 0x80000000, v107
	v_xor_b32_e32 v68, 0x80000000, v106
	v_pk_fma_f32 v[76:77], v[100:101], v[76:77], v[84:85]
	v_mfma_f32_16x16x32_bf16 v[36:39], v[36:39], v[16:19], v[44:47]
	v_fma_f32 v144, v70, v76, v72
	v_fma_f32 v145, v71, v77, v73
	s_waitcnt vmcnt(0)
	v_lshlrev_b32_e32 v82, 16, v80
	v_and_b32_e32 v83, 0xffff0000, v80
	v_lshlrev_b32_e32 v80, 16, v81
	v_and_b32_e32 v81, 0xffff0000, v81
	v_lshl_add_u64 v[44:45], v[118:119], 0, v[102:103]
	v_cvt_pk_bf16_f32 v36, v36, v37
	v_cvt_pk_bf16_f32 v37, v38, v39
	v_pk_fma_f32 v[148:149], v[0:1], v[82:83], v[68:69]
	v_xor_b32_e32 v69, 0x80000000, v109
	v_xor_b32_e32 v68, 0x80000000, v108
	v_pk_fma_f32 v[150:151], v[100:101], v[80:81], v[68:69]
	s_waitcnt vmcnt(11)
	v_mov_b64_e32 v[84:85], v[218:219]
	v_mov_b64_e32 v[86:87], v[220:221]
	s_waitcnt vmcnt(10)
	v_mov_b64_e32 v[80:81], v[222:223]
	v_mov_b64_e32 v[82:83], v[224:225]
	global_load_dwordx4 v[72:75], v158, s[46:47] offset:128
	global_load_dwordx4 v[76:79], v158, s[48:49] offset:128
	global_load_dwordx4 v[68:71], v158, s[50:51] offset:128
	v_pk_fma_f32 v[40:41], v[40:41], v[148:149], v[106:107]
	v_pk_fma_f32 v[42:43], v[42:43], v[150:151], v[108:109]
	v_cvt_pk_bf16_f32 v40, v40, v41
	v_cvt_pk_bf16_f32 v41, v42, v43
	s_waitcnt vmcnt(3)
	v_add_f32_e32 v2, v64, v84
	v_max_f32_e64 v64, -v2, 0
	v_mul_f32_e64 v2, |v2|, s57
	v_exp_f32_e32 v2, v2
	s_nop 0
	v_add_f32_e32 v2, 1.0, v2
	v_cmp_gt_f32_e64 s[0:1], s75, v2
	s_nop 1
	v_cndmask_b32_e64 v84, 0, 32, s[0:1]
	v_ldexp_f32 v2, v2, v84
	v_log_f32_e32 v2, v2
	s_nop 0
	v_mul_f32_e32 v84, 0x3f317217, v2
	v_cmp_lt_f32_e64 s[4:5], |v2|, s59
	v_fma_f32 v84, v2, s58, -v84
	v_fmac_f32_e32 v84, 0x3377d1cf, v2
	v_fmac_f32_e32 v84, 0x3f317217, v2
	v_cndmask_b32_e64 v2, v2, v84, s[4:5]
	v_cndmask_b32_e64 v84, 0, v243, s[0:1]
	v_sub_f32_e32 v2, v2, v84
	v_add_f32_e32 v2, v64, v2
	v_sub_f32_e32 v2, -0.5, v2
	v_mul_f32_e32 v2, 0x3fb8aa3b, v2
	v_exp_f32_e32 v2, v2
	s_nop 0
	v_mul_f32_e32 v2, 0xbfb8aa3b, v2
	v_exp_f32_e32 v64, v2
	s_waitcnt vmcnt(3)
	v_add_f32_e32 v2, v60, v80
	v_mul_f32_e32 v2, 0xbfb8aa3b, v2
	v_exp_f32_e32 v2, v2
	s_nop 0
	v_add_f32_e32 v2, 1.0, v2
	v_rcp_f32_e32 v80, v2
	v_add_f32_e32 v2, v65, v85
	v_max_f32_e64 v60, -v2, 0
	v_mul_f32_e64 v2, |v2|, s57
	v_exp_f32_e32 v2, v2
	s_nop 0
	v_add_f32_e32 v2, 1.0, v2
	v_cmp_gt_f32_e64 s[0:1], s75, v2
	s_nop 1
	v_cndmask_b32_e64 v65, 0, 32, s[0:1]
	v_ldexp_f32 v2, v2, v65
	v_log_f32_e32 v2, v2
	s_nop 0
	v_mul_f32_e32 v65, 0x3f317217, v2
	v_cmp_lt_f32_e64 s[4:5], |v2|, s59
	v_fma_f32 v65, v2, s58, -v65
	v_fmac_f32_e32 v65, 0x3377d1cf, v2
	v_fmac_f32_e32 v65, 0x3f317217, v2
	v_cndmask_b32_e64 v2, v2, v65, s[4:5]
	v_cndmask_b32_e64 v65, 0, v243, s[0:1]
	v_sub_f32_e32 v2, v2, v65
	v_add_f32_e32 v2, v60, v2
	v_sub_f32_e32 v2, -0.5, v2
	v_mul_f32_e32 v2, 0x3fb8aa3b, v2
	v_exp_f32_e32 v2, v2
	s_nop 0
	v_mul_f32_e32 v2, 0xbfb8aa3b, v2
	v_exp_f32_e32 v65, v2
	v_add_f32_e32 v2, v61, v81
	v_mul_f32_e32 v2, 0xbfb8aa3b, v2
	v_exp_f32_e32 v2, v2
	s_nop 0
	v_add_f32_e32 v2, 1.0, v2
	v_rcp_f32_e32 v81, v2
	v_add_f32_e32 v2, v66, v86
	v_max_f32_e64 v60, -v2, 0
	v_mul_f32_e64 v2, |v2|, s57
	v_exp_f32_e32 v2, v2
	s_nop 0
	v_add_f32_e32 v2, 1.0, v2
	v_cmp_gt_f32_e64 s[0:1], s75, v2
	s_nop 1
	v_cndmask_b32_e64 v61, 0, 32, s[0:1]
	v_ldexp_f32 v2, v2, v61
	v_log_f32_e32 v2, v2
	s_nop 0
	v_mul_f32_e32 v61, 0x3f317217, v2
	v_cmp_lt_f32_e64 s[4:5], |v2|, s59
	v_fma_f32 v61, v2, s58, -v61
	v_fmac_f32_e32 v61, 0x3377d1cf, v2
	v_fmac_f32_e32 v61, 0x3f317217, v2
	v_cndmask_b32_e64 v2, v2, v61, s[4:5]
	v_cndmask_b32_e64 v61, 0, v243, s[0:1]
	v_sub_f32_e32 v2, v2, v61
	v_add_f32_e32 v2, v60, v2
	v_sub_f32_e32 v2, -0.5, v2
	v_mul_f32_e32 v2, 0x3fb8aa3b, v2
	v_exp_f32_e32 v2, v2
	s_nop 0
	v_mul_f32_e32 v2, 0xbfb8aa3b, v2
	v_exp_f32_e32 v66, v2
	v_add_f32_e32 v2, v62, v82
	v_mul_f32_e32 v2, 0xbfb8aa3b, v2
	v_exp_f32_e32 v2, v2
	v_lshlrev_b32_e32 v62, 16, v152
	v_add_f32_e32 v2, 1.0, v2
	v_rcp_f32_e32 v82, v2
	v_add_f32_e32 v2, v67, v87
	v_max_f32_e64 v60, -v2, 0
	v_mul_f32_e64 v2, |v2|, s57
	v_exp_f32_e32 v2, v2
	s_nop 0
	v_add_f32_e32 v2, 1.0, v2
	v_cmp_gt_f32_e64 s[0:1], s75, v2
	s_nop 1
	v_cndmask_b32_e64 v61, 0, 32, s[0:1]
	v_ldexp_f32 v2, v2, v61
	v_log_f32_e32 v2, v2
	s_nop 0
	v_mul_f32_e32 v61, 0x3f317217, v2
	v_fma_f32 v61, v2, s58, -v61
	v_fmac_f32_e32 v61, 0x3377d1cf, v2
	v_fmac_f32_e32 v61, 0x3f317217, v2
	v_cmp_lt_f32_e64 s[4:5], |v2|, s59
	s_nop 1
	v_cndmask_b32_e64 v2, v2, v61, s[4:5]
	v_cndmask_b32_e64 v61, 0, v243, s[0:1]
	v_sub_f32_e32 v2, v2, v61
	v_add_f32_e32 v2, v60, v2
	v_sub_f32_e32 v2, -0.5, v2
	v_mul_f32_e32 v2, 0x3fb8aa3b, v2
	v_exp_f32_e32 v2, v2
	v_lshlrev_b32_e32 v60, 16, v153
	v_and_b32_e32 v61, 0xffff0000, v153
	v_xor_b32_e32 v85, 0x80000000, v61
	v_mul_f32_e32 v2, 0xbfb8aa3b, v2
	v_exp_f32_e32 v67, v2
	v_add_f32_e32 v2, v63, v83
	v_mul_f32_e32 v2, 0xbfb8aa3b, v2
	v_exp_f32_e32 v2, v2
	v_and_b32_e32 v63, 0xffff0000, v152
	v_xor_b32_e32 v84, 0x80000000, v60
	v_pk_fma_f32 v[86:87], v[100:101], v[156:157], v[84:85]
	v_add_f32_e32 v2, 1.0, v2
	v_rcp_f32_e32 v83, v2
	v_xor_b32_e32 v85, 0x80000000, v63
	v_xor_b32_e32 v84, 0x80000000, v62
	v_pk_fma_f32 v[84:85], v[0:1], v[154:155], v[84:85]
	v_pk_fma_f32 v[58:59], v[58:59], v[86:87], v[60:61]
	v_pk_fma_f32 v[56:57], v[56:57], v[84:85], v[62:63]
	v_pk_add_f32 v[62:63], v[80:81], -1.0 op_sel_hi:[1,0]
	s_waitcnt vmcnt(2)
; __device__ __forceinline__ void st_bf4(unsigned char* q, f32x4 v) { u32x2 w; w.x = cvt_pk_bf16(v[0], v[1]); w.y = cvt_pk_bf16(v[2], v[3]); *(u32x2*)q = w; }
; __device__ __forceinline__ f32x4 ld_bf4(const bf16_t* q) { const u32x2 u = *(const u32x2*)q; return (f32x4){bflo(u.x), bfhi(u.x), bflo(u.y), bfhi(u.y)}; }
; __device__ __forceinline__ void rwkv_prep_item(const Params& p, const Lt& lt, int l, int item) {
;     ...
;             const int crow = h * 64 + ct * 16 + qi;
;             f32x4 aw = {0.f, 0.f, 0.f, 0.f}, aa = aw, ag = aw;
; #pragma unroll
;             for (int ks = 0; ks < 2; ++ks) {
;                 aw = __builtin_amdgcn_mfma_f32_16x16x32_bf16(*(const bf16x8*)(decT + crow * 64 + ks * 32 + quad * 8), fw[ks], aw, 0, 0, 0);
;                 aa = __builtin_amdgcn_mfma_f32_16x16x32_bf16(*(const bf16x8*)(aT + crow * 64 + ks * 32 + quad * 8), fa[ks], aa, 0, 0, 0);
;             }
; #pragma unroll
;             for (int ks = 0; ks < 4; ++ks) ag = __builtin_amdgcn_mfma_f32_16x16x32_bf16(*(const bf16x8*)(gT + crow * 128 + ks * 32 + quad * 8), fg[ks], ag, 0, 0, 0);
;             const int c = h * 64 + ct * 16 + quad * 4;
;             const f32x4 mr = *(const f32x4*)(mu + c), mk = *(const f32x4*)(mu + COL_K + c), mv = *(const f32x4*)(mu + COL_V + c);
;             const f32x4 cr = ld_bf4(pt + c), ck = ld_bf4(pt + COL_K + c), cv = ld_bf4(pt + COL_V + c);
;             const f32x4 qr = ld_bf4(pp + c) * pm, qk = ld_bf4(pp + COL_K + c) * pm, qv = ld_bf4(pp + COL_V + c) * pm;
;             const f32x4 r = cr + (qr - cr) * mr, k = ck + (qk - ck) * mk, v = cv + (qv - cv) * mv;
;             const f32x4 w0v = *(const f32x4*)(w0 + c), a0v = *(const f32x4*)(a0 + c), kkv = *(const f32x4*)(kkp + c), kav = *(const f32x4*)(kap + c), rkv = *(const f32x4*)(rkp + c);
;     ...
;                 nrm += kk[j] * kk[j];
;                 k2[j] = k[j] * (1.0f + (a[j] - 1.0f) * kav[j]);
;                 bon += r[j] * k2[j] * rkv[j];
;             }
;             va[ct] = a; vkk[ct] = kk;
;             { const int cc = ct * 16 + quad * 4; *(f32x4*)(ob + cc * 4) = dec; st_bf4(ob + 512 + cc * 2, k2); st_bf4(ob + 640 + cc * 2, v); st_bf4(ob + 768 + cc * 2, r); }
;             st_bf4((unsigned char*)((bf16_t*)gate + (size_t)t * RW + c), ag);
;         }
	v_pk_mul_f32 v[72:73], v[72:73], v[56:57]
	s_waitcnt vmcnt(1)
	v_pk_fma_f32 v[62:63], v[76:77], v[62:63], 1.0 op_sel_hi:[1,1,0]
	v_pk_add_f32 v[60:61], v[82:83], -1.0 op_sel_hi:[1,0]
	v_pk_mul_f32 v[56:57], v[56:57], v[62:63]
	v_pk_fma_f32 v[60:61], v[78:79], v[60:61], 1.0 op_sel_hi:[1,1,0]
	v_mul_f32_e32 v2, v146, v56
	s_waitcnt vmcnt(0)
	v_fmac_f32_e32 v159, v68, v2
	v_mul_f32_e32 v2, v147, v57
	v_pk_mul_f32 v[60:61], v[58:59], v[60:61]
	v_sub_u32_e32 v233, v44, v232
	ds_write_b128 v233, v[64:67]
	v_lshl_add_u64 v[44:45], v[118:119], 0, v[104:105]
	v_fmac_f32_e32 v159, v69, v2
	v_mul_f32_e32 v2, v144, v60
	v_sub_u32_e32 v233, v44, v232
	ds_write_b64 v233, v[40:41] offset:640
	v_cvt_pk_bf16_f32 v40, v146, v147
	v_cvt_pk_bf16_f32 v41, v144, v145
	s_or_b32 s0, s10, 48
	v_fmac_f32_e32 v159, v70, v2
	v_mul_f32_e32 v2, v145, v61
	v_sub_u32_e32 v233, v44, v232
	ds_write_b64 v233, v[40:41] offset:768
	v_or_b32_e32 v40, s0, v180
	v_fmac_f32_e32 v159, v71, v2
	v_cvt_pk_bf16_f32 v46, v56, v57
	v_cvt_pk_bf16_f32 v47, v60, v61
	v_lshlrev_b32_e32 v2, 7, v40
	v_sub_u32_e32 v233, v44, v232
	ds_write_b64 v233, v[46:47] offset:512
	global_store_dwordx2 v[116:117], v[36:37], off offset:64
	v_lshl_add_u64 v[36:37], v[88:89], 0, v[2:3]
	v_pk_mul_f32 v[74:75], v[74:75], v[58:59]
	v_lshl_add_u64 v[38:39], v[92:93], 0, v[2:3]
	global_load_dwordx4 v[210:213], v158, s[8:9] offset:192
	global_load_dwordx4 v[214:217], v158, s[8:9] offset:3264
	global_load_dwordx2 v[236:237], v[126:127], off offset:96
	global_load_dwordx2 v[194:195], v[126:127], off offset:1632
	global_load_dwordx2 v[198:199], v[126:127], off offset:3168
	global_load_dwordx2 v[206:207], v[124:125], off offset:1632
	global_load_dwordx2 v[248:249], v[124:125], off offset:96
	global_load_dwordx4 v[218:221], v158, s[42:43] offset:192
	global_load_dwordx4 v[222:225], v158, s[44:45] offset:192
	global_load_dwordx4 v[52:55], v[36:37], off
	global_load_dwordx4 v[56:59], v[38:39], off
	global_load_dwordx4 v[60:63], v[36:37], off offset:64
	global_load_dwordx4 v[64:67], v[38:39], off offset:64
	v_lshlrev_b32_e32 v2, 8, v40
	v_lshl_add_u64 v[36:37], v[94:95], 0, v[2:3]
	v_or_b32_e32 v2, s0, v181
	v_lshlrev_b32_e32 v2, 2, v2
	global_load_dwordx4 v[48:51], v[36:37], off
	global_load_dwordx4 v[44:47], v[36:37], off offset:64
	global_load_dwordx4 v[40:43], v[36:37], off offset:128
	s_nop 0
	global_load_dwordx4 v[36:39], v[36:37], off offset:192
	v_pk_mul_f32 v[84:85], v[72:73], v[72:73]
	v_pk_mul_f32 v[76:77], v[74:75], v[74:75]
	s_waitcnt vmcnt(7)
	v_mfma_f32_16x16x32_bf16 v[20:23], v[52:55], v[20:23], 0
	s_waitcnt vmcnt(6)
	v_mfma_f32_16x16x32_bf16 v[28:31], v[56:59], v[28:31], 0
	s_waitcnt vmcnt(5)
	v_mfma_f32_16x16x32_bf16 v[52:55], v[60:63], v[24:27], v[20:23]
	s_waitcnt vmcnt(4)
	v_mfma_f32_16x16x32_bf16 v[28:31], v[64:67], v[32:35], v[28:31]
	s_waitcnt vmcnt(16)
	v_mov_b64_e32 v[32:33], v[210:211]
	v_mov_b64_e32 v[34:35], v[212:213]
	s_waitcnt vmcnt(15)
	v_mov_b64_e32 v[24:25], v[214:215]
	v_mov_b64_e32 v[26:27], v[216:217]
	global_load_dwordx4 v[20:23], v2, s[52:53]
	s_waitcnt vmcnt(15)
	v_mov_b64_e32 v[56:57], v[236:237]
	s_waitcnt vmcnt(14)
	v_mov_b64_e32 v[104:105], v[194:195]
	s_waitcnt vmcnt(13)
	v_mov_b64_e32 v[60:61], v[198:199]
	s_waitcnt vmcnt(4)
	v_mfma_f32_16x16x32_bf16 v[4:7], v[48:51], v[4:7], 0
	s_waitcnt vmcnt(12)
	v_mov_b64_e32 v[64:65], v[206:207]
	s_waitcnt vmcnt(0)
	v_lshlrev_b32_e32 v58, 16, v56
	s_waitcnt vmcnt(0)
	v_lshlrev_b32_e32 v78, 16, v60
	v_and_b32_e32 v79, 0xffff0000, v60
	v_lshlrev_b32_e32 v86, 16, v61
	v_and_b32_e32 v87, 0xffff0000, v61
	s_waitcnt vmcnt(11)
	v_mov_b64_e32 v[60:61], v[248:249]
	v_and_b32_e32 v59, 0xffff0000, v56
	v_xor_b32_e32 v69, 0x80000000, v59
	v_xor_b32_e32 v68, 0x80000000, v58
	v_lshlrev_b32_e32 v56, 16, v57
	v_and_b32_e32 v57, 0xffff0000, v57
	v_mfma_f32_16x16x32_bf16 v[4:7], v[44:47], v[8:11], v[4:7]
	s_waitcnt vmcnt(0)
	v_lshlrev_b32_e32 v106, 16, v64
	v_and_b32_e32 v107, 0xffff0000, v64
	v_lshlrev_b32_e32 v108, 16, v65
	v_and_b32_e32 v109, 0xffff0000, v65
	global_load_dwordx2 v[64:65], v[124:125], off offset:3168
	v_mfma_f32_16x16x32_bf16 v[4:7], v[40:43], v[12:15], v[4:7]
	v_lshl_add_u64 v[12:13], v[118:119], 0, v[96:97]
	s_waitcnt vmcnt(1)
	v_lshlrev_b32_e32 v62, 16, v60
	v_and_b32_e32 v63, 0xffff0000, v60
	v_pk_fma_f32 v[62:63], v[0:1], v[62:63], v[68:69]
	v_lshlrev_b32_e32 v60, 16, v61
	v_and_b32_e32 v61, 0xffff0000, v61
	v_xor_b32_e32 v69, 0x80000000, v57
	v_xor_b32_e32 v68, 0x80000000, v56
	v_pk_fma_f32 v[92:93], v[32:33], v[62:63], v[58:59]
	v_xor_b32_e32 v33, 0x80000000, v79
	v_xor_b32_e32 v32, 0x80000000, v78
	v_pk_fma_f32 v[60:61], v[100:101], v[60:61], v[68:69]
	v_mfma_f32_16x16x32_bf16 v[4:7], v[36:39], v[16:19], v[4:7]
	v_fma_f32 v88, v34, v60, v56
	v_fma_f32 v89, v35, v61, v57
	s_waitcnt vmcnt(0)
	v_lshlrev_b32_e32 v66, 16, v64
	v_and_b32_e32 v67, 0xffff0000, v64
	v_lshlrev_b32_e32 v64, 16, v65
	v_and_b32_e32 v65, 0xffff0000, v65
	s_nop 0
	v_cvt_pk_bf16_f32 v4, v4, v5
	v_cvt_pk_bf16_f32 v5, v6, v7
	v_pk_fma_f32 v[94:95], v[0:1], v[66:67], v[32:33]
	v_xor_b32_e32 v33, 0x80000000, v87
	v_xor_b32_e32 v32, 0x80000000, v86
	v_pk_fma_f32 v[102:103], v[100:101], v[64:65], v[32:33]
	s_waitcnt vmcnt(11)
	v_mov_b64_e32 v[60:61], v[218:219]
	v_mov_b64_e32 v[62:63], v[220:221]
	s_waitcnt vmcnt(10)
	v_mov_b64_e32 v[68:69], v[222:223]
	v_mov_b64_e32 v[70:71], v[224:225]
	global_load_dwordx4 v[56:59], v158, s[46:47] offset:192
	global_load_dwordx4 v[64:67], v158, s[48:49] offset:192
	global_load_dwordx4 v[32:35], v158, s[50:51] offset:192
	v_pk_fma_f32 v[10:11], v[20:21], v[94:95], v[78:79]
	v_pk_fma_f32 v[8:9], v[22:23], v[102:103], v[86:87]
	v_cvt_pk_bf16_f32 v10, v10, v11
	v_cvt_pk_bf16_f32 v11, v8, v9
	v_cvt_pk_bf16_f32 v8, v92, v93
	v_cvt_pk_bf16_f32 v9, v88, v89
	s_waitcnt vmcnt(3)
; __device__ __forceinline__ float quad_sum(float v) { v += xor16(v); v += xor32(v); return v; }
; __device__ __forceinline__ float sigmoidf_(float x) { return __builtin_amdgcn_rcpf(1.0f + __expf(-x)); }
; __device__ __forceinline__ void st_bf4(unsigned char* q, f32x4 v) { u32x2 w; w.x = cvt_pk_bf16(v[0], v[1]); w.y = cvt_pk_bf16(v[2], v[3]); *(u32x2*)q = w; }
; __device__ __forceinline__ void rwkv_prep_item(const Params& p, const Lt& lt, int l, int item) {
;     ...
;             for (int j = 0; j < 4; ++j) {
;                 const float z = -(w0v[j] + aw[j]);
;                 const float sp = fmaxf(z, 0.f) + __logf(1.0f + __expf(-fabsf(z)));
;                 dec[j] = __expf(-__expf(-sp - 0.5f));
;                 a[j] = sigmoidf_(a0v[j] + aa[j]);
;                 kk[j] = k[j] * kkv[j];
;                 nrm += kk[j] * kk[j];
;                 k2[j] = k[j] * (1.0f + (a[j] - 1.0f) * kav[j]);
;                 bon += r[j] * k2[j] * rkv[j];
;             }
;             va[ct] = a; vkk[ct] = kk;
;             { const int cc = ct * 16 + quad * 4; *(f32x4*)(ob + cc * 4) = dec; st_bf4(ob + 512 + cc * 2, k2); st_bf4(ob + 640 + cc * 2, v); st_bf4(ob + 768 + cc * 2, r); }
;             st_bf4((unsigned char*)((bf16_t*)gate + (size_t)t * RW + c), ag);
;         }
;         nrm = quad_sum(nrm); bon = quad_sum(bon);
	v_add_f32_e32 v2, v52, v60
	v_max_f32_e64 v52, -v2, 0
	v_mul_f32_e64 v2, |v2|, s57
	v_exp_f32_e32 v2, v2
	s_nop 0
	v_add_f32_e32 v2, 1.0, v2
	v_cmp_gt_f32_e64 s[0:1], s75, v2
	s_nop 1
	v_cndmask_b32_e64 v60, 0, 32, s[0:1]
	v_ldexp_f32 v2, v2, v60
	v_log_f32_e32 v2, v2
	s_nop 0
	v_mul_f32_e32 v60, 0x3f317217, v2
	v_cmp_lt_f32_e64 s[4:5], |v2|, s59
	v_fma_f32 v60, v2, s58, -v60
	v_fmac_f32_e32 v60, 0x3377d1cf, v2
	v_fmac_f32_e32 v60, 0x3f317217, v2
	v_cndmask_b32_e64 v2, v2, v60, s[4:5]
	v_cndmask_b32_e64 v60, 0, v243, s[0:1]
	v_sub_f32_e32 v2, v2, v60
	v_add_f32_e32 v2, v52, v2
	v_sub_f32_e32 v2, -0.5, v2
	v_mul_f32_e32 v2, 0x3fb8aa3b, v2
	v_exp_f32_e32 v2, v2
	s_nop 0
	v_mul_f32_e32 v2, 0xbfb8aa3b, v2
	v_exp_f32_e32 v52, v2
	s_waitcnt vmcnt(3)
	v_add_f32_e32 v2, v28, v68
	v_mul_f32_e32 v2, 0xbfb8aa3b, v2
	v_exp_f32_e32 v2, v2
	s_nop 0
	v_add_f32_e32 v2, 1.0, v2
	v_rcp_f32_e32 v28, v2
	v_add_f32_e32 v2, v53, v61
	v_and_b32_e32 v61, 0xffff0000, v105
	v_max_f32_e64 v53, -v2, 0
	v_mul_f32_e64 v2, |v2|, s57
	v_exp_f32_e32 v2, v2
	s_nop 0
	v_add_f32_e32 v2, 1.0, v2
	v_cmp_gt_f32_e64 s[0:1], s75, v2
	s_nop 1
	v_cndmask_b32_e64 v60, 0, 32, s[0:1]
	v_ldexp_f32 v2, v2, v60
	v_log_f32_e32 v2, v2
	s_nop 0
	v_mul_f32_e32 v60, 0x3f317217, v2
	v_fma_f32 v60, v2, s58, -v60
	v_fmac_f32_e32 v60, 0x3377d1cf, v2
	v_fmac_f32_e32 v60, 0x3f317217, v2
	v_cmp_lt_f32_e64 s[4:5], |v2|, s59
	s_nop 1
	v_cndmask_b32_e64 v2, v2, v60, s[4:5]
	v_cndmask_b32_e64 v60, 0, v243, s[0:1]
	v_sub_f32_e32 v2, v2, v60
	v_add_f32_e32 v2, v53, v2
	v_sub_f32_e32 v2, -0.5, v2
	v_mul_f32_e32 v2, 0x3fb8aa3b, v2
	v_exp_f32_e32 v2, v2
	s_nop 0
	v_mul_f32_e32 v2, 0xbfb8aa3b, v2
	v_exp_f32_e32 v53, v2
	v_add_f32_e32 v2, v29, v69
	v_mul_f32_e32 v2, 0xbfb8aa3b, v2
	v_exp_f32_e32 v2, v2
	v_xor_b32_e32 v69, 0x80000000, v61
	v_add_f32_e32 v2, 1.0, v2
	v_rcp_f32_e32 v29, v2
	v_add_f32_e32 v2, v54, v62
	v_max_f32_e64 v54, -v2, 0
	v_mul_f32_e64 v2, |v2|, s57
	v_exp_f32_e32 v2, v2
	v_lshlrev_b32_e32 v62, 16, v104
	v_add_f32_e32 v2, 1.0, v2
	v_cmp_gt_f32_e64 s[0:1], s75, v2
	s_nop 1
	v_cndmask_b32_e64 v60, 0, 32, s[0:1]
	v_ldexp_f32 v2, v2, v60
	v_log_f32_e32 v2, v2
	s_nop 0
	v_mul_f32_e32 v60, 0x3f317217, v2
	v_fma_f32 v60, v2, s58, -v60
	v_fmac_f32_e32 v60, 0x3377d1cf, v2
	v_fmac_f32_e32 v60, 0x3f317217, v2
	v_cmp_lt_f32_e64 s[4:5], |v2|, s59
	s_nop 1
	v_cndmask_b32_e64 v2, v2, v60, s[4:5]
	v_cndmask_b32_e64 v60, 0, v243, s[0:1]
	v_sub_f32_e32 v2, v2, v60
	v_add_f32_e32 v2, v54, v2
	v_sub_f32_e32 v2, -0.5, v2
	v_mul_f32_e32 v2, 0x3fb8aa3b, v2
	v_exp_f32_e32 v2, v2
	s_nop 0
	v_mul_f32_e32 v2, 0xbfb8aa3b, v2
	v_exp_f32_e32 v54, v2
	v_add_f32_e32 v2, v30, v70
	v_mul_f32_e32 v2, 0xbfb8aa3b, v2
	v_exp_f32_e32 v2, v2
	v_xor_b32_e32 v70, 0x80000000, v62
	v_add_f32_e32 v2, 1.0, v2
	v_rcp_f32_e32 v30, v2
	v_add_f32_e32 v2, v55, v63
	v_max_f32_e64 v55, -v2, 0
	v_mul_f32_e64 v2, |v2|, s57
	v_exp_f32_e32 v2, v2
	v_and_b32_e32 v63, 0xffff0000, v104
	v_add_f32_e32 v2, 1.0, v2
	v_cmp_gt_f32_e64 s[0:1], s75, v2
	s_nop 1
	v_cndmask_b32_e64 v60, 0, 32, s[0:1]
	v_ldexp_f32 v2, v2, v60
	v_log_f32_e32 v2, v2
	s_nop 0
	v_mul_f32_e32 v60, 0x3f317217, v2
	v_fma_f32 v60, v2, s58, -v60
	v_fmac_f32_e32 v60, 0x3377d1cf, v2
	v_fmac_f32_e32 v60, 0x3f317217, v2
	v_cmp_lt_f32_e64 s[4:5], |v2|, s59
	s_nop 1
	v_cndmask_b32_e64 v2, v2, v60, s[4:5]
	v_cndmask_b32_e64 v60, 0, v243, s[0:1]
	v_sub_f32_e32 v2, v2, v60
	v_add_f32_e32 v2, v55, v2
	v_sub_f32_e32 v2, -0.5, v2
	v_mul_f32_e32 v2, 0x3fb8aa3b, v2
	v_exp_f32_e32 v2, v2
	v_lshlrev_b32_e32 v60, 16, v105
	v_xor_b32_e32 v68, 0x80000000, v60
	v_pk_fma_f32 v[68:69], v[100:101], v[108:109], v[68:69]
	v_mul_f32_e32 v2, 0xbfb8aa3b, v2
	v_exp_f32_e32 v55, v2
	v_add_f32_e32 v2, v31, v71
	v_mul_f32_e32 v2, 0xbfb8aa3b, v2
	v_exp_f32_e32 v2, v2
	v_xor_b32_e32 v71, 0x80000000, v63
	v_pk_fma_f32 v[0:1], v[0:1], v[106:107], v[70:71]
	v_sub_u32_e32 v233, v12, v232
	ds_write_b128 v233, v[52:55]
	v_add_f32_e32 v2, 1.0, v2
	v_rcp_f32_e32 v31, v2
	v_pk_fma_f32 v[24:25], v[24:25], v[0:1], v[62:63]
	v_pk_add_f32 v[62:63], v[28:29], -1.0 op_sel_hi:[1,0]
	s_waitcnt vmcnt(2)
	v_pk_mul_f32 v[0:1], v[56:57], v[24:25]
	s_waitcnt vmcnt(1)
	v_pk_fma_f32 v[62:63], v[64:65], v[62:63], 1.0 op_sel_hi:[1,1,0]
	v_pk_mul_f32 v[56:57], v[0:1], v[0:1]
	v_pk_mul_f32 v[62:63], v[24:25], v[62:63]
	v_pk_fma_f32 v[24:25], v[26:27], v[68:69], v[60:61]
	v_pk_add_f32 v[26:27], v[30:31], -1.0 op_sel_hi:[1,0]
	v_mul_f32_e32 v2, v92, v62
	v_pk_fma_f32 v[26:27], v[66:67], v[26:27], 1.0 op_sel_hi:[1,1,0]
	s_waitcnt vmcnt(0)
	v_fmac_f32_e32 v159, v32, v2
	v_mul_f32_e32 v2, v93, v63
	v_pk_mul_f32 v[26:27], v[24:25], v[26:27]
	v_fmac_f32_e32 v159, v33, v2
	v_mul_f32_e32 v2, v88, v26
	v_fmac_f32_e32 v159, v34, v2
	v_add_f32_e32 v2, v128, v129
	v_add_f32_e32 v2, v130, v2
	v_add_f32_e32 v2, v131, v2
	v_add_f32_e32 v2, v2, v140
	v_add_f32_e32 v2, v141, v2
	v_add_f32_e32 v2, v142, v2
	v_add_f32_e32 v2, v143, v2
	v_add_f32_e32 v2, v2, v84
	v_add_f32_e32 v2, v85, v2
	v_add_f32_e32 v2, v76, v2
	v_add_f32_e32 v2, v77, v2
	v_pk_mul_f32 v[24:25], v[58:59], v[24:25]
	v_add_f32_e32 v2, v2, v56
	v_pk_mul_f32 v[32:33], v[24:25], v[24:25]
	v_add_f32_e32 v2, v57, v2
	v_add_f32_e32 v2, v32, v2
	v_add_f32_e32 v2, v33, v2
	v_lshl_add_u64 v[12:13], v[118:119], 0, v[98:99]
	v_cvt_pk_bf16_f32 v14, v62, v63
	v_cvt_pk_bf16_f32 v15, v26, v27
	v_sub_u32_e32 v233, v12, v232
	ds_write_b64 v233, v[14:15] offset:512
	v_sub_u32_e32 v233, v12, v232
	ds_write_b64 v233, v[10:11] offset:640
	v_sub_u32_e32 v233, v12, v232
	ds_write_b64 v233, v[8:9] offset:768
	global_store_dwordx2 v[116:117], v[4:5], off offset:96
	ds_bpermute_b32 v4, v182, v2
	v_mul_f32_e32 v32, v89, v27
	v_fmac_f32_e32 v159, v35, v32
	s_waitcnt lgkmcnt(0)
; __device__ __forceinline__ float quad_sum(float v) { v += xor16(v); v += xor32(v); return v; }
; __device__ __forceinline__ void st_bf4(unsigned char* q, f32x4 v) { u32x2 w; w.x = cvt_pk_bf16(v[0], v[1]); w.y = cvt_pk_bf16(v[2], v[3]); *(u32x2*)q = w; }
; __device__ __forceinline__ void rwkv_prep_item(const Params& p, const Lt& lt, int l, int item) {
;     ...
;         nrm = quad_sum(nrm); bon = quad_sum(bon);
;         const float inv = rsqrtf(fmaxf(nrm, 1e-24f));
; #pragma unroll
;         for (int ct = 0; ct < 4; ++ct) {
;             const int cc = ct * 16 + quad * 4;
;             const f32x4 kkn = vkk[ct] * inv;
;             st_bf4(ob + 256 + cc * 2, -kkn);
;             st_bf4(ob + 384 + cc * 2, kkn * va[ct]);
;         }
;         if (quad == 0) bonus[(size_t)t * 16 + h] = bon;
	v_add_f32_e32 v2, v2, v4
	ds_bpermute_b32 v4, v183, v2
	s_waitcnt lgkmcnt(0)
	v_add_f32_e32 v5, v2, v4
	v_max_f32_e32 v5, 0x179abe15, v5
	v_rsq_f32_e32 v6, v5
	ds_bpermute_b32 v2, v182, v159
	v_pk_mul_f32 v[8:9], v[120:121], v[6:7] op_sel_hi:[1,0]
	v_pk_mul_f32 v[10:11], v[122:123], v[6:7] op_sel_hi:[1,0]
	v_xor_b32_e32 v12, 0x80000000, v9
	v_xor_b32_e32 v5, 0x80000000, v11
	v_xor_b32_e32 v7, 0x80000000, v10
	v_xor_b32_e32 v13, 0x80000000, v8
	v_pk_mul_f32 v[10:11], v[114:115], v[10:11]
	v_pk_mul_f32 v[8:9], v[110:111], v[8:9]
	v_cvt_pk_bf16_f32 v12, v13, v12
	v_cvt_pk_bf16_f32 v8, v8, v9
	v_cvt_pk_bf16_f32 v9, v10, v11
	v_cvt_pk_bf16_f32 v13, v7, v5
	v_sub_u32_e32 v233, v112, v232
	ds_write_b64 v233, v[8:9] offset:384
	v_pk_mul_f32 v[8:9], v[136:137], v[6:7] op_sel_hi:[1,0]
	v_pk_mul_f32 v[10:11], v[138:139], v[6:7] op_sel_hi:[1,0]
	v_sub_u32_e32 v233, v112, v232
	ds_write_b64 v233, v[12:13] offset:256
	v_xor_b32_e32 v5, 0x80000000, v11
	v_xor_b32_e32 v7, 0x80000000, v10
	v_xor_b32_e32 v12, 0x80000000, v9
	v_xor_b32_e32 v13, 0x80000000, v8
	v_pk_mul_f32 v[10:11], v[134:135], v[10:11]
	v_pk_mul_f32 v[8:9], v[132:133], v[8:9]
	s_waitcnt lgkmcnt(0)
	v_add_f32_e32 v2, v159, v2
	v_cvt_pk_bf16_f32 v8, v8, v9
	v_cvt_pk_bf16_f32 v9, v10, v11
	ds_bpermute_b32 v4, v183, v2
	v_cvt_pk_bf16_f32 v12, v13, v12
	v_cvt_pk_bf16_f32 v13, v7, v5
	v_sub_u32_e32 v233, v112, v232
	ds_write_b64 v233, v[8:9] offset:416
	v_pk_mul_f32 v[8:9], v[72:73], v[6:7] op_sel_hi:[1,0]
	v_pk_mul_f32 v[10:11], v[74:75], v[6:7] op_sel_hi:[1,0]
	v_sub_u32_e32 v233, v112, v232
	ds_write_b64 v233, v[12:13] offset:288
	v_xor_b32_e32 v5, 0x80000000, v11
	v_xor_b32_e32 v7, 0x80000000, v10
	v_xor_b32_e32 v12, 0x80000000, v9
	v_xor_b32_e32 v13, 0x80000000, v8
	v_pk_mul_f32 v[10:11], v[82:83], v[10:11]
	v_pk_mul_f32 v[8:9], v[80:81], v[8:9]
	v_cvt_pk_bf16_f32 v12, v13, v12
	v_cvt_pk_bf16_f32 v13, v7, v5
	v_cvt_pk_bf16_f32 v8, v8, v9
	v_cvt_pk_bf16_f32 v9, v10, v11
	v_pk_mul_f32 v[0:1], v[0:1], v[6:7] op_sel_hi:[1,0]
	v_pk_mul_f32 v[6:7], v[24:25], v[6:7] op_sel_hi:[1,0]
	v_sub_u32_e32 v233, v112, v232
	ds_write_b64 v233, v[8:9] offset:448
	v_xor_b32_e32 v5, 0x80000000, v7
	v_xor_b32_e32 v9, 0x80000000, v6
	v_xor_b32_e32 v8, 0x80000000, v1
	v_xor_b32_e32 v10, 0x80000000, v0
	v_pk_mul_f32 v[6:7], v[30:31], v[6:7]
	v_pk_mul_f32 v[0:1], v[28:29], v[0:1]
	v_cvt_pk_bf16_f32 v8, v10, v8
	v_cvt_pk_bf16_f32 v9, v9, v5
	v_cvt_pk_bf16_f32 v0, v0, v1
	v_cvt_pk_bf16_f32 v1, v6, v7
	v_sub_u32_e32 v233, v112, v232
	ds_write_b64 v233, v[12:13] offset:320
	v_sub_u32_e32 v233, v112, v232
	ds_write_b64 v233, v[8:9] offset:352
	v_sub_u32_e32 v233, v112, v232
	ds_write_b64 v233, v[0:1] offset:480
	s_waitcnt lgkmcnt(0)
	s_mov_b32 s98, -1
	s_mov_b32 s99, 0xffffff
	s_mov_b64 exec, s[98:99]
	s_movk_i32 s98, 1792
	s_mov_b32 s99, 0
	v_lshl_add_u64 v[228:229], v[234:235], 0, s[98:99]
	s_movk_i32 s98, 0x2a00
	ds_read_b128 v[210:213], v226 offset:0
	ds_read_b128 v[214:217], v226 offset:912
	ds_read_b128 v[218:221], v226 offset:1824
	ds_read_b128 v[222:225], v226 offset:2736
	s_waitcnt lgkmcnt(3)
	global_store_dwordx4 v[228:229], v[210:213], off
	v_lshl_add_u64 v[228:229], v[228:229], 0, s[98:99]
	s_waitcnt lgkmcnt(2)
	global_store_dwordx4 v[228:229], v[214:217], off
	v_lshl_add_u64 v[228:229], v[228:229], 0, s[98:99]
	s_waitcnt lgkmcnt(1)
	global_store_dwordx4 v[228:229], v[218:221], off
	v_lshl_add_u64 v[228:229], v[228:229], 0, s[98:99]
	s_waitcnt lgkmcnt(0)
	global_store_dwordx4 v[228:229], v[222:225], off
	v_lshl_add_u64 v[228:229], v[228:229], 0, s[98:99]
	ds_read_b128 v[210:213], v226 offset:3648
	ds_read_b128 v[214:217], v226 offset:4560
	ds_read_b128 v[218:221], v226 offset:5472
	ds_read_b128 v[222:225], v226 offset:6384
	s_waitcnt lgkmcnt(3)
	global_store_dwordx4 v[228:229], v[210:213], off
	v_lshl_add_u64 v[228:229], v[228:229], 0, s[98:99]
	s_waitcnt lgkmcnt(2)
	global_store_dwordx4 v[228:229], v[214:217], off
	v_lshl_add_u64 v[228:229], v[228:229], 0, s[98:99]
	s_waitcnt lgkmcnt(1)
	global_store_dwordx4 v[228:229], v[218:221], off
	v_lshl_add_u64 v[228:229], v[228:229], 0, s[98:99]
	s_waitcnt lgkmcnt(0)
	global_store_dwordx4 v[228:229], v[222:225], off
	v_lshl_add_u64 v[228:229], v[228:229], 0, s[98:99]
	ds_read_b128 v[210:213], v226 offset:7296
	ds_read_b128 v[214:217], v226 offset:8208
	ds_read_b128 v[218:221], v226 offset:9120
	ds_read_b128 v[222:225], v226 offset:10032
	s_waitcnt lgkmcnt(3)
	global_store_dwordx4 v[228:229], v[210:213], off
	v_lshl_add_u64 v[228:229], v[228:229], 0, s[98:99]
	s_waitcnt lgkmcnt(2)
	global_store_dwordx4 v[228:229], v[214:217], off
	v_lshl_add_u64 v[228:229], v[228:229], 0, s[98:99]
	s_waitcnt lgkmcnt(1)
	global_store_dwordx4 v[228:229], v[218:221], off
	v_lshl_add_u64 v[228:229], v[228:229], 0, s[98:99]
	s_waitcnt lgkmcnt(0)
	global_store_dwordx4 v[228:229], v[222:225], off
	v_lshl_add_u64 v[228:229], v[228:229], 0, s[98:99]
	ds_read_b128 v[210:213], v226 offset:10944
	ds_read_b128 v[214:217], v226 offset:11856
	ds_read_b128 v[218:221], v226 offset:12768
	ds_read_b128 v[222:225], v226 offset:13680
	s_waitcnt lgkmcnt(3)
	global_store_dwordx4 v[228:229], v[210:213], off
	v_lshl_add_u64 v[228:229], v[228:229], 0, s[98:99]
	s_waitcnt lgkmcnt(2)
	global_store_dwordx4 v[228:229], v[214:217], off
	v_lshl_add_u64 v[228:229], v[228:229], 0, s[98:99]
	s_waitcnt lgkmcnt(1)
	global_store_dwordx4 v[228:229], v[218:221], off
	v_lshl_add_u64 v[228:229], v[228:229], 0, s[98:99]
	s_waitcnt lgkmcnt(0)
	global_store_dwordx4 v[228:229], v[222:225], off
	v_lshl_add_u64 v[228:229], v[228:229], 0, s[98:99]
	s_mov_b64 exec, -1
	s_and_saveexec_b64 s[0:1], vcc
	s_cbranch_execz .LBB0_342
	s_lshl_b32 s10, s56, 2
	v_lshl_add_u64 v[0:1], v[90:91], 0, s[10:11]
	s_waitcnt lgkmcnt(0)
	v_add_f32_e32 v2, v2, v4
	global_store_dword v[0:1], v2, off offset:8
	s_branch .LBB0_342
